# conv chunk body hand-rewritten (prefetch, interleaved tap chains, stats once per token via SGPR broadcast, rcp/rsq); P0 gain preload; P4 waits; P6 epilogue load batching
# speedup vs baseline: 1.0654x; 1.0401x over previous
.LBB0_115:
	s_cmpk_gt_i32 s15, 0x7fff
	s_cbranch_scc1 .LBB0_134
	v_mov_b32_e32 v1, 0
	v_lshlrev_b32_e32 v0, 4, v86
	v_mov_b32_e32 v17, v1
	v_lshl_add_u64 v[68:69], s[16:17], 0, v[0:1]
	v_lshl_add_u64 v[70:71], s[18:19], 0, v[0:1]
	v_lshl_add_u64 v[0:1], s[12:13], 0, v[16:17]
	s_mov_b64 s[0:1], 0x7000000
	v_lshl_add_u64 v[72:73], v[0:1], 0, s[0:1]
	s_mov_b64 s[0:1], 0x1000
	v_lshl_add_u64 v[74:75], v[70:71], 0, s[0:1]
	s_mov_b64 s[0:1], 0x1400
	v_lshl_add_u64 v[76:77], v[70:71], 0, s[0:1]
	s_mov_b64 s[0:1], 0x1800
	v_lshl_add_u64 v[78:79], v[70:71], 0, s[0:1]
	s_mov_b64 s[0:1], 0x1c00
	v_lshl_add_u64 v[80:81], v[70:71], 0, s[0:1]
	s_lshl_b32 s0, s5, 3
	s_sub_i32 s15, 0, s0
	s_lshl_b32 s0, s3, 4
	s_lshl_b32 s1, s5, 4
	s_sub_i32 s20, s0, s1
	s_sub_i32 s21, s4, s1
	s_movk_i32 s22, 0x1000
	v_mov_b32_e32 v92, 0x358637bd
	s_mov_b32 s23, 0xf800000
	v_mov_b32_e32 v93, 0x260
	global_load_dwordx4 v[100:103], v[70:71], off
	global_load_dwordx4 v[104:107], v[70:71], off offset:1024
	global_load_dwordx4 v[108:111], v[70:71], off offset:2048
	global_load_dwordx4 v[112:115], v[70:71], off offset:3072
	global_load_dwordx4 v[116:119], v[74:75], off
	global_load_dwordx4 v[120:123], v[76:77], off
	global_load_dwordx4 v[124:127], v[78:79], off
	global_load_dwordx4 v[128:131], v[80:81], off
	s_branch .LBB0_118

.LBB0_118:
	s_add_i32 s4, s15, s14
	s_ashr_i32 s5, s4, 31
	s_lshl_b64 s[0:1], s[4:5], 13
	s_add_i32 s24, s21, s14
	s_cmp_lt_i32 s24, 0x8000
	v_lshl_add_u64 v[0:1], v[68:69], 0, s[0:1]
	s_cselect_b64 s[16:17], -1, 0
	global_load_dwordx4 v[56:59], v[0:1], off
	global_load_dwordx4 v[48:51], v[0:1], off offset:1024
	global_load_dwordx4 v[40:43], v[0:1], off offset:2048
	global_load_dwordx4 v[32:35], v[0:1], off offset:3072
	s_and_b64 s[0:1], s[16:17], exec
	s_cselect_b32 s18, s24, s4
	v_add_co_u32_e32 v64, vcc, s22, v0
	s_ashr_i32 s19, s18, 31
	s_nop 0
	v_addc_co_u32_e32 v65, vcc, 0, v1, vcc
	s_lshl_b64 s[0:1], s[18:19], 13
	global_load_dwordx4 v[28:31], v[64:65], off
	global_load_dwordx4 v[20:23], v[64:65], off offset:1024
	v_lshl_add_u64 v[0:1], v[68:69], 0, s[0:1]
	global_load_dwordx4 v[60:63], v[0:1], off
	global_load_dwordx4 v[52:55], v[0:1], off offset:1024
	global_load_dwordx4 v[44:47], v[0:1], off offset:2048
	global_load_dwordx4 v[36:39], v[0:1], off offset:3072
	v_add_co_u32_e32 v66, vcc, s22, v0
	s_lshl_b64 s[26:27], s[4:5], 12
	s_nop 0
	v_addc_co_u32_e32 v67, vcc, 0, v1, vcc
	global_load_dwordx4 v[24:27], v[66:67], off
	global_load_dwordx4 v[12:15], v[64:65], off offset:2048
	global_load_dwordx4 v[4:7], v[64:65], off offset:3072
	global_load_dwordx4 v[16:19], v[66:67], off offset:1024
	global_load_dwordx4 v[8:11], v[66:67], off offset:2048
	global_load_dwordx4 v[0:3], v[66:67], off offset:3072
	s_lshl_b64 s[18:19], s[18:19], 12
	s_cmpk_gt_i32 s24, 0x7fff
	s_waitcnt vmcnt(15)
	v_mul_f32_e32 v64, v57, v57
	v_mul_f32_e32 v65, v59, v59
	s_waitcnt vmcnt(14)
	v_mul_f32_e32 v66, v49, v49
	v_mul_f32_e32 v67, v51, v51
	s_waitcnt vmcnt(13)
	v_mul_f32_e32 v82, v41, v41
	v_mul_f32_e32 v83, v43, v43
	v_fmac_f32_e32 v64, v56, v56
	v_fmac_f32_e32 v65, v58, v58
	v_fmac_f32_e32 v66, v48, v48
	v_fmac_f32_e32 v67, v50, v50
	s_waitcnt vmcnt(12)
	v_mul_f32_e32 v84, v33, v33
	v_mul_f32_e32 v85, v35, v35
	v_fmac_f32_e32 v82, v40, v40
	v_fmac_f32_e32 v83, v42, v42
	v_add_f32_e32 v64, v64, v65
	v_add_f32_e32 v65, v66, v67
	v_fmac_f32_e32 v84, v32, v32
	v_fmac_f32_e32 v85, v34, v34
	v_add_f32_e32 v66, v82, v83
	v_add_f32_e32 v64, v64, v65
	v_add_f32_e32 v67, v84, v85
	v_add_f32_e32 v64, v64, v66
	s_waitcnt vmcnt(11)
	v_mul_f32_e32 v94, v29, v29
	v_mul_f32_e32 v95, v31, v31
	v_add_f32_e32 v64, v64, v67
	s_waitcnt vmcnt(9)
	v_mul_f32_e32 v66, v61, v61
	v_mul_f32_e32 v67, v63, v63
	s_waitcnt vmcnt(8)
	v_mul_f32_e32 v82, v53, v53
	v_mul_f32_e32 v83, v55, v55
	v_fmac_f32_e32 v94, v28, v28
	v_fmac_f32_e32 v95, v30, v30
	s_waitcnt vmcnt(7)
	v_mul_f32_e32 v84, v45, v45
	v_mul_f32_e32 v85, v47, v47
	v_fmac_f32_e32 v66, v60, v60
	v_fmac_f32_e32 v67, v62, v62
	v_fmac_f32_e32 v82, v52, v52
	v_fmac_f32_e32 v83, v54, v54
	v_add_f32_e32 v65, v94, v95
	s_waitcnt vmcnt(6)
	v_mul_f32_e32 v94, v37, v37
	v_mul_f32_e32 v95, v39, v39
	v_fmac_f32_e32 v84, v44, v44
	v_fmac_f32_e32 v85, v46, v46
	v_add_f32_e32 v66, v66, v67
	v_add_f32_e32 v67, v82, v83
	v_add_f32_e32 v64, v64, v65
	v_fmac_f32_e32 v94, v36, v36
	v_fmac_f32_e32 v95, v38, v38
	s_waitcnt vmcnt(5)
	v_mul_f32_e32 v65, v25, v25
	v_mul_f32_e32 v98, v27, v27
	v_add_f32_e32 v82, v84, v85
	v_add_f32_e32 v66, v66, v67
	v_mul_f32_e32 v96, v21, v21
	v_mul_f32_e32 v97, v23, v23
	v_add_f32_e32 v83, v94, v95
	v_fmac_f32_e32 v65, v24, v24
	v_fmac_f32_e32 v98, v26, v26
	v_add_f32_e32 v66, v66, v82
	v_fmac_f32_e32 v96, v20, v20
	v_add_f32_e32 v65, v65, v98
	v_add_f32_e32 v66, v66, v83
	v_fmac_f32_e32 v97, v22, v22
	v_add_f32_e32 v65, v66, v65
	v_add_f32_e32 v66, v96, v97
	v_add_f32_e32 v64, v64, v66
	s_waitcnt vmcnt(4)
	v_mul_f32_e32 v66, v13, v13
	v_mul_f32_e32 v67, v15, v15
	v_fmac_f32_e32 v66, v12, v12
	v_fmac_f32_e32 v67, v14, v14
	v_add_f32_e32 v66, v66, v67
	v_add_f32_e32 v64, v64, v66
	s_waitcnt vmcnt(3)
	v_mul_f32_e32 v66, v5, v5
	v_mul_f32_e32 v67, v7, v7
	v_fmac_f32_e32 v66, v4, v4
	v_fmac_f32_e32 v67, v6, v6
	v_add_f32_e32 v66, v66, v67
	v_add_f32_e32 v64, v64, v66
	ds_bpermute_b32 v66, v87, v64
	s_waitcnt vmcnt(2)
	v_mul_f32_e32 v67, v17, v17
	v_mul_f32_e32 v82, v19, v19
	v_fmac_f32_e32 v67, v16, v16
	v_fmac_f32_e32 v82, v18, v18
	s_waitcnt lgkmcnt(0)
	v_add_f32_e32 v64, v64, v66
	ds_bpermute_b32 v66, v88, v64
	v_add_f32_e32 v67, v67, v82
	v_add_f32_e32 v65, v65, v67
	s_waitcnt vmcnt(1)
	v_mul_f32_e32 v67, v9, v9
	v_mul_f32_e32 v82, v11, v11
	s_waitcnt lgkmcnt(0)
	v_add_f32_e32 v64, v64, v66
	ds_bpermute_b32 v66, v89, v64
	v_fmac_f32_e32 v67, v8, v8
	v_fmac_f32_e32 v82, v10, v10
	v_add_f32_e32 v67, v67, v82
	v_add_f32_e32 v65, v65, v67
	s_waitcnt lgkmcnt(0)
	v_add_f32_e32 v64, v64, v66
	ds_bpermute_b32 v66, v90, v64
	s_waitcnt vmcnt(0)
	v_mul_f32_e32 v67, v1, v1
	v_mul_f32_e32 v82, v3, v3
	v_fmac_f32_e32 v67, v0, v0
	v_fmac_f32_e32 v82, v2, v2
	s_waitcnt lgkmcnt(0)
	v_add_f32_e32 v64, v64, v66
	v_mov_b32_e32 v66, v64
	s_nop 1
	v_permlane16_swap_b32_e32 v64, v66
	v_add_f32_e32 v64, v64, v66
	v_mov_b32_e32 v66, v64
	s_nop 1
	v_permlane32_swap_b32_e32 v64, v66
	v_add_f32_e32 v64, v64, v66
	v_fmamk_f32 v64, v64, 0x3a000000, v92
	v_mul_f32_e32 v66, 0x4f800000, v64
	v_cmp_gt_f32_e32 vcc, s23, v64
	s_nop 1
	v_cndmask_b32_e32 v83, v64, v66, vcc
	v_add_f32_e32 v64, v67, v82
	v_add_f32_e32 v82, v65, v64
	v_mov_b64_e32 v[64:65], v[100:101]
	v_mov_b64_e32 v[66:67], v[102:103]
	v_sqrt_f32_e32 v84, v83
	ds_bpermute_b32 v95, v87, v82
	v_add_u32_e32 v85, -1, v84
	v_fma_f32 v94, -v85, v84, v83
	v_cmp_ge_f32_e64 s[0:1], 0, v94
	v_add_u32_e32 v94, 1, v84
	s_waitcnt lgkmcnt(0)
	v_add_f32_e32 v82, v82, v95
	v_cndmask_b32_e64 v85, v84, v85, s[0:1]
	v_fma_f32 v84, -v94, v84, v83
	v_cmp_lt_f32_e64 s[0:1], 0, v84
	s_nop 1
	v_cndmask_b32_e64 v84, v85, v94, s[0:1]
	v_mul_f32_e32 v85, 0x37800000, v84
	v_cndmask_b32_e32 v84, v84, v85, vcc
	ds_bpermute_b32 v85, v88, v82
	v_cmp_class_f32_e32 vcc, v83, v93
	s_waitcnt lgkmcnt(0)
	v_add_f32_e32 v82, v82, v85
	ds_bpermute_b32 v85, v89, v82
	v_cndmask_b32_e32 v83, v84, v83, vcc
	v_div_scale_f32 v84, s[0:1], v83, v83, 1.0
	v_rcp_f32_e32 v94, v84
	s_waitcnt lgkmcnt(0)
	v_add_f32_e32 v82, v82, v85
	ds_bpermute_b32 v85, v90, v82
	v_fma_f32 v95, -v84, v94, 1.0
	v_fmac_f32_e32 v94, v95, v94
	v_div_scale_f32 v95, vcc, 1.0, v83, 1.0
	s_waitcnt lgkmcnt(0)
	v_add_f32_e32 v82, v82, v85
	v_mov_b32_e32 v85, v82
	s_nop 1
	v_permlane16_swap_b32_e32 v82, v85
	v_add_f32_e32 v82, v82, v85
	v_mov_b32_e32 v85, v82
	s_nop 1
	v_permlane32_swap_b32_e32 v82, v85
	v_add_f32_e32 v82, v82, v85
	v_fmamk_f32 v82, v82, 0x3a000000, v92
	v_mul_f32_e32 v85, 0x4f800000, v82
	v_cmp_gt_f32_e64 s[0:1], s23, v82
	v_mul_f32_e32 v96, v95, v94
	v_fma_f32 v97, -v84, v96, v95
	v_cndmask_b32_e64 v82, v82, v85, s[0:1]
	v_sqrt_f32_e32 v85, v82
	v_fmac_f32_e32 v96, v97, v94
	v_fma_f32 v84, -v84, v96, v95
	v_div_fmas_f32 v84, v84, v94, v96
	v_add_u32_e32 v95, -1, v85
	v_fma_f32 v97, -v95, v85, v82
	v_cmp_ge_f32_e64 s[4:5], 0, v97
	v_add_u32_e32 v97, 1, v85
	s_nop 0
	v_cndmask_b32_e64 v95, v85, v95, s[4:5]
	v_fma_f32 v85, -v97, v85, v82
	v_cmp_lt_f32_e64 s[4:5], 0, v85
	s_nop 1
	v_cndmask_b32_e64 v85, v95, v97, s[4:5]
	v_mul_f32_e32 v95, 0x37800000, v85
	v_cndmask_b32_e64 v85, v85, v95, s[0:1]
	v_cmp_class_f32_e64 s[0:1], v82, v93
	v_div_fixup_f32 v95, v84, v83, 1.0
	v_mul_f32_e32 v56, v95, v56
	v_cndmask_b32_e64 v82, v85, v82, s[0:1]
	v_div_scale_f32 v85, s[0:1], v82, v82, 1.0
	v_rcp_f32_e32 v97, v85
	v_mul_f32_e32 v57, v95, v57
	v_fma_f32 v83, -v85, v97, 1.0
	v_fmac_f32_e32 v97, v83, v97
	v_div_scale_f32 v83, vcc, 1.0, v82, 1.0
	v_mul_f32_e32 v84, v83, v97
	v_fma_f32 v94, -v85, v84, v83
	v_fmac_f32_e32 v84, v94, v97
	v_fma_f32 v83, -v85, v84, v83
	v_mul_f32_e32 v56, v64, v56
	v_mul_f32_e32 v57, v65, v57
	v_div_fmas_f32 v83, v83, v97, v84
	v_cvt_pk_bf16_f32 v56, v56, v57
	v_mul_f32_e32 v57, v95, v58
	v_div_fixup_f32 v94, v83, v82, 1.0
	v_lshl_add_u64 v[84:85], v[72:73], 0, s[26:27]
	v_lshl_add_u64 v[82:83], v[72:73], 0, s[18:19]
	v_mul_f32_e32 v57, v66, v57
	v_mul_f32_e32 v58, v95, v59
	v_mul_f32_e32 v58, v67, v58
	v_cvt_pk_bf16_f32 v57, v57, v58
	global_store_dwordx2 v[84:85], v[56:57], off
	s_cbranch_scc1 .LBB0_120
	v_mul_f32_e32 v56, v94, v60
	v_mul_f32_e32 v57, v94, v61
	v_mul_f32_e32 v56, v64, v56
	v_mul_f32_e32 v57, v65, v57
	v_cvt_pk_bf16_f32 v56, v56, v57
	v_mul_f32_e32 v57, v94, v62
	v_mul_f32_e32 v57, v66, v57
	v_mul_f32_e32 v58, v94, v63
	v_mul_f32_e32 v58, v67, v58
	v_cvt_pk_bf16_f32 v57, v57, v58
	global_store_dwordx2 v[82:83], v[56:57], off
.LBB0_120:
	v_mov_b64_e32 v[56:57], v[104:105]
	v_mov_b64_e32 v[58:59], v[106:107]
	v_mul_f32_e32 v48, v95, v48
	v_mul_f32_e32 v49, v95, v49
	v_cndmask_b32_e64 v60, 0, 1, s[16:17]
	v_mul_f32_e32 v50, v95, v50
	v_mul_f32_e32 v51, v95, v51
	v_cmp_ne_u32_e64 s[0:1], 1, v60
	s_andn2_b64 vcc, exec, s[16:17]
	v_mul_f32_e32 v48, v56, v48
	v_mul_f32_e32 v49, v57, v49
	v_mul_f32_e32 v50, v58, v50
	v_mul_f32_e32 v51, v59, v51
	v_cvt_pk_bf16_f32 v48, v48, v49
	v_cvt_pk_bf16_f32 v49, v50, v51
	global_store_dwordx2 v[84:85], v[48:49], off offset:512
	s_cbranch_vccnz .LBB0_122
	v_mul_f32_e32 v48, v94, v52
	v_mul_f32_e32 v49, v94, v53
	v_mul_f32_e32 v48, v56, v48
	v_mul_f32_e32 v49, v57, v49
	v_cvt_pk_bf16_f32 v48, v48, v49
	v_mul_f32_e32 v49, v94, v54
	v_mul_f32_e32 v49, v58, v49
	v_mul_f32_e32 v50, v94, v55
	v_mul_f32_e32 v50, v59, v50
	v_cvt_pk_bf16_f32 v49, v49, v50
	global_store_dwordx2 v[82:83], v[48:49], off offset:512
.LBB0_122:
	v_mov_b64_e32 v[48:49], v[108:109]
	v_mov_b64_e32 v[50:51], v[110:111]
	v_mul_f32_e32 v40, v95, v40
	v_mul_f32_e32 v41, v95, v41
	v_mul_f32_e32 v42, v95, v42
	v_mul_f32_e32 v43, v95, v43
	s_and_b64 vcc, exec, s[0:1]
	v_mul_f32_e32 v40, v48, v40
	v_mul_f32_e32 v41, v49, v41
	v_mul_f32_e32 v42, v50, v42
	v_mul_f32_e32 v43, v51, v43
	v_cvt_pk_bf16_f32 v40, v40, v41
	v_cvt_pk_bf16_f32 v41, v42, v43
	global_store_dwordx2 v[84:85], v[40:41], off offset:1024
	s_cbranch_vccnz .LBB0_124
	v_mul_f32_e32 v40, v94, v44
	v_mul_f32_e32 v41, v94, v45
	v_mul_f32_e32 v40, v48, v40
	v_mul_f32_e32 v41, v49, v41
	v_cvt_pk_bf16_f32 v40, v40, v41
	v_mul_f32_e32 v41, v94, v46
	v_mul_f32_e32 v41, v50, v41
	v_mul_f32_e32 v42, v94, v47
	v_mul_f32_e32 v42, v51, v42
	v_cvt_pk_bf16_f32 v41, v41, v42
	global_store_dwordx2 v[82:83], v[40:41], off offset:1024
.LBB0_124:
	v_mov_b64_e32 v[40:41], v[112:113]
	v_mov_b64_e32 v[42:43], v[114:115]
	v_mul_f32_e32 v32, v95, v32
	v_mul_f32_e32 v33, v95, v33
	v_mul_f32_e32 v34, v95, v34
	v_mul_f32_e32 v35, v95, v35
	s_and_b64 vcc, exec, s[0:1]
	v_mul_f32_e32 v32, v40, v32
	v_mul_f32_e32 v33, v41, v33
	v_mul_f32_e32 v34, v42, v34
	v_mul_f32_e32 v35, v43, v35
	v_cvt_pk_bf16_f32 v32, v32, v33
	v_cvt_pk_bf16_f32 v33, v34, v35
	global_store_dwordx2 v[84:85], v[32:33], off offset:1536
	s_cbranch_vccnz .LBB0_126
	v_mul_f32_e32 v32, v94, v36
	v_mul_f32_e32 v33, v94, v37
	v_mul_f32_e32 v32, v40, v32
	v_mul_f32_e32 v33, v41, v33
	v_cvt_pk_bf16_f32 v32, v32, v33
	v_mul_f32_e32 v33, v94, v38
	v_mul_f32_e32 v33, v42, v33
	v_mul_f32_e32 v34, v94, v39
	v_mul_f32_e32 v34, v43, v34
	v_cvt_pk_bf16_f32 v33, v33, v34
	global_store_dwordx2 v[82:83], v[32:33], off offset:1536
.LBB0_126:
	v_mov_b64_e32 v[32:33], v[116:117]
	v_mov_b64_e32 v[34:35], v[118:119]
	v_mul_f32_e32 v28, v95, v28
	v_mul_f32_e32 v29, v95, v29
	v_mul_f32_e32 v30, v95, v30
	v_mul_f32_e32 v31, v95, v31
	s_and_b64 vcc, exec, s[0:1]
	v_mul_f32_e32 v28, v32, v28
	v_mul_f32_e32 v29, v33, v29
	v_mul_f32_e32 v30, v34, v30
	v_mul_f32_e32 v31, v35, v31
	v_cvt_pk_bf16_f32 v28, v28, v29
	v_cvt_pk_bf16_f32 v29, v30, v31
	global_store_dwordx2 v[84:85], v[28:29], off offset:2048
	s_cbranch_vccnz .LBB0_128
	v_mul_f32_e32 v24, v94, v24
	v_mul_f32_e32 v25, v94, v25
	v_mul_f32_e32 v24, v32, v24
	v_mul_f32_e32 v25, v33, v25
	v_cvt_pk_bf16_f32 v24, v24, v25
	v_mul_f32_e32 v25, v94, v26
	v_mul_f32_e32 v25, v34, v25
	v_mul_f32_e32 v26, v94, v27
	v_mul_f32_e32 v26, v35, v26
	v_cvt_pk_bf16_f32 v25, v25, v26
	global_store_dwordx2 v[82:83], v[24:25], off offset:2048
.LBB0_128:
	v_mov_b64_e32 v[24:25], v[120:121]
	v_mov_b64_e32 v[26:27], v[122:123]
	v_mul_f32_e32 v20, v95, v20
	v_mul_f32_e32 v21, v95, v21
	v_mul_f32_e32 v22, v95, v22
	v_mul_f32_e32 v23, v95, v23
	s_and_b64 vcc, exec, s[0:1]
	v_mul_f32_e32 v20, v24, v20
	v_mul_f32_e32 v21, v25, v21
	v_mul_f32_e32 v22, v26, v22
	v_mul_f32_e32 v23, v27, v23
	v_cvt_pk_bf16_f32 v20, v20, v21
	v_cvt_pk_bf16_f32 v21, v22, v23
	global_store_dwordx2 v[84:85], v[20:21], off offset:2560
	s_cbranch_vccnz .LBB0_130
	v_mul_f32_e32 v16, v94, v16
	v_mul_f32_e32 v17, v94, v17
	v_mul_f32_e32 v16, v24, v16
	v_mul_f32_e32 v17, v25, v17
	v_cvt_pk_bf16_f32 v16, v16, v17
	v_mul_f32_e32 v17, v94, v18
	v_mul_f32_e32 v17, v26, v17
	v_mul_f32_e32 v18, v94, v19
	v_mul_f32_e32 v18, v27, v18
	v_cvt_pk_bf16_f32 v17, v17, v18
	global_store_dwordx2 v[82:83], v[16:17], off offset:2560
.LBB0_130:
	v_mov_b64_e32 v[16:17], v[124:125]
	v_mov_b64_e32 v[18:19], v[126:127]
	v_mul_f32_e32 v12, v95, v12
	v_mul_f32_e32 v13, v95, v13
	v_mul_f32_e32 v14, v95, v14
	v_mul_f32_e32 v15, v95, v15
	s_and_b64 vcc, exec, s[0:1]
	v_mul_f32_e32 v12, v16, v12
	v_mul_f32_e32 v13, v17, v13
	v_mul_f32_e32 v14, v18, v14
	v_mul_f32_e32 v15, v19, v15
	v_cvt_pk_bf16_f32 v12, v12, v13
	v_cvt_pk_bf16_f32 v13, v14, v15
	global_store_dwordx2 v[84:85], v[12:13], off offset:3072
	s_cbranch_vccnz .LBB0_132
	v_mul_f32_e32 v8, v94, v8
	v_mul_f32_e32 v9, v94, v9
	v_mul_f32_e32 v8, v16, v8
	v_mul_f32_e32 v9, v17, v9
	v_cvt_pk_bf16_f32 v8, v8, v9
	v_mul_f32_e32 v9, v94, v10
	v_mul_f32_e32 v9, v18, v9
	v_mul_f32_e32 v10, v94, v11
	v_mul_f32_e32 v10, v19, v10
	v_cvt_pk_bf16_f32 v9, v9, v10
	global_store_dwordx2 v[82:83], v[8:9], off offset:3072
.LBB0_132:
	v_mov_b64_e32 v[8:9], v[128:129]
	v_mov_b64_e32 v[10:11], v[130:131]
	v_mul_f32_e32 v4, v95, v4
	v_mul_f32_e32 v5, v95, v5
	v_mul_f32_e32 v6, v95, v6
	v_mul_f32_e32 v7, v95, v7
	s_and_b64 vcc, exec, s[0:1]
	v_mul_f32_e32 v4, v8, v4
	v_mul_f32_e32 v5, v9, v5
	v_mul_f32_e32 v6, v10, v6
	v_mul_f32_e32 v7, v11, v7
	v_cvt_pk_bf16_f32 v4, v4, v5
	v_cvt_pk_bf16_f32 v5, v6, v7
	global_store_dwordx2 v[84:85], v[4:5], off offset:3584
	s_cbranch_vccnz .LBB0_117
	v_mul_f32_e32 v0, v94, v0
	v_mul_f32_e32 v1, v94, v1
	v_mul_f32_e32 v0, v8, v0
	v_mul_f32_e32 v1, v9, v1
	v_cvt_pk_bf16_f32 v0, v0, v1
	v_mul_f32_e32 v1, v94, v2
	v_mul_f32_e32 v1, v10, v1
	v_mul_f32_e32 v2, v94, v3
	v_mul_f32_e32 v2, v11, v2
	v_cvt_pk_bf16_f32 v1, v1, v2
	global_store_dwordx2 v[82:83], v[0:1], off offset:3584
	s_branch .LBB0_117

.LBB0_316:
	v_lshlrev_b32_e32 v251, 2, v11
	v_lshrrev_b32_e32 v252, 4, v10
	v_lshlrev_b32_e32 v252, 8, v252
	s_lshl_b32 s98, s26, 3
	v_add_u32_e32 v252, s98, v252
	v_add_u32_e32 v252, 0x23800, v252
	v_and_b32_e32 v253, 15, v10
	v_lshlrev_b32_e32 v253, 6, v253
	v_add_u32_e32 v253, 0x23800, v253
	v_and_b32_e32 v4, 0xffffffc0, v10
	v_xor_b32_e32 v3, 8, v10
	v_add_u32_e32 v4, 64, v4
	v_cmp_lt_i32_e32 vcc, v3, v4
	v_lshlrev_b32_e32 v0, 1, v11
	s_lshl_b32 s14, s26, 3
	v_cndmask_b32_e32 v3, v10, v3, vcc
	v_lshlrev_b32_e32 v139, 2, v3
	v_xor_b32_e32 v3, 4, v10
	v_cmp_lt_i32_e32 vcc, v3, v4
	v_ashrrev_i32_e32 v1, 31, v0
	v_and_b32_e32 v2, 8, v10
	v_cndmask_b32_e32 v3, v10, v3, vcc
	v_lshlrev_b32_e32 v234, 2, v3
	v_xor_b32_e32 v3, 2, v10
	v_cmp_lt_i32_e32 vcc, v3, v4
	s_add_i32 s14, s14, 0
	v_cmp_eq_u32_e64 s[0:1], 0, v2
	v_cndmask_b32_e32 v3, v10, v3, vcc
	v_lshlrev_b32_e32 v235, 2, v3
	v_xor_b32_e32 v3, 1, v10
	v_cmp_lt_i32_e32 vcc, v3, v4
	v_and_b32_e32 v2, 4, v10
	s_add_i32 s14, s14, 0x23800
	v_cndmask_b32_e32 v3, v10, v3, vcc
	v_lshlrev_b32_e32 v236, 2, v3
	v_and_b32_e32 v3, 3, v10
	v_cmp_eq_u32_e64 s[4:5], 0, v3
	v_lshlrev_b32_e32 v3, 3, v10
	v_and_b32_e32 v3, 0x1c0, v3
	v_lshlrev_b64 v[8:9], 2, v[0:1]
	v_cmp_eq_u32_e64 s[10:11], 0, v2
	v_add3_u32 v237, s14, v3, v2
	v_lshl_add_u64 v[2:3], s[6:7], 0, v[8:9]
	s_mov_b64 s[6:7], 0x1000
	v_lshl_add_u64 v[10:11], v[2:3], 0, s[6:7]
	s_mov_b64 s[6:7], 0x2000
	v_lshl_add_u64 v[12:13], v[2:3], 0, s[6:7]
	s_mov_b64 s[6:7], 0x3000
	v_lshl_add_u64 v[14:15], v[2:3], 0, s[6:7]
	s_mov_b64 s[6:7], 0x4000
	v_lshl_add_u64 v[16:17], v[2:3], 0, s[6:7]
	s_mov_b64 s[6:7], 0x5000
	v_lshl_add_u64 v[18:19], v[2:3], 0, s[6:7]
	s_mov_b64 s[6:7], 0x6000
	v_lshl_add_u64 v[20:21], v[2:3], 0, s[6:7]
	s_mov_b64 s[6:7], 0x7000
	v_lshl_add_u64 v[22:23], v[2:3], 0, s[6:7]
	s_mov_b64 s[6:7], 0x8000
	v_lshl_add_u64 v[24:25], v[2:3], 0, s[6:7]
	s_mov_b64 s[6:7], 0x9000
	v_lshl_add_u64 v[26:27], v[2:3], 0, s[6:7]
	s_mov_b64 s[6:7], 0xa000
	v_lshl_add_u64 v[28:29], v[2:3], 0, s[6:7]
	s_mov_b64 s[6:7], 0xb000
	v_lshl_add_u64 v[30:31], v[2:3], 0, s[6:7]
	s_mov_b64 s[6:7], 0xc000
	v_lshl_add_u64 v[32:33], v[2:3], 0, s[6:7]
	s_mov_b64 s[6:7], 0xd000
	v_lshl_add_u64 v[34:35], v[2:3], 0, s[6:7]
	s_mov_b64 s[6:7], 0xe000
	v_lshl_add_u64 v[36:37], v[2:3], 0, s[6:7]
	s_mov_b64 s[6:7], 0xf000
	v_lshl_add_u64 v[38:39], v[2:3], 0, s[6:7]
	s_mov_b64 s[6:7], 0x10000
	v_lshl_add_u64 v[40:41], v[2:3], 0, s[6:7]
	s_mov_b64 s[6:7], 0x11000
	v_lshl_add_u64 v[42:43], v[2:3], 0, s[6:7]
	s_mov_b64 s[6:7], 0x12000
	v_lshl_add_u64 v[44:45], v[2:3], 0, s[6:7]
	s_mov_b64 s[6:7], 0x13000
	v_lshl_add_u64 v[46:47], v[2:3], 0, s[6:7]
	s_mov_b64 s[6:7], 0x14000
	v_lshl_add_u64 v[48:49], v[2:3], 0, s[6:7]
	s_mov_b64 s[6:7], 0x15000
	v_lshl_add_u64 v[50:51], v[2:3], 0, s[6:7]
	s_mov_b64 s[6:7], 0x16000
	v_lshl_add_u64 v[52:53], v[2:3], 0, s[6:7]
	s_mov_b64 s[6:7], 0x17000
	v_lshl_add_u64 v[54:55], v[2:3], 0, s[6:7]
	s_mov_b64 s[6:7], 0x18000
	v_lshl_add_u64 v[56:57], v[2:3], 0, s[6:7]
	s_mov_b64 s[6:7], 0x19000
	v_lshl_add_u64 v[58:59], v[2:3], 0, s[6:7]
	s_mov_b64 s[6:7], 0x1a000
	v_lshl_add_u64 v[60:61], v[2:3], 0, s[6:7]
	s_mov_b64 s[6:7], 0x1b000
	s_add_u32 s18, s16, 0x1b000000
	v_lshl_add_u64 v[62:63], v[2:3], 0, s[6:7]
	s_mov_b64 s[6:7], 0x1c000
	s_addc_u32 s19, s17, 0
	v_lshl_add_u64 v[64:65], v[2:3], 0, s[6:7]
	s_mov_b64 s[6:7], 0x1d000
	s_add_u32 s20, s16, 0x1f000000
	v_lshl_add_u64 v[66:67], v[2:3], 0, s[6:7]
	s_mov_b64 s[6:7], 0x1e000
	s_addc_u32 s21, s17, 0
	v_lshl_add_u64 v[4:5], s[8:9], 0, v[8:9]
	v_lshl_add_u64 v[6:7], s[12:13], 0, v[8:9]
	v_lshl_add_u64 v[8:9], s[22:23], 0, v[8:9]
	v_lshl_add_u64 v[68:69], v[2:3], 0, s[6:7]
	s_lshl_b32 s30, s2, 7
	s_lshl_b32 s31, s3, 7
	s_add_i32 s34, 0, 0x23810
	s_add_i32 s35, 0, 0x23820
	s_add_i32 s36, 0, 0x23830
	s_mov_b32 s37, 0x3a800000
	s_mov_b32 s38, 0xf800000
	v_mov_b32_e32 v238, 0x260
	s_mov_b32 s39, 0x23000000
	s_add_i32 s40, 0, 0x23840
	s_add_i32 s41, 0, 0x23850
	s_add_i32 s42, 0, 0x23860
	s_add_i32 s43, 0, 0x23870
	s_add_i32 s44, 0, 0x23880
	s_add_i32 s45, 0, 0x23890
	s_add_i32 s46, 0, 0x238a0
	s_add_i32 s47, 0, 0x238b0
	s_add_i32 s48, 0, 0x238c0
	s_add_i32 s49, 0, 0x238d0
	s_add_i32 s50, 0, 0x238e0
	s_add_i32 s51, 0, 0x238f0
	s_add_i32 s52, 0, 0x23900
	s_add_i32 s53, 0, 0x23910
	s_add_i32 s54, 0, 0x23920
	s_add_i32 s55, 0, 0x23930
	s_add_i32 s56, 0, 0x23940
	s_add_i32 s57, 0, 0x23950
	s_add_i32 s58, 0, 0x23960
	s_add_i32 s59, 0, 0x23970
	s_add_i32 s60, 0, 0x23980
	s_add_i32 s61, 0, 0x23990
	s_add_i32 s62, 0, 0x239a0
	s_add_i32 s63, 0, 0x239b0
	s_add_i32 s64, 0, 0x239c0
	s_add_i32 s65, 0, 0x239d0
	s_add_i32 s66, 0, 0x239e0
	s_add_i32 s67, 0, 0x239f0
	s_add_i32 s68, 0, 0x23a00
	s_add_i32 s69, 0, 0x23a10
	s_add_i32 s70, 0, 0x23a20
	s_add_i32 s71, 0, 0x23a30
	s_add_i32 s72, 0, 0x23a40
	s_add_i32 s73, 0, 0x23a50
	s_add_i32 s74, 0, 0x23a60
	s_add_i32 s75, 0, 0x23a70
	s_add_i32 s76, 0, 0x23a80
	s_add_i32 s77, 0, 0x23a90
	s_add_i32 s78, 0, 0x23aa0
	s_add_i32 s79, 0, 0x23ab0
	s_add_i32 s80, 0, 0x23ac0
	s_add_i32 s81, 0, 0x23ad0
	s_add_i32 s82, 0, 0x23ae0
	s_add_i32 s83, 0, 0x23af0
	s_add_i32 s84, 0, 0x23b00
	s_add_i32 s85, 0, 0x23b10
	s_add_i32 s87, 0, 0x23b20
	s_add_i32 s88, 0, 0x23b30
	s_add_i32 s89, 0, 0x23b40
	s_add_i32 s90, 0, 0x23b50
	s_add_i32 s91, 0, 0x23b60
	s_add_i32 s92, 0, 0x23b70
	s_add_i32 s93, 0, 0x23b80
	s_add_i32 s94, 0, 0x23b90
	s_add_i32 s95, 0, 0x23ba0
	s_add_i32 s96, 0, 0x23bb0
	s_add_i32 s97, 0, 0x23bc0
	s_add_i32 s26, 0, 0x23bd0
	s_add_i32 s27, 0, 0x23be0
	s_add_i32 s14, 0, 0x23bf0
	s_mov_b32 s15, s2
	s_branch .LBB0_318
.LBB0_317:
	s_add_i32 s15, s15, s3
	s_add_i32 s30, s30, s31
	s_cmpk_gt_i32 s15, 0xff
	s_cbranch_scc1 .LBB0_456
	s_mov_b64 s[6:7], 0x1000
	v_lshl_add_u64 v[10:11], v[2:3], 0, s[6:7]
	s_mov_b64 s[6:7], 0x2000
	v_lshl_add_u64 v[12:13], v[2:3], 0, s[6:7]
	s_mov_b64 s[6:7], 0x3000
	v_lshl_add_u64 v[14:15], v[2:3], 0, s[6:7]
	s_mov_b64 s[6:7], 0x4000
	v_lshl_add_u64 v[16:17], v[2:3], 0, s[6:7]
	s_mov_b64 s[6:7], 0x5000
	v_lshl_add_u64 v[18:19], v[2:3], 0, s[6:7]
	s_mov_b64 s[6:7], 0x6000
	v_lshl_add_u64 v[20:21], v[2:3], 0, s[6:7]
	s_mov_b64 s[6:7], 0x7000
	v_lshl_add_u64 v[22:23], v[2:3], 0, s[6:7]
	s_mov_b64 s[6:7], 0x8000
	v_lshl_add_u64 v[24:25], v[2:3], 0, s[6:7]
	s_mov_b64 s[6:7], 0x9000
	v_lshl_add_u64 v[26:27], v[2:3], 0, s[6:7]
	s_mov_b64 s[6:7], 0xa000
	v_lshl_add_u64 v[28:29], v[2:3], 0, s[6:7]
	s_mov_b64 s[6:7], 0xb000
	v_lshl_add_u64 v[30:31], v[2:3], 0, s[6:7]
	s_mov_b64 s[6:7], 0xc000
	v_lshl_add_u64 v[32:33], v[2:3], 0, s[6:7]
	s_mov_b64 s[6:7], 0xd000
	v_lshl_add_u64 v[34:35], v[2:3], 0, s[6:7]
	s_mov_b64 s[6:7], 0xe000
	v_lshl_add_u64 v[36:37], v[2:3], 0, s[6:7]
	s_mov_b64 s[6:7], 0xf000
	v_lshl_add_u64 v[38:39], v[2:3], 0, s[6:7]
	s_mov_b64 s[6:7], 0x10000
	v_lshl_add_u64 v[40:41], v[2:3], 0, s[6:7]
	s_mov_b64 s[6:7], 0x11000
	v_lshl_add_u64 v[42:43], v[2:3], 0, s[6:7]
	s_mov_b64 s[6:7], 0x12000
	v_lshl_add_u64 v[44:45], v[2:3], 0, s[6:7]
	s_mov_b64 s[6:7], 0x13000
	v_lshl_add_u64 v[46:47], v[2:3], 0, s[6:7]
	s_mov_b64 s[6:7], 0x14000
	v_lshl_add_u64 v[48:49], v[2:3], 0, s[6:7]
	s_mov_b64 s[6:7], 0x15000
	v_lshl_add_u64 v[50:51], v[2:3], 0, s[6:7]
	s_mov_b64 s[6:7], 0x16000
	v_lshl_add_u64 v[52:53], v[2:3], 0, s[6:7]
	s_mov_b64 s[6:7], 0x17000
	v_lshl_add_u64 v[54:55], v[2:3], 0, s[6:7]
	s_mov_b64 s[6:7], 0x18000
	v_lshl_add_u64 v[56:57], v[2:3], 0, s[6:7]
	s_mov_b64 s[6:7], 0x19000
	v_lshl_add_u64 v[58:59], v[2:3], 0, s[6:7]
	s_mov_b64 s[6:7], 0x1a000
	v_lshl_add_u64 v[60:61], v[2:3], 0, s[6:7]
	s_mov_b64 s[6:7], 0x1b000
	v_lshl_add_u64 v[62:63], v[2:3], 0, s[6:7]
	s_mov_b64 s[6:7], 0x1c000
	v_lshl_add_u64 v[64:65], v[2:3], 0, s[6:7]
	s_mov_b64 s[6:7], 0x1d000
	v_lshl_add_u64 v[66:67], v[2:3], 0, s[6:7]
	s_mov_b64 s[6:7], 0x1e000
	v_lshl_add_u64 v[68:69], v[2:3], 0, s[6:7]
.LBB0_318:
	global_load_dwordx2 v[70:71], v[2:3], off
	global_load_dwordx2 v[72:73], v[10:11], off
	global_load_dwordx2 v[74:75], v[12:13], off
	global_load_dwordx2 v[76:77], v[14:15], off
	global_load_dwordx2 v[78:79], v[16:17], off
	global_load_dwordx2 v[80:81], v[18:19], off
	global_load_dwordx2 v[82:83], v[20:21], off
	global_load_dwordx2 v[84:85], v[22:23], off
	global_load_dwordx2 v[86:87], v[24:25], off
	global_load_dwordx2 v[88:89], v[66:67], off
	global_load_dwordx2 v[90:91], v[68:69], off
	global_load_dwordx2 v[92:93], v[26:27], off
	global_load_dwordx2 v[94:95], v[28:29], off
	global_load_dwordx2 v[96:97], v[30:31], off
	global_load_dwordx2 v[98:99], v[32:33], off
	global_load_dwordx2 v[100:101], v[34:35], off
	global_load_dwordx2 v[102:103], v[36:37], off
	global_load_dwordx2 v[104:105], v[38:39], off
	global_load_dwordx2 v[106:107], v[40:41], off
	global_load_dwordx2 v[108:109], v[42:43], off
	global_load_dwordx2 v[110:111], v[44:45], off
	global_load_dwordx2 v[112:113], v[46:47], off
	global_load_dwordx2 v[114:115], v[48:49], off
	global_load_dwordx2 v[116:117], v[50:51], off
	global_load_dwordx2 v[118:119], v[52:53], off
	global_load_dwordx2 v[120:121], v[54:55], off
	global_load_dwordx2 v[122:123], v[56:57], off
	global_load_dwordx2 v[124:125], v[58:59], off
	global_load_dwordx2 v[126:127], v[60:61], off
	global_load_dwordx2 v[128:129], v[62:63], off
	global_load_dwordx2 v[130:131], v[64:65], off
	global_load_dwordx2 v[132:133], v[4:5], off
	global_load_dwordx2 v[134:135], v[6:7], off
	global_load_dwordx2 v[136:137], v[8:9], off
	s_and_b32 s6, s15, 0x7f
	v_mov_b32_e32 v141, 0
	s_cmp_eq_u32 s6, 0
	s_mov_b32 s86, 0
	s_mov_b32 s33, -1
	v_mov_b32_e32 v140, v141
	v_mov_b32_e32 v142, v141
	v_mov_b32_e32 v143, v141
	v_mov_b32_e32 v144, v141
	v_mov_b32_e32 v145, v141
	v_mov_b32_e32 v146, v141
	v_mov_b32_e32 v147, v141
	v_mov_b32_e32 v148, v141
	v_mov_b32_e32 v149, v141
	v_mov_b32_e32 v150, v141
	v_mov_b32_e32 v151, v141
	v_mov_b32_e32 v152, v141
	v_mov_b32_e32 v153, v141
	v_mov_b32_e32 v154, v141
	v_mov_b32_e32 v155, v141
	v_mov_b32_e32 v156, v141
	v_mov_b32_e32 v157, v141
	v_mov_b32_e32 v158, v141
	v_mov_b32_e32 v159, v141
	v_mov_b32_e32 v160, v141
	v_mov_b32_e32 v161, v141
	v_mov_b32_e32 v162, v141
	v_mov_b32_e32 v163, v141
	v_mov_b32_e32 v164, v141
	v_mov_b32_e32 v165, v141
	v_mov_b32_e32 v166, v141
	v_mov_b32_e32 v167, v141
	v_mov_b32_e32 v202, v141
	v_mov_b32_e32 v203, v141
	v_mov_b32_e32 v200, v141
	v_mov_b32_e32 v201, v141
	v_mov_b32_e32 v168, v141
	v_mov_b32_e32 v169, v141
	v_mov_b32_e32 v170, v141
	v_mov_b32_e32 v171, v141
	v_mov_b32_e32 v172, v141
	v_mov_b32_e32 v173, v141
	v_mov_b32_e32 v174, v141
	v_mov_b32_e32 v175, v141
	v_mov_b32_e32 v176, v141
	s_cselect_b64 s[22:23], -1, 0
	v_mov_b32_e32 v177, v141
	v_mov_b32_e32 v178, v141
	v_mov_b32_e32 v179, v141
	v_mov_b32_e32 v180, v141
	v_mov_b32_e32 v181, v141
	v_mov_b32_e32 v182, v141
	v_mov_b32_e32 v183, v141
	v_mov_b32_e32 v184, v141
	v_mov_b32_e32 v185, v141
	v_mov_b32_e32 v186, v141
	s_waitcnt vmcnt(23)
	v_mov_b32_e32 v138, v91
	v_mov_b32_e32 v187, v141
	v_mov_b32_e32 v188, v141
	v_mov_b32_e32 v189, v141
	v_mov_b32_e32 v190, v141
	v_mov_b32_e32 v191, v141
	v_mov_b32_e32 v192, v141
	v_mov_b32_e32 v193, v141
	v_mov_b32_e32 v194, v141
	v_mov_b32_e32 v195, v141
	s_sub_i32 s98, s30, 32
	s_lshl_b32 s98, s98, 11
	s_ashr_i32 s99, s98, 31
	s_add_u32 s100, s98, s20
	s_addc_u32 s101, s99, s21
	s_add_u32 s98, s98, s18
	s_addc_u32 s99, s99, s19
	global_load_dword v10, v251, s[98:99]
	global_load_dword v26, v251, s[100:101]
	global_load_dword v11, v251, s[98:99] offset:2048
	global_load_dword v27, v251, s[100:101] offset:2048
	s_add_u32 s98, s98, 0x1000
	s_addc_u32 s99, s99, 0
	s_add_u32 s100, s100, 0x1000
	s_addc_u32 s101, s101, 0
	global_load_dword v12, v251, s[98:99]
	global_load_dword v28, v251, s[100:101]
	global_load_dword v13, v251, s[98:99] offset:2048
	global_load_dword v29, v251, s[100:101] offset:2048
	s_add_u32 s98, s98, 0x1000
	s_addc_u32 s99, s99, 0
	s_add_u32 s100, s100, 0x1000
	s_addc_u32 s101, s101, 0
	global_load_dword v14, v251, s[98:99]
	global_load_dword v30, v251, s[100:101]
	global_load_dword v15, v251, s[98:99] offset:2048
	global_load_dword v31, v251, s[100:101] offset:2048
	s_add_u32 s98, s98, 0x1000
	s_addc_u32 s99, s99, 0
	s_add_u32 s100, s100, 0x1000
	s_addc_u32 s101, s101, 0
	global_load_dword v16, v251, s[98:99]
	global_load_dword v32, v251, s[100:101]
	global_load_dword v17, v251, s[98:99] offset:2048
	global_load_dword v33, v251, s[100:101] offset:2048
	s_add_u32 s98, s98, 0x1000
	s_addc_u32 s99, s99, 0
	s_add_u32 s100, s100, 0x1000
	s_addc_u32 s101, s101, 0
	global_load_dword v18, v251, s[98:99]
	global_load_dword v34, v251, s[100:101]
	global_load_dword v19, v251, s[98:99] offset:2048
	global_load_dword v35, v251, s[100:101] offset:2048
	s_add_u32 s98, s98, 0x1000
	s_addc_u32 s99, s99, 0
	s_add_u32 s100, s100, 0x1000
	s_addc_u32 s101, s101, 0
	global_load_dword v20, v251, s[98:99]
	global_load_dword v36, v251, s[100:101]
	global_load_dword v21, v251, s[98:99] offset:2048
	global_load_dword v37, v251, s[100:101] offset:2048
	s_add_u32 s98, s98, 0x1000
	s_addc_u32 s99, s99, 0
	s_add_u32 s100, s100, 0x1000
	s_addc_u32 s101, s101, 0
	global_load_dword v22, v251, s[98:99]
	global_load_dword v38, v251, s[100:101]
	global_load_dword v23, v251, s[98:99] offset:2048
	global_load_dword v39, v251, s[100:101] offset:2048
	s_add_u32 s98, s98, 0x1000
	s_addc_u32 s99, s99, 0
	s_add_u32 s100, s100, 0x1000
	s_addc_u32 s101, s101, 0
	global_load_dword v24, v251, s[98:99]
	global_load_dword v40, v251, s[100:101]
	global_load_dword v25, v251, s[98:99] offset:2048
	global_load_dword v41, v251, s[100:101] offset:2048
	s_branch .LBB0_321

.LBB0_321:
	s_add_i32 s24, s30, s86
	s_sub_i32 s28, s24, 32
	s_cmp_lt_i32 s33, 0
	s_cselect_b64 s[6:7], -1, 0
	s_and_b64 s[6:7], s[6:7], s[22:23]
	s_and_b64 vcc, exec, s[6:7]
	s_cbranch_vccnz .Lp2_zero_0
	s_cmp_gt_i32 s33, 0
	s_cbranch_scc1 .Lp2_w16_0
	s_waitcnt vmcnt(0)
	s_branch .Lp2_wd_0
.Lp2_w16_0:
	s_waitcnt vmcnt(16)
.Lp2_wd_0:
	v_lshlrev_b32_e32 v240, 16, v26
	v_and_b32_e32 v241, 0xffff0000, v26
	v_lshlrev_b32_e32 v242, 16, v27
	v_and_b32_e32 v243, 0xffff0000, v27
	v_lshlrev_b32_e32 v244, 16, v28
	v_and_b32_e32 v245, 0xffff0000, v28
	v_lshlrev_b32_e32 v246, 16, v29
	v_and_b32_e32 v247, 0xffff0000, v29
	v_mul_f32_e32 v240, 0xbfb8aa3b, v240
	v_mul_f32_e32 v241, 0xbfb8aa3b, v241
	v_mul_f32_e32 v242, 0xbfb8aa3b, v242
	v_mul_f32_e32 v243, 0xbfb8aa3b, v243
	v_mul_f32_e32 v244, 0xbfb8aa3b, v244
	v_mul_f32_e32 v245, 0xbfb8aa3b, v245
	v_mul_f32_e32 v246, 0xbfb8aa3b, v246
	v_mul_f32_e32 v247, 0xbfb8aa3b, v247
	v_exp_f32_e32 v240, v240
	v_exp_f32_e32 v241, v241
	v_exp_f32_e32 v242, v242
	v_exp_f32_e32 v243, v243
	v_exp_f32_e32 v244, v244
	v_exp_f32_e32 v245, v245
	v_exp_f32_e32 v246, v246
	v_exp_f32_e32 v247, v247
	v_add_f32_e32 v240, 1.0, v240
	v_add_f32_e32 v241, 1.0, v241
	v_add_f32_e32 v242, 1.0, v242
	v_add_f32_e32 v243, 1.0, v243
	v_add_f32_e32 v244, 1.0, v244
	v_add_f32_e32 v245, 1.0, v245
	v_add_f32_e32 v246, 1.0, v246
	v_add_f32_e32 v247, 1.0, v247
	v_rcp_f32_e32 v240, v240
	v_rcp_f32_e32 v241, v241
	v_rcp_f32_e32 v242, v242
	v_rcp_f32_e32 v243, v243
	v_rcp_f32_e32 v244, v244
	v_rcp_f32_e32 v245, v245
	v_rcp_f32_e32 v246, v246
	v_rcp_f32_e32 v247, v247
	v_lshlrev_b32_e32 v42, 16, v10
	v_and_b32_e32 v43, 0xffff0000, v10
	v_lshlrev_b32_e32 v44, 16, v11
	v_and_b32_e32 v45, 0xffff0000, v11
	v_lshlrev_b32_e32 v46, 16, v12
	v_and_b32_e32 v47, 0xffff0000, v12
	v_lshlrev_b32_e32 v48, 16, v13
	v_and_b32_e32 v49, 0xffff0000, v13
	v_mul_f32_e32 v42, v240, v42
	v_mul_f32_e32 v43, v241, v43
	v_mul_f32_e32 v44, v242, v44
	v_mul_f32_e32 v45, v243, v45
	v_mul_f32_e32 v46, v244, v46
	v_mul_f32_e32 v47, v245, v47
	v_mul_f32_e32 v48, v246, v48
	v_mul_f32_e32 v49, v247, v49
	v_lshlrev_b32_e32 v240, 16, v30
	v_and_b32_e32 v241, 0xffff0000, v30
	v_lshlrev_b32_e32 v242, 16, v31
	v_and_b32_e32 v243, 0xffff0000, v31
	v_lshlrev_b32_e32 v244, 16, v32
	v_and_b32_e32 v245, 0xffff0000, v32
	v_lshlrev_b32_e32 v246, 16, v33
	v_and_b32_e32 v247, 0xffff0000, v33
	v_mul_f32_e32 v240, 0xbfb8aa3b, v240
	v_mul_f32_e32 v241, 0xbfb8aa3b, v241
	v_mul_f32_e32 v242, 0xbfb8aa3b, v242
	v_mul_f32_e32 v243, 0xbfb8aa3b, v243
	v_mul_f32_e32 v244, 0xbfb8aa3b, v244
	v_mul_f32_e32 v245, 0xbfb8aa3b, v245
	v_mul_f32_e32 v246, 0xbfb8aa3b, v246
	v_mul_f32_e32 v247, 0xbfb8aa3b, v247
	v_exp_f32_e32 v240, v240
	v_exp_f32_e32 v241, v241
	v_exp_f32_e32 v242, v242
	v_exp_f32_e32 v243, v243
	v_exp_f32_e32 v244, v244
	v_exp_f32_e32 v245, v245
	v_exp_f32_e32 v246, v246
	v_exp_f32_e32 v247, v247
	v_add_f32_e32 v240, 1.0, v240
	v_add_f32_e32 v241, 1.0, v241
	v_add_f32_e32 v242, 1.0, v242
	v_add_f32_e32 v243, 1.0, v243
	v_add_f32_e32 v244, 1.0, v244
	v_add_f32_e32 v245, 1.0, v245
	v_add_f32_e32 v246, 1.0, v246
	v_add_f32_e32 v247, 1.0, v247
	v_rcp_f32_e32 v240, v240
	v_rcp_f32_e32 v241, v241
	v_rcp_f32_e32 v242, v242
	v_rcp_f32_e32 v243, v243
	v_rcp_f32_e32 v244, v244
	v_rcp_f32_e32 v245, v245
	v_rcp_f32_e32 v246, v246
	v_rcp_f32_e32 v247, v247
	v_lshlrev_b32_e32 v50, 16, v14
	v_and_b32_e32 v51, 0xffff0000, v14
	v_lshlrev_b32_e32 v52, 16, v15
	v_and_b32_e32 v53, 0xffff0000, v15
	v_lshlrev_b32_e32 v54, 16, v16
	v_and_b32_e32 v55, 0xffff0000, v16
	v_lshlrev_b32_e32 v56, 16, v17
	v_and_b32_e32 v57, 0xffff0000, v17
	v_mul_f32_e32 v50, v240, v50
	v_mul_f32_e32 v51, v241, v51
	v_mul_f32_e32 v52, v242, v52
	v_mul_f32_e32 v53, v243, v53
	v_mul_f32_e32 v54, v244, v54
	v_mul_f32_e32 v55, v245, v55
	v_mul_f32_e32 v56, v246, v56
	v_mul_f32_e32 v57, v247, v57
	v_lshlrev_b32_e32 v240, 16, v34
	v_and_b32_e32 v241, 0xffff0000, v34
	v_lshlrev_b32_e32 v242, 16, v35
	v_and_b32_e32 v243, 0xffff0000, v35
	v_lshlrev_b32_e32 v244, 16, v36
	v_and_b32_e32 v245, 0xffff0000, v36
	v_lshlrev_b32_e32 v246, 16, v37
	v_and_b32_e32 v247, 0xffff0000, v37
	v_mul_f32_e32 v240, 0xbfb8aa3b, v240
	v_mul_f32_e32 v241, 0xbfb8aa3b, v241
	v_mul_f32_e32 v242, 0xbfb8aa3b, v242
	v_mul_f32_e32 v243, 0xbfb8aa3b, v243
	v_mul_f32_e32 v244, 0xbfb8aa3b, v244
	v_mul_f32_e32 v245, 0xbfb8aa3b, v245
	v_mul_f32_e32 v246, 0xbfb8aa3b, v246
	v_mul_f32_e32 v247, 0xbfb8aa3b, v247
	v_exp_f32_e32 v240, v240
	v_exp_f32_e32 v241, v241
	v_exp_f32_e32 v242, v242
	v_exp_f32_e32 v243, v243
	v_exp_f32_e32 v244, v244
	v_exp_f32_e32 v245, v245
	v_exp_f32_e32 v246, v246
	v_exp_f32_e32 v247, v247
	v_add_f32_e32 v240, 1.0, v240
	v_add_f32_e32 v241, 1.0, v241
	v_add_f32_e32 v242, 1.0, v242
	v_add_f32_e32 v243, 1.0, v243
	v_add_f32_e32 v244, 1.0, v244
	v_add_f32_e32 v245, 1.0, v245
	v_add_f32_e32 v246, 1.0, v246
	v_add_f32_e32 v247, 1.0, v247
	v_rcp_f32_e32 v240, v240
	v_rcp_f32_e32 v241, v241
	v_rcp_f32_e32 v242, v242
	v_rcp_f32_e32 v243, v243
	v_rcp_f32_e32 v244, v244
	v_rcp_f32_e32 v245, v245
	v_rcp_f32_e32 v246, v246
	v_rcp_f32_e32 v247, v247
	v_lshlrev_b32_e32 v58, 16, v18
	v_and_b32_e32 v59, 0xffff0000, v18
	v_lshlrev_b32_e32 v60, 16, v19
	v_and_b32_e32 v61, 0xffff0000, v19
	v_lshlrev_b32_e32 v62, 16, v20
	v_and_b32_e32 v63, 0xffff0000, v20
	v_lshlrev_b32_e32 v64, 16, v21
	v_and_b32_e32 v65, 0xffff0000, v21
	v_mul_f32_e32 v58, v240, v58
	v_mul_f32_e32 v59, v241, v59
	v_mul_f32_e32 v60, v242, v60
	v_mul_f32_e32 v61, v243, v61
	v_mul_f32_e32 v62, v244, v62
	v_mul_f32_e32 v63, v245, v63
	v_mul_f32_e32 v64, v246, v64
	v_mul_f32_e32 v65, v247, v65
	v_lshlrev_b32_e32 v240, 16, v38
	v_and_b32_e32 v241, 0xffff0000, v38
	v_lshlrev_b32_e32 v242, 16, v39
	v_and_b32_e32 v243, 0xffff0000, v39
	v_lshlrev_b32_e32 v244, 16, v40
	v_and_b32_e32 v245, 0xffff0000, v40
	v_lshlrev_b32_e32 v246, 16, v41
	v_and_b32_e32 v247, 0xffff0000, v41
	v_mul_f32_e32 v240, 0xbfb8aa3b, v240
	v_mul_f32_e32 v241, 0xbfb8aa3b, v241
	v_mul_f32_e32 v242, 0xbfb8aa3b, v242
	v_mul_f32_e32 v243, 0xbfb8aa3b, v243
	v_mul_f32_e32 v244, 0xbfb8aa3b, v244
	v_mul_f32_e32 v245, 0xbfb8aa3b, v245
	v_mul_f32_e32 v246, 0xbfb8aa3b, v246
	v_mul_f32_e32 v247, 0xbfb8aa3b, v247
	v_exp_f32_e32 v240, v240
	v_exp_f32_e32 v241, v241
	v_exp_f32_e32 v242, v242
	v_exp_f32_e32 v243, v243
	v_exp_f32_e32 v244, v244
	v_exp_f32_e32 v245, v245
	v_exp_f32_e32 v246, v246
	v_exp_f32_e32 v247, v247
	v_add_f32_e32 v240, 1.0, v240
	v_add_f32_e32 v241, 1.0, v241
	v_add_f32_e32 v242, 1.0, v242
	v_add_f32_e32 v243, 1.0, v243
	v_add_f32_e32 v244, 1.0, v244
	v_add_f32_e32 v245, 1.0, v245
	v_add_f32_e32 v246, 1.0, v246
	v_add_f32_e32 v247, 1.0, v247
	v_rcp_f32_e32 v240, v240
	v_rcp_f32_e32 v241, v241
	v_rcp_f32_e32 v242, v242
	v_rcp_f32_e32 v243, v243
	v_rcp_f32_e32 v244, v244
	v_rcp_f32_e32 v245, v245
	v_rcp_f32_e32 v246, v246
	v_rcp_f32_e32 v247, v247
	v_lshlrev_b32_e32 v66, 16, v22
	v_and_b32_e32 v67, 0xffff0000, v22
	v_lshlrev_b32_e32 v68, 16, v23
	v_and_b32_e32 v69, 0xffff0000, v23
	v_lshlrev_b32_e32 v236, 16, v24
	v_and_b32_e32 v237, 0xffff0000, v24
	v_lshlrev_b32_e32 v238, 16, v25
	v_and_b32_e32 v239, 0xffff0000, v25
	v_mul_f32_e32 v66, v240, v66
	v_mul_f32_e32 v67, v241, v67
	v_mul_f32_e32 v68, v242, v68
	v_mul_f32_e32 v69, v243, v69
	v_mul_f32_e32 v236, v244, v236
	v_mul_f32_e32 v237, v245, v237
	v_mul_f32_e32 v238, v246, v238
	v_mul_f32_e32 v239, v247, v239
	s_branch .Lp2_glud_0
.Lp2_zero_0:
	v_mov_b32_e32 v42, 0
	v_mov_b32_e32 v43, 0
	v_mov_b32_e32 v44, 0
	v_mov_b32_e32 v45, 0
	v_mov_b32_e32 v46, 0
	v_mov_b32_e32 v47, 0
	v_mov_b32_e32 v48, 0
	v_mov_b32_e32 v49, 0
	v_mov_b32_e32 v50, 0
	v_mov_b32_e32 v51, 0
	v_mov_b32_e32 v52, 0
	v_mov_b32_e32 v53, 0
	v_mov_b32_e32 v54, 0
	v_mov_b32_e32 v55, 0
	v_mov_b32_e32 v56, 0
	v_mov_b32_e32 v57, 0
	v_mov_b32_e32 v58, 0
	v_mov_b32_e32 v59, 0
	v_mov_b32_e32 v60, 0
	v_mov_b32_e32 v61, 0
	v_mov_b32_e32 v62, 0
	v_mov_b32_e32 v63, 0
	v_mov_b32_e32 v64, 0
	v_mov_b32_e32 v65, 0
	v_mov_b32_e32 v66, 0
	v_mov_b32_e32 v67, 0
	v_mov_b32_e32 v68, 0
	v_mov_b32_e32 v69, 0
	v_mov_b32_e32 v236, 0
	v_mov_b32_e32 v237, 0
	v_mov_b32_e32 v238, 0
	v_mov_b32_e32 v239, 0
.Lp2_glud_0:
	s_sub_i32 s98, s24, 16
	s_lshl_b32 s98, s98, 11
	s_ashr_i32 s99, s98, 31
	s_add_u32 s100, s98, s20
	s_addc_u32 s101, s99, s21
	s_add_u32 s98, s98, s18
	s_addc_u32 s99, s99, s19
	global_load_dword v10, v251, s[98:99]
	global_load_dword v26, v251, s[100:101]
	global_load_dword v11, v251, s[98:99] offset:2048
	global_load_dword v27, v251, s[100:101] offset:2048
	s_add_u32 s98, s98, 0x1000
	s_addc_u32 s99, s99, 0
	s_add_u32 s100, s100, 0x1000
	s_addc_u32 s101, s101, 0
	global_load_dword v12, v251, s[98:99]
	global_load_dword v28, v251, s[100:101]
	global_load_dword v13, v251, s[98:99] offset:2048
	global_load_dword v29, v251, s[100:101] offset:2048
	s_add_u32 s98, s98, 0x1000
	s_addc_u32 s99, s99, 0
	s_add_u32 s100, s100, 0x1000
	s_addc_u32 s101, s101, 0
	global_load_dword v14, v251, s[98:99]
	global_load_dword v30, v251, s[100:101]
	global_load_dword v15, v251, s[98:99] offset:2048
	global_load_dword v31, v251, s[100:101] offset:2048
	s_add_u32 s98, s98, 0x1000
	s_addc_u32 s99, s99, 0
	s_add_u32 s100, s100, 0x1000
	s_addc_u32 s101, s101, 0
	global_load_dword v16, v251, s[98:99]
	global_load_dword v32, v251, s[100:101]
	global_load_dword v17, v251, s[98:99] offset:2048
	global_load_dword v33, v251, s[100:101] offset:2048
	s_add_u32 s98, s98, 0x1000
	s_addc_u32 s99, s99, 0
	s_add_u32 s100, s100, 0x1000
	s_addc_u32 s101, s101, 0
	global_load_dword v18, v251, s[98:99]
	global_load_dword v34, v251, s[100:101]
	global_load_dword v19, v251, s[98:99] offset:2048
	global_load_dword v35, v251, s[100:101] offset:2048
	s_add_u32 s98, s98, 0x1000
	s_addc_u32 s99, s99, 0
	s_add_u32 s100, s100, 0x1000
	s_addc_u32 s101, s101, 0
	global_load_dword v20, v251, s[98:99]
	global_load_dword v36, v251, s[100:101]
	global_load_dword v21, v251, s[98:99] offset:2048
	global_load_dword v37, v251, s[100:101] offset:2048
	s_add_u32 s98, s98, 0x1000
	s_addc_u32 s99, s99, 0
	s_add_u32 s100, s100, 0x1000
	s_addc_u32 s101, s101, 0
	global_load_dword v22, v251, s[98:99]
	global_load_dword v38, v251, s[100:101]
	global_load_dword v23, v251, s[98:99] offset:2048
	global_load_dword v39, v251, s[100:101] offset:2048
	s_add_u32 s98, s98, 0x1000
	s_addc_u32 s99, s99, 0
	s_add_u32 s100, s100, 0x1000
	s_addc_u32 s101, s101, 0
	global_load_dword v24, v251, s[98:99]
	global_load_dword v40, v251, s[100:101]
	global_load_dword v25, v251, s[98:99] offset:2048
	global_load_dword v41, v251, s[100:101] offset:2048
	s_cmp_lt_i32 s33, 0
	s_cbranch_scc1 .Lp2_nofma_0
	v_pk_fma_f32 v[204:205], v[144:145], v[70:71], v[132:133]
	v_pk_fma_f32 v[206:207], v[146:147], v[70:71], v[132:133]
	v_pk_fma_f32 v[208:209], v[148:149], v[70:71], v[132:133]
	v_pk_fma_f32 v[210:211], v[150:151], v[70:71], v[132:133]
	v_pk_fma_f32 v[204:205], v[146:147], v[72:73], v[204:205]
	v_pk_fma_f32 v[206:207], v[148:149], v[72:73], v[206:207]
	v_pk_fma_f32 v[208:209], v[150:151], v[72:73], v[208:209]
	v_pk_fma_f32 v[210:211], v[152:153], v[72:73], v[210:211]
	v_pk_fma_f32 v[204:205], v[148:149], v[74:75], v[204:205]
	v_pk_fma_f32 v[206:207], v[150:151], v[74:75], v[206:207]
	v_pk_fma_f32 v[208:209], v[152:153], v[74:75], v[208:209]
	v_pk_fma_f32 v[210:211], v[154:155], v[74:75], v[210:211]
	v_pk_fma_f32 v[204:205], v[150:151], v[76:77], v[204:205]
	v_pk_fma_f32 v[206:207], v[152:153], v[76:77], v[206:207]
	v_pk_fma_f32 v[208:209], v[154:155], v[76:77], v[208:209]
	v_pk_fma_f32 v[210:211], v[156:157], v[76:77], v[210:211]
	v_pk_fma_f32 v[204:205], v[152:153], v[78:79], v[204:205]
	v_pk_fma_f32 v[206:207], v[154:155], v[78:79], v[206:207]
	v_pk_fma_f32 v[208:209], v[156:157], v[78:79], v[208:209]
	v_pk_fma_f32 v[210:211], v[158:159], v[78:79], v[210:211]
	v_pk_fma_f32 v[204:205], v[154:155], v[80:81], v[204:205]
	v_pk_fma_f32 v[206:207], v[156:157], v[80:81], v[206:207]
	v_pk_fma_f32 v[208:209], v[158:159], v[80:81], v[208:209]
	v_pk_fma_f32 v[210:211], v[160:161], v[80:81], v[210:211]
	v_pk_fma_f32 v[204:205], v[156:157], v[82:83], v[204:205]
	v_pk_fma_f32 v[206:207], v[158:159], v[82:83], v[206:207]
	v_pk_fma_f32 v[208:209], v[160:161], v[82:83], v[208:209]
	v_pk_fma_f32 v[210:211], v[162:163], v[82:83], v[210:211]
	v_pk_fma_f32 v[204:205], v[158:159], v[84:85], v[204:205]
	v_pk_fma_f32 v[206:207], v[160:161], v[84:85], v[206:207]
	v_pk_fma_f32 v[208:209], v[162:163], v[84:85], v[208:209]
	v_pk_fma_f32 v[210:211], v[164:165], v[84:85], v[210:211]
	v_pk_fma_f32 v[204:205], v[160:161], v[86:87], v[204:205]
	v_pk_fma_f32 v[206:207], v[162:163], v[86:87], v[206:207]
	v_pk_fma_f32 v[208:209], v[164:165], v[86:87], v[208:209]
	v_pk_fma_f32 v[210:211], v[166:167], v[86:87], v[210:211]
	v_pk_fma_f32 v[204:205], v[162:163], v[92:93], v[204:205]
	v_pk_fma_f32 v[206:207], v[164:165], v[92:93], v[206:207]
	v_pk_fma_f32 v[208:209], v[166:167], v[92:93], v[208:209]
	v_pk_fma_f32 v[210:211], v[168:169], v[92:93], v[210:211]
	v_pk_fma_f32 v[204:205], v[164:165], v[94:95], v[204:205]
	v_pk_fma_f32 v[206:207], v[166:167], v[94:95], v[206:207]
	v_pk_fma_f32 v[208:209], v[168:169], v[94:95], v[208:209]
	v_pk_fma_f32 v[210:211], v[170:171], v[94:95], v[210:211]
	v_pk_fma_f32 v[204:205], v[166:167], v[96:97], v[204:205]
	v_pk_fma_f32 v[206:207], v[168:169], v[96:97], v[206:207]
	v_pk_fma_f32 v[208:209], v[170:171], v[96:97], v[208:209]
	v_pk_fma_f32 v[210:211], v[172:173], v[96:97], v[210:211]
	v_pk_fma_f32 v[204:205], v[168:169], v[98:99], v[204:205]
	v_pk_fma_f32 v[206:207], v[170:171], v[98:99], v[206:207]
	v_pk_fma_f32 v[208:209], v[172:173], v[98:99], v[208:209]
	v_pk_fma_f32 v[210:211], v[174:175], v[98:99], v[210:211]
	v_pk_fma_f32 v[204:205], v[170:171], v[100:101], v[204:205]
	v_pk_fma_f32 v[206:207], v[172:173], v[100:101], v[206:207]
	v_pk_fma_f32 v[208:209], v[174:175], v[100:101], v[208:209]
	v_pk_fma_f32 v[210:211], v[176:177], v[100:101], v[210:211]
	v_pk_fma_f32 v[204:205], v[172:173], v[102:103], v[204:205]
	v_pk_fma_f32 v[206:207], v[174:175], v[102:103], v[206:207]
	v_pk_fma_f32 v[208:209], v[176:177], v[102:103], v[208:209]
	v_pk_fma_f32 v[210:211], v[178:179], v[102:103], v[210:211]
	v_pk_fma_f32 v[204:205], v[174:175], v[104:105], v[204:205]
	v_pk_fma_f32 v[206:207], v[176:177], v[104:105], v[206:207]
	v_pk_fma_f32 v[208:209], v[178:179], v[104:105], v[208:209]
	v_pk_fma_f32 v[210:211], v[180:181], v[104:105], v[210:211]
	v_pk_fma_f32 v[204:205], v[176:177], v[106:107], v[204:205]
	v_pk_fma_f32 v[206:207], v[178:179], v[106:107], v[206:207]
	v_pk_fma_f32 v[208:209], v[180:181], v[106:107], v[208:209]
	v_pk_fma_f32 v[210:211], v[182:183], v[106:107], v[210:211]
	v_pk_fma_f32 v[204:205], v[178:179], v[108:109], v[204:205]
	v_pk_fma_f32 v[206:207], v[180:181], v[108:109], v[206:207]
	v_pk_fma_f32 v[208:209], v[182:183], v[108:109], v[208:209]
	v_pk_fma_f32 v[210:211], v[184:185], v[108:109], v[210:211]
	v_pk_fma_f32 v[204:205], v[180:181], v[110:111], v[204:205]
	v_pk_fma_f32 v[206:207], v[182:183], v[110:111], v[206:207]
	v_pk_fma_f32 v[208:209], v[184:185], v[110:111], v[208:209]
	v_pk_fma_f32 v[210:211], v[186:187], v[110:111], v[210:211]
	v_pk_fma_f32 v[204:205], v[182:183], v[112:113], v[204:205]
	v_pk_fma_f32 v[206:207], v[184:185], v[112:113], v[206:207]
	v_pk_fma_f32 v[208:209], v[186:187], v[112:113], v[208:209]
	v_pk_fma_f32 v[210:211], v[188:189], v[112:113], v[210:211]
	v_pk_fma_f32 v[204:205], v[184:185], v[114:115], v[204:205]
	v_pk_fma_f32 v[206:207], v[186:187], v[114:115], v[206:207]
	v_pk_fma_f32 v[208:209], v[188:189], v[114:115], v[208:209]
	v_pk_fma_f32 v[210:211], v[190:191], v[114:115], v[210:211]
	v_pk_fma_f32 v[204:205], v[186:187], v[116:117], v[204:205]
	v_pk_fma_f32 v[206:207], v[188:189], v[116:117], v[206:207]
	v_pk_fma_f32 v[208:209], v[190:191], v[116:117], v[208:209]
	v_pk_fma_f32 v[210:211], v[192:193], v[116:117], v[210:211]
	v_pk_fma_f32 v[204:205], v[188:189], v[118:119], v[204:205]
	v_pk_fma_f32 v[206:207], v[190:191], v[118:119], v[206:207]
	v_pk_fma_f32 v[208:209], v[192:193], v[118:119], v[208:209]
	v_pk_fma_f32 v[210:211], v[194:195], v[118:119], v[210:211]
	v_pk_fma_f32 v[204:205], v[190:191], v[120:121], v[204:205]
	v_pk_fma_f32 v[206:207], v[192:193], v[120:121], v[206:207]
	v_pk_fma_f32 v[208:209], v[194:195], v[120:121], v[208:209]
	v_pk_fma_f32 v[210:211], v[196:197], v[120:121], v[210:211]
	v_pk_fma_f32 v[204:205], v[192:193], v[122:123], v[204:205]
	v_pk_fma_f32 v[206:207], v[194:195], v[122:123], v[206:207]
	v_pk_fma_f32 v[208:209], v[196:197], v[122:123], v[208:209]
	v_pk_fma_f32 v[210:211], v[198:199], v[122:123], v[210:211]
	v_pk_fma_f32 v[204:205], v[194:195], v[124:125], v[204:205]
	v_pk_fma_f32 v[206:207], v[196:197], v[124:125], v[206:207]
	v_pk_fma_f32 v[208:209], v[198:199], v[124:125], v[208:209]
	v_pk_fma_f32 v[210:211], v[200:201], v[124:125], v[210:211]
	v_pk_fma_f32 v[204:205], v[196:197], v[126:127], v[204:205]
	v_pk_fma_f32 v[206:207], v[198:199], v[126:127], v[206:207]
	v_pk_fma_f32 v[208:209], v[200:201], v[126:127], v[208:209]
	v_pk_fma_f32 v[210:211], v[202:203], v[126:127], v[210:211]
	v_pk_fma_f32 v[204:205], v[198:199], v[128:129], v[204:205]
	v_pk_fma_f32 v[206:207], v[200:201], v[128:129], v[206:207]
	v_pk_fma_f32 v[208:209], v[202:203], v[128:129], v[208:209]
	v_pk_fma_f32 v[210:211], v[42:43], v[128:129], v[210:211]
	v_pk_fma_f32 v[204:205], v[200:201], v[130:131], v[204:205]
	v_pk_fma_f32 v[206:207], v[202:203], v[130:131], v[206:207]
	v_pk_fma_f32 v[208:209], v[42:43], v[130:131], v[208:209]
	v_pk_fma_f32 v[210:211], v[44:45], v[130:131], v[210:211]
	v_pk_fma_f32 v[204:205], v[202:203], v[88:89], v[204:205]
	v_pk_fma_f32 v[206:207], v[42:43], v[88:89], v[206:207]
	v_pk_fma_f32 v[208:209], v[44:45], v[88:89], v[208:209]
	v_pk_fma_f32 v[210:211], v[46:47], v[88:89], v[210:211]
	v_pk_fma_f32 v[204:205], v[42:43], v[90:91], v[204:205]
	v_pk_fma_f32 v[206:207], v[44:45], v[90:91], v[206:207]
	v_pk_fma_f32 v[208:209], v[46:47], v[90:91], v[208:209]
	v_pk_fma_f32 v[210:211], v[48:49], v[90:91], v[210:211]
	v_pk_fma_f32 v[212:213], v[152:153], v[70:71], v[132:133]
	v_pk_fma_f32 v[214:215], v[154:155], v[70:71], v[132:133]
	v_pk_fma_f32 v[216:217], v[156:157], v[70:71], v[132:133]
	v_pk_fma_f32 v[218:219], v[158:159], v[70:71], v[132:133]
	v_pk_fma_f32 v[212:213], v[154:155], v[72:73], v[212:213]
	v_pk_fma_f32 v[214:215], v[156:157], v[72:73], v[214:215]
	v_pk_fma_f32 v[216:217], v[158:159], v[72:73], v[216:217]
	v_pk_fma_f32 v[218:219], v[160:161], v[72:73], v[218:219]
	v_pk_fma_f32 v[212:213], v[156:157], v[74:75], v[212:213]
	v_pk_fma_f32 v[214:215], v[158:159], v[74:75], v[214:215]
	v_pk_fma_f32 v[216:217], v[160:161], v[74:75], v[216:217]
	v_pk_fma_f32 v[218:219], v[162:163], v[74:75], v[218:219]
	v_pk_fma_f32 v[212:213], v[158:159], v[76:77], v[212:213]
	v_pk_fma_f32 v[214:215], v[160:161], v[76:77], v[214:215]
	v_pk_fma_f32 v[216:217], v[162:163], v[76:77], v[216:217]
	v_pk_fma_f32 v[218:219], v[164:165], v[76:77], v[218:219]
	v_pk_fma_f32 v[212:213], v[160:161], v[78:79], v[212:213]
	v_pk_fma_f32 v[214:215], v[162:163], v[78:79], v[214:215]
	v_pk_fma_f32 v[216:217], v[164:165], v[78:79], v[216:217]
	v_pk_fma_f32 v[218:219], v[166:167], v[78:79], v[218:219]
	v_pk_fma_f32 v[212:213], v[162:163], v[80:81], v[212:213]
	v_pk_fma_f32 v[214:215], v[164:165], v[80:81], v[214:215]
	v_pk_fma_f32 v[216:217], v[166:167], v[80:81], v[216:217]
	v_pk_fma_f32 v[218:219], v[168:169], v[80:81], v[218:219]
	v_pk_fma_f32 v[212:213], v[164:165], v[82:83], v[212:213]
	v_pk_fma_f32 v[214:215], v[166:167], v[82:83], v[214:215]
	v_pk_fma_f32 v[216:217], v[168:169], v[82:83], v[216:217]
	v_pk_fma_f32 v[218:219], v[170:171], v[82:83], v[218:219]
	v_pk_fma_f32 v[212:213], v[166:167], v[84:85], v[212:213]
	v_pk_fma_f32 v[214:215], v[168:169], v[84:85], v[214:215]
	v_pk_fma_f32 v[216:217], v[170:171], v[84:85], v[216:217]
	v_pk_fma_f32 v[218:219], v[172:173], v[84:85], v[218:219]
	v_pk_fma_f32 v[212:213], v[168:169], v[86:87], v[212:213]
	v_pk_fma_f32 v[214:215], v[170:171], v[86:87], v[214:215]
	v_pk_fma_f32 v[216:217], v[172:173], v[86:87], v[216:217]
	v_pk_fma_f32 v[218:219], v[174:175], v[86:87], v[218:219]
	v_pk_fma_f32 v[212:213], v[170:171], v[92:93], v[212:213]
	v_pk_fma_f32 v[214:215], v[172:173], v[92:93], v[214:215]
	v_pk_fma_f32 v[216:217], v[174:175], v[92:93], v[216:217]
	v_pk_fma_f32 v[218:219], v[176:177], v[92:93], v[218:219]
	v_pk_fma_f32 v[212:213], v[172:173], v[94:95], v[212:213]
	v_pk_fma_f32 v[214:215], v[174:175], v[94:95], v[214:215]
	v_pk_fma_f32 v[216:217], v[176:177], v[94:95], v[216:217]
	v_pk_fma_f32 v[218:219], v[178:179], v[94:95], v[218:219]
	v_pk_fma_f32 v[212:213], v[174:175], v[96:97], v[212:213]
	v_pk_fma_f32 v[214:215], v[176:177], v[96:97], v[214:215]
	v_pk_fma_f32 v[216:217], v[178:179], v[96:97], v[216:217]
	v_pk_fma_f32 v[218:219], v[180:181], v[96:97], v[218:219]
	v_pk_fma_f32 v[212:213], v[176:177], v[98:99], v[212:213]
	v_pk_fma_f32 v[214:215], v[178:179], v[98:99], v[214:215]
	v_pk_fma_f32 v[216:217], v[180:181], v[98:99], v[216:217]
	v_pk_fma_f32 v[218:219], v[182:183], v[98:99], v[218:219]
	v_pk_fma_f32 v[212:213], v[178:179], v[100:101], v[212:213]
	v_pk_fma_f32 v[214:215], v[180:181], v[100:101], v[214:215]
	v_pk_fma_f32 v[216:217], v[182:183], v[100:101], v[216:217]
	v_pk_fma_f32 v[218:219], v[184:185], v[100:101], v[218:219]
	v_pk_fma_f32 v[212:213], v[180:181], v[102:103], v[212:213]
	v_pk_fma_f32 v[214:215], v[182:183], v[102:103], v[214:215]
	v_pk_fma_f32 v[216:217], v[184:185], v[102:103], v[216:217]
	v_pk_fma_f32 v[218:219], v[186:187], v[102:103], v[218:219]
	v_pk_fma_f32 v[212:213], v[182:183], v[104:105], v[212:213]
	v_pk_fma_f32 v[214:215], v[184:185], v[104:105], v[214:215]
	v_pk_fma_f32 v[216:217], v[186:187], v[104:105], v[216:217]
	v_pk_fma_f32 v[218:219], v[188:189], v[104:105], v[218:219]
	v_pk_fma_f32 v[212:213], v[184:185], v[106:107], v[212:213]
	v_pk_fma_f32 v[214:215], v[186:187], v[106:107], v[214:215]
	v_pk_fma_f32 v[216:217], v[188:189], v[106:107], v[216:217]
	v_pk_fma_f32 v[218:219], v[190:191], v[106:107], v[218:219]
	v_pk_fma_f32 v[212:213], v[186:187], v[108:109], v[212:213]
	v_pk_fma_f32 v[214:215], v[188:189], v[108:109], v[214:215]
	v_pk_fma_f32 v[216:217], v[190:191], v[108:109], v[216:217]
	v_pk_fma_f32 v[218:219], v[192:193], v[108:109], v[218:219]
	v_pk_fma_f32 v[212:213], v[188:189], v[110:111], v[212:213]
	v_pk_fma_f32 v[214:215], v[190:191], v[110:111], v[214:215]
	v_pk_fma_f32 v[216:217], v[192:193], v[110:111], v[216:217]
	v_pk_fma_f32 v[218:219], v[194:195], v[110:111], v[218:219]
	v_pk_fma_f32 v[212:213], v[190:191], v[112:113], v[212:213]
	v_pk_fma_f32 v[214:215], v[192:193], v[112:113], v[214:215]
	v_pk_fma_f32 v[216:217], v[194:195], v[112:113], v[216:217]
	v_pk_fma_f32 v[218:219], v[196:197], v[112:113], v[218:219]
	v_pk_fma_f32 v[212:213], v[192:193], v[114:115], v[212:213]
	v_pk_fma_f32 v[214:215], v[194:195], v[114:115], v[214:215]
	v_pk_fma_f32 v[216:217], v[196:197], v[114:115], v[216:217]
	v_pk_fma_f32 v[218:219], v[198:199], v[114:115], v[218:219]
	v_pk_fma_f32 v[212:213], v[194:195], v[116:117], v[212:213]
	v_pk_fma_f32 v[214:215], v[196:197], v[116:117], v[214:215]
	v_pk_fma_f32 v[216:217], v[198:199], v[116:117], v[216:217]
	v_pk_fma_f32 v[218:219], v[200:201], v[116:117], v[218:219]
	v_pk_fma_f32 v[212:213], v[196:197], v[118:119], v[212:213]
	v_pk_fma_f32 v[214:215], v[198:199], v[118:119], v[214:215]
	v_pk_fma_f32 v[216:217], v[200:201], v[118:119], v[216:217]
	v_pk_fma_f32 v[218:219], v[202:203], v[118:119], v[218:219]
	v_pk_fma_f32 v[212:213], v[198:199], v[120:121], v[212:213]
	v_pk_fma_f32 v[214:215], v[200:201], v[120:121], v[214:215]
	v_pk_fma_f32 v[216:217], v[202:203], v[120:121], v[216:217]
	v_pk_fma_f32 v[218:219], v[42:43], v[120:121], v[218:219]
	v_pk_fma_f32 v[212:213], v[200:201], v[122:123], v[212:213]
	v_pk_fma_f32 v[214:215], v[202:203], v[122:123], v[214:215]
	v_pk_fma_f32 v[216:217], v[42:43], v[122:123], v[216:217]
	v_pk_fma_f32 v[218:219], v[44:45], v[122:123], v[218:219]
	v_pk_fma_f32 v[212:213], v[202:203], v[124:125], v[212:213]
	v_pk_fma_f32 v[214:215], v[42:43], v[124:125], v[214:215]
	v_pk_fma_f32 v[216:217], v[44:45], v[124:125], v[216:217]
	v_pk_fma_f32 v[218:219], v[46:47], v[124:125], v[218:219]
	v_pk_fma_f32 v[212:213], v[42:43], v[126:127], v[212:213]
	v_pk_fma_f32 v[214:215], v[44:45], v[126:127], v[214:215]
	v_pk_fma_f32 v[216:217], v[46:47], v[126:127], v[216:217]
	v_pk_fma_f32 v[218:219], v[48:49], v[126:127], v[218:219]
	v_pk_fma_f32 v[212:213], v[44:45], v[128:129], v[212:213]
	v_pk_fma_f32 v[214:215], v[46:47], v[128:129], v[214:215]
	v_pk_fma_f32 v[216:217], v[48:49], v[128:129], v[216:217]
	v_pk_fma_f32 v[218:219], v[50:51], v[128:129], v[218:219]
	v_pk_fma_f32 v[212:213], v[46:47], v[130:131], v[212:213]
	v_pk_fma_f32 v[214:215], v[48:49], v[130:131], v[214:215]
	v_pk_fma_f32 v[216:217], v[50:51], v[130:131], v[216:217]
	v_pk_fma_f32 v[218:219], v[52:53], v[130:131], v[218:219]
	v_pk_fma_f32 v[212:213], v[48:49], v[88:89], v[212:213]
	v_pk_fma_f32 v[214:215], v[50:51], v[88:89], v[214:215]
	v_pk_fma_f32 v[216:217], v[52:53], v[88:89], v[216:217]
	v_pk_fma_f32 v[218:219], v[54:55], v[88:89], v[218:219]
	v_pk_fma_f32 v[212:213], v[50:51], v[90:91], v[212:213]
	v_pk_fma_f32 v[214:215], v[52:53], v[90:91], v[214:215]
	v_pk_fma_f32 v[216:217], v[54:55], v[90:91], v[216:217]
	v_pk_fma_f32 v[218:219], v[56:57], v[90:91], v[218:219]
	v_pk_fma_f32 v[220:221], v[160:161], v[70:71], v[132:133]
	v_pk_fma_f32 v[222:223], v[162:163], v[70:71], v[132:133]
	v_pk_fma_f32 v[224:225], v[164:165], v[70:71], v[132:133]
	v_pk_fma_f32 v[226:227], v[166:167], v[70:71], v[132:133]
	v_pk_fma_f32 v[220:221], v[162:163], v[72:73], v[220:221]
	v_pk_fma_f32 v[222:223], v[164:165], v[72:73], v[222:223]
	v_pk_fma_f32 v[224:225], v[166:167], v[72:73], v[224:225]
	v_pk_fma_f32 v[226:227], v[168:169], v[72:73], v[226:227]
	v_pk_fma_f32 v[220:221], v[164:165], v[74:75], v[220:221]
	v_pk_fma_f32 v[222:223], v[166:167], v[74:75], v[222:223]
	v_pk_fma_f32 v[224:225], v[168:169], v[74:75], v[224:225]
	v_pk_fma_f32 v[226:227], v[170:171], v[74:75], v[226:227]
	v_pk_fma_f32 v[220:221], v[166:167], v[76:77], v[220:221]
	v_pk_fma_f32 v[222:223], v[168:169], v[76:77], v[222:223]
	v_pk_fma_f32 v[224:225], v[170:171], v[76:77], v[224:225]
	v_pk_fma_f32 v[226:227], v[172:173], v[76:77], v[226:227]
	v_pk_fma_f32 v[220:221], v[168:169], v[78:79], v[220:221]
	v_pk_fma_f32 v[222:223], v[170:171], v[78:79], v[222:223]
	v_pk_fma_f32 v[224:225], v[172:173], v[78:79], v[224:225]
	v_pk_fma_f32 v[226:227], v[174:175], v[78:79], v[226:227]
	v_pk_fma_f32 v[220:221], v[170:171], v[80:81], v[220:221]
	v_pk_fma_f32 v[222:223], v[172:173], v[80:81], v[222:223]
	v_pk_fma_f32 v[224:225], v[174:175], v[80:81], v[224:225]
	v_pk_fma_f32 v[226:227], v[176:177], v[80:81], v[226:227]
	v_pk_fma_f32 v[220:221], v[172:173], v[82:83], v[220:221]
	v_pk_fma_f32 v[222:223], v[174:175], v[82:83], v[222:223]
	v_pk_fma_f32 v[224:225], v[176:177], v[82:83], v[224:225]
	v_pk_fma_f32 v[226:227], v[178:179], v[82:83], v[226:227]
	v_pk_fma_f32 v[220:221], v[174:175], v[84:85], v[220:221]
	v_pk_fma_f32 v[222:223], v[176:177], v[84:85], v[222:223]
	v_pk_fma_f32 v[224:225], v[178:179], v[84:85], v[224:225]
	v_pk_fma_f32 v[226:227], v[180:181], v[84:85], v[226:227]
	v_pk_fma_f32 v[220:221], v[176:177], v[86:87], v[220:221]
	v_pk_fma_f32 v[222:223], v[178:179], v[86:87], v[222:223]
	v_pk_fma_f32 v[224:225], v[180:181], v[86:87], v[224:225]
	v_pk_fma_f32 v[226:227], v[182:183], v[86:87], v[226:227]
	v_pk_fma_f32 v[220:221], v[178:179], v[92:93], v[220:221]
	v_pk_fma_f32 v[222:223], v[180:181], v[92:93], v[222:223]
	v_pk_fma_f32 v[224:225], v[182:183], v[92:93], v[224:225]
	v_pk_fma_f32 v[226:227], v[184:185], v[92:93], v[226:227]
	v_pk_fma_f32 v[220:221], v[180:181], v[94:95], v[220:221]
	v_pk_fma_f32 v[222:223], v[182:183], v[94:95], v[222:223]
	v_pk_fma_f32 v[224:225], v[184:185], v[94:95], v[224:225]
	v_pk_fma_f32 v[226:227], v[186:187], v[94:95], v[226:227]
	v_pk_fma_f32 v[220:221], v[182:183], v[96:97], v[220:221]
	v_pk_fma_f32 v[222:223], v[184:185], v[96:97], v[222:223]
	v_pk_fma_f32 v[224:225], v[186:187], v[96:97], v[224:225]
	v_pk_fma_f32 v[226:227], v[188:189], v[96:97], v[226:227]
	v_pk_fma_f32 v[220:221], v[184:185], v[98:99], v[220:221]
	v_pk_fma_f32 v[222:223], v[186:187], v[98:99], v[222:223]
	v_pk_fma_f32 v[224:225], v[188:189], v[98:99], v[224:225]
	v_pk_fma_f32 v[226:227], v[190:191], v[98:99], v[226:227]
	v_pk_fma_f32 v[220:221], v[186:187], v[100:101], v[220:221]
	v_pk_fma_f32 v[222:223], v[188:189], v[100:101], v[222:223]
	v_pk_fma_f32 v[224:225], v[190:191], v[100:101], v[224:225]
	v_pk_fma_f32 v[226:227], v[192:193], v[100:101], v[226:227]
	v_pk_fma_f32 v[220:221], v[188:189], v[102:103], v[220:221]
	v_pk_fma_f32 v[222:223], v[190:191], v[102:103], v[222:223]
	v_pk_fma_f32 v[224:225], v[192:193], v[102:103], v[224:225]
	v_pk_fma_f32 v[226:227], v[194:195], v[102:103], v[226:227]
	v_pk_fma_f32 v[220:221], v[190:191], v[104:105], v[220:221]
	v_pk_fma_f32 v[222:223], v[192:193], v[104:105], v[222:223]
	v_pk_fma_f32 v[224:225], v[194:195], v[104:105], v[224:225]
	v_pk_fma_f32 v[226:227], v[196:197], v[104:105], v[226:227]
	v_pk_fma_f32 v[220:221], v[192:193], v[106:107], v[220:221]
	v_pk_fma_f32 v[222:223], v[194:195], v[106:107], v[222:223]
	v_pk_fma_f32 v[224:225], v[196:197], v[106:107], v[224:225]
	v_pk_fma_f32 v[226:227], v[198:199], v[106:107], v[226:227]
	v_pk_fma_f32 v[220:221], v[194:195], v[108:109], v[220:221]
	v_pk_fma_f32 v[222:223], v[196:197], v[108:109], v[222:223]
	v_pk_fma_f32 v[224:225], v[198:199], v[108:109], v[224:225]
	v_pk_fma_f32 v[226:227], v[200:201], v[108:109], v[226:227]
	v_pk_fma_f32 v[220:221], v[196:197], v[110:111], v[220:221]
	v_pk_fma_f32 v[222:223], v[198:199], v[110:111], v[222:223]
	v_pk_fma_f32 v[224:225], v[200:201], v[110:111], v[224:225]
	v_pk_fma_f32 v[226:227], v[202:203], v[110:111], v[226:227]
	v_pk_fma_f32 v[220:221], v[198:199], v[112:113], v[220:221]
	v_pk_fma_f32 v[222:223], v[200:201], v[112:113], v[222:223]
	v_pk_fma_f32 v[224:225], v[202:203], v[112:113], v[224:225]
	v_pk_fma_f32 v[226:227], v[42:43], v[112:113], v[226:227]
	v_pk_fma_f32 v[220:221], v[200:201], v[114:115], v[220:221]
	v_pk_fma_f32 v[222:223], v[202:203], v[114:115], v[222:223]
	v_pk_fma_f32 v[224:225], v[42:43], v[114:115], v[224:225]
	v_pk_fma_f32 v[226:227], v[44:45], v[114:115], v[226:227]
	v_pk_fma_f32 v[220:221], v[202:203], v[116:117], v[220:221]
	v_pk_fma_f32 v[222:223], v[42:43], v[116:117], v[222:223]
	v_pk_fma_f32 v[224:225], v[44:45], v[116:117], v[224:225]
	v_pk_fma_f32 v[226:227], v[46:47], v[116:117], v[226:227]
	v_pk_fma_f32 v[220:221], v[42:43], v[118:119], v[220:221]
	v_pk_fma_f32 v[222:223], v[44:45], v[118:119], v[222:223]
	v_pk_fma_f32 v[224:225], v[46:47], v[118:119], v[224:225]
	v_pk_fma_f32 v[226:227], v[48:49], v[118:119], v[226:227]
	v_pk_fma_f32 v[220:221], v[44:45], v[120:121], v[220:221]
	v_pk_fma_f32 v[222:223], v[46:47], v[120:121], v[222:223]
	v_pk_fma_f32 v[224:225], v[48:49], v[120:121], v[224:225]
	v_pk_fma_f32 v[226:227], v[50:51], v[120:121], v[226:227]
	v_pk_fma_f32 v[220:221], v[46:47], v[122:123], v[220:221]
	v_pk_fma_f32 v[222:223], v[48:49], v[122:123], v[222:223]
	v_pk_fma_f32 v[224:225], v[50:51], v[122:123], v[224:225]
	v_pk_fma_f32 v[226:227], v[52:53], v[122:123], v[226:227]
	v_pk_fma_f32 v[220:221], v[48:49], v[124:125], v[220:221]
	v_pk_fma_f32 v[222:223], v[50:51], v[124:125], v[222:223]
	v_pk_fma_f32 v[224:225], v[52:53], v[124:125], v[224:225]
	v_pk_fma_f32 v[226:227], v[54:55], v[124:125], v[226:227]
	v_pk_fma_f32 v[220:221], v[50:51], v[126:127], v[220:221]
	v_pk_fma_f32 v[222:223], v[52:53], v[126:127], v[222:223]
	v_pk_fma_f32 v[224:225], v[54:55], v[126:127], v[224:225]
	v_pk_fma_f32 v[226:227], v[56:57], v[126:127], v[226:227]
	v_pk_fma_f32 v[220:221], v[52:53], v[128:129], v[220:221]
	v_pk_fma_f32 v[222:223], v[54:55], v[128:129], v[222:223]
	v_pk_fma_f32 v[224:225], v[56:57], v[128:129], v[224:225]
	v_pk_fma_f32 v[226:227], v[58:59], v[128:129], v[226:227]
	v_pk_fma_f32 v[220:221], v[54:55], v[130:131], v[220:221]
	v_pk_fma_f32 v[222:223], v[56:57], v[130:131], v[222:223]
	v_pk_fma_f32 v[224:225], v[58:59], v[130:131], v[224:225]
	v_pk_fma_f32 v[226:227], v[60:61], v[130:131], v[226:227]
	v_pk_fma_f32 v[220:221], v[56:57], v[88:89], v[220:221]
	v_pk_fma_f32 v[222:223], v[58:59], v[88:89], v[222:223]
	v_pk_fma_f32 v[224:225], v[60:61], v[88:89], v[224:225]
	v_pk_fma_f32 v[226:227], v[62:63], v[88:89], v[226:227]
	v_pk_fma_f32 v[220:221], v[58:59], v[90:91], v[220:221]
	v_pk_fma_f32 v[222:223], v[60:61], v[90:91], v[222:223]
	v_pk_fma_f32 v[224:225], v[62:63], v[90:91], v[224:225]
	v_pk_fma_f32 v[226:227], v[64:65], v[90:91], v[226:227]
	v_pk_fma_f32 v[228:229], v[168:169], v[70:71], v[132:133]
	v_pk_fma_f32 v[230:231], v[170:171], v[70:71], v[132:133]
	v_pk_fma_f32 v[232:233], v[172:173], v[70:71], v[132:133]
	v_pk_fma_f32 v[234:235], v[174:175], v[70:71], v[132:133]
	v_pk_fma_f32 v[228:229], v[170:171], v[72:73], v[228:229]
	v_pk_fma_f32 v[230:231], v[172:173], v[72:73], v[230:231]
	v_pk_fma_f32 v[232:233], v[174:175], v[72:73], v[232:233]
	v_pk_fma_f32 v[234:235], v[176:177], v[72:73], v[234:235]
	v_pk_fma_f32 v[228:229], v[172:173], v[74:75], v[228:229]
	v_pk_fma_f32 v[230:231], v[174:175], v[74:75], v[230:231]
	v_pk_fma_f32 v[232:233], v[176:177], v[74:75], v[232:233]
	v_pk_fma_f32 v[234:235], v[178:179], v[74:75], v[234:235]
	v_pk_fma_f32 v[228:229], v[174:175], v[76:77], v[228:229]
	v_pk_fma_f32 v[230:231], v[176:177], v[76:77], v[230:231]
	v_pk_fma_f32 v[232:233], v[178:179], v[76:77], v[232:233]
	v_pk_fma_f32 v[234:235], v[180:181], v[76:77], v[234:235]
	v_pk_fma_f32 v[228:229], v[176:177], v[78:79], v[228:229]
	v_pk_fma_f32 v[230:231], v[178:179], v[78:79], v[230:231]
	v_pk_fma_f32 v[232:233], v[180:181], v[78:79], v[232:233]
	v_pk_fma_f32 v[234:235], v[182:183], v[78:79], v[234:235]
	v_pk_fma_f32 v[228:229], v[178:179], v[80:81], v[228:229]
	v_pk_fma_f32 v[230:231], v[180:181], v[80:81], v[230:231]
	v_pk_fma_f32 v[232:233], v[182:183], v[80:81], v[232:233]
	v_pk_fma_f32 v[234:235], v[184:185], v[80:81], v[234:235]
	v_pk_fma_f32 v[228:229], v[180:181], v[82:83], v[228:229]
	v_pk_fma_f32 v[230:231], v[182:183], v[82:83], v[230:231]
	v_pk_fma_f32 v[232:233], v[184:185], v[82:83], v[232:233]
	v_pk_fma_f32 v[234:235], v[186:187], v[82:83], v[234:235]
	v_pk_fma_f32 v[228:229], v[182:183], v[84:85], v[228:229]
	v_pk_fma_f32 v[230:231], v[184:185], v[84:85], v[230:231]
	v_pk_fma_f32 v[232:233], v[186:187], v[84:85], v[232:233]
	v_pk_fma_f32 v[234:235], v[188:189], v[84:85], v[234:235]
	v_pk_fma_f32 v[228:229], v[184:185], v[86:87], v[228:229]
	v_pk_fma_f32 v[230:231], v[186:187], v[86:87], v[230:231]
	v_pk_fma_f32 v[232:233], v[188:189], v[86:87], v[232:233]
	v_pk_fma_f32 v[234:235], v[190:191], v[86:87], v[234:235]
	v_pk_fma_f32 v[228:229], v[186:187], v[92:93], v[228:229]
	v_pk_fma_f32 v[230:231], v[188:189], v[92:93], v[230:231]
	v_pk_fma_f32 v[232:233], v[190:191], v[92:93], v[232:233]
	v_pk_fma_f32 v[234:235], v[192:193], v[92:93], v[234:235]
	v_pk_fma_f32 v[228:229], v[188:189], v[94:95], v[228:229]
	v_pk_fma_f32 v[230:231], v[190:191], v[94:95], v[230:231]
	v_pk_fma_f32 v[232:233], v[192:193], v[94:95], v[232:233]
	v_pk_fma_f32 v[234:235], v[194:195], v[94:95], v[234:235]
	v_pk_fma_f32 v[228:229], v[190:191], v[96:97], v[228:229]
	v_pk_fma_f32 v[230:231], v[192:193], v[96:97], v[230:231]
	v_pk_fma_f32 v[232:233], v[194:195], v[96:97], v[232:233]
	v_pk_fma_f32 v[234:235], v[196:197], v[96:97], v[234:235]
	v_pk_fma_f32 v[228:229], v[192:193], v[98:99], v[228:229]
	v_pk_fma_f32 v[230:231], v[194:195], v[98:99], v[230:231]
	v_pk_fma_f32 v[232:233], v[196:197], v[98:99], v[232:233]
	v_pk_fma_f32 v[234:235], v[198:199], v[98:99], v[234:235]
	v_pk_fma_f32 v[228:229], v[194:195], v[100:101], v[228:229]
	v_pk_fma_f32 v[230:231], v[196:197], v[100:101], v[230:231]
	v_pk_fma_f32 v[232:233], v[198:199], v[100:101], v[232:233]
	v_pk_fma_f32 v[234:235], v[200:201], v[100:101], v[234:235]
	v_pk_fma_f32 v[228:229], v[196:197], v[102:103], v[228:229]
	v_pk_fma_f32 v[230:231], v[198:199], v[102:103], v[230:231]
	v_pk_fma_f32 v[232:233], v[200:201], v[102:103], v[232:233]
	v_pk_fma_f32 v[234:235], v[202:203], v[102:103], v[234:235]
	v_pk_fma_f32 v[228:229], v[198:199], v[104:105], v[228:229]
	v_pk_fma_f32 v[230:231], v[200:201], v[104:105], v[230:231]
	v_pk_fma_f32 v[232:233], v[202:203], v[104:105], v[232:233]
	v_pk_fma_f32 v[234:235], v[42:43], v[104:105], v[234:235]
	v_pk_fma_f32 v[228:229], v[200:201], v[106:107], v[228:229]
	v_pk_fma_f32 v[230:231], v[202:203], v[106:107], v[230:231]
	v_pk_fma_f32 v[232:233], v[42:43], v[106:107], v[232:233]
	v_pk_fma_f32 v[234:235], v[44:45], v[106:107], v[234:235]
	v_pk_fma_f32 v[228:229], v[202:203], v[108:109], v[228:229]
	v_pk_fma_f32 v[230:231], v[42:43], v[108:109], v[230:231]
	v_pk_fma_f32 v[232:233], v[44:45], v[108:109], v[232:233]
	v_pk_fma_f32 v[234:235], v[46:47], v[108:109], v[234:235]
	v_pk_fma_f32 v[228:229], v[42:43], v[110:111], v[228:229]
	v_pk_fma_f32 v[230:231], v[44:45], v[110:111], v[230:231]
	v_pk_fma_f32 v[232:233], v[46:47], v[110:111], v[232:233]
	v_pk_fma_f32 v[234:235], v[48:49], v[110:111], v[234:235]
	v_pk_fma_f32 v[228:229], v[44:45], v[112:113], v[228:229]
	v_pk_fma_f32 v[230:231], v[46:47], v[112:113], v[230:231]
	v_pk_fma_f32 v[232:233], v[48:49], v[112:113], v[232:233]
	v_pk_fma_f32 v[234:235], v[50:51], v[112:113], v[234:235]
	v_pk_fma_f32 v[228:229], v[46:47], v[114:115], v[228:229]
	v_pk_fma_f32 v[230:231], v[48:49], v[114:115], v[230:231]
	v_pk_fma_f32 v[232:233], v[50:51], v[114:115], v[232:233]
	v_pk_fma_f32 v[234:235], v[52:53], v[114:115], v[234:235]
	v_pk_fma_f32 v[228:229], v[48:49], v[116:117], v[228:229]
	v_pk_fma_f32 v[230:231], v[50:51], v[116:117], v[230:231]
	v_pk_fma_f32 v[232:233], v[52:53], v[116:117], v[232:233]
	v_pk_fma_f32 v[234:235], v[54:55], v[116:117], v[234:235]
	v_pk_fma_f32 v[228:229], v[50:51], v[118:119], v[228:229]
	v_pk_fma_f32 v[230:231], v[52:53], v[118:119], v[230:231]
	v_pk_fma_f32 v[232:233], v[54:55], v[118:119], v[232:233]
	v_pk_fma_f32 v[234:235], v[56:57], v[118:119], v[234:235]
	v_pk_fma_f32 v[228:229], v[52:53], v[120:121], v[228:229]
	v_pk_fma_f32 v[230:231], v[54:55], v[120:121], v[230:231]
	v_pk_fma_f32 v[232:233], v[56:57], v[120:121], v[232:233]
	v_pk_fma_f32 v[234:235], v[58:59], v[120:121], v[234:235]
	v_pk_fma_f32 v[228:229], v[54:55], v[122:123], v[228:229]
	v_pk_fma_f32 v[230:231], v[56:57], v[122:123], v[230:231]
	v_pk_fma_f32 v[232:233], v[58:59], v[122:123], v[232:233]
	v_pk_fma_f32 v[234:235], v[60:61], v[122:123], v[234:235]
	v_pk_fma_f32 v[228:229], v[56:57], v[124:125], v[228:229]
	v_pk_fma_f32 v[230:231], v[58:59], v[124:125], v[230:231]
	v_pk_fma_f32 v[232:233], v[60:61], v[124:125], v[232:233]
	v_pk_fma_f32 v[234:235], v[62:63], v[124:125], v[234:235]
	v_pk_fma_f32 v[228:229], v[58:59], v[126:127], v[228:229]
	v_pk_fma_f32 v[230:231], v[60:61], v[126:127], v[230:231]
	v_pk_fma_f32 v[232:233], v[62:63], v[126:127], v[232:233]
	v_pk_fma_f32 v[234:235], v[64:65], v[126:127], v[234:235]
	v_pk_fma_f32 v[228:229], v[60:61], v[128:129], v[228:229]
	v_pk_fma_f32 v[230:231], v[62:63], v[128:129], v[230:231]
	v_pk_fma_f32 v[232:233], v[64:65], v[128:129], v[232:233]
	v_pk_fma_f32 v[234:235], v[66:67], v[128:129], v[234:235]
	v_pk_fma_f32 v[228:229], v[62:63], v[130:131], v[228:229]
	v_pk_fma_f32 v[230:231], v[64:65], v[130:131], v[230:231]
	v_pk_fma_f32 v[232:233], v[66:67], v[130:131], v[232:233]
	v_pk_fma_f32 v[234:235], v[68:69], v[130:131], v[234:235]
	v_pk_fma_f32 v[228:229], v[64:65], v[88:89], v[228:229]
	v_pk_fma_f32 v[230:231], v[66:67], v[88:89], v[230:231]
	v_pk_fma_f32 v[232:233], v[68:69], v[88:89], v[232:233]
	v_pk_fma_f32 v[234:235], v[236:237], v[88:89], v[234:235]
	v_pk_fma_f32 v[228:229], v[66:67], v[90:91], v[228:229]
	v_pk_fma_f32 v[230:231], v[68:69], v[90:91], v[230:231]
	v_pk_fma_f32 v[232:233], v[236:237], v[90:91], v[232:233]
	v_pk_fma_f32 v[234:235], v[238:239], v[90:91], v[234:235]
.Lp2_nofma_0:
	v_mov_b64_e32 v[140:141], v[42:43]
	v_mov_b64_e32 v[142:143], v[44:45]
	v_mov_b64_e32 v[144:145], v[46:47]
	v_mov_b64_e32 v[146:147], v[48:49]
	v_mov_b64_e32 v[148:149], v[50:51]
	v_mov_b64_e32 v[150:151], v[52:53]
	v_mov_b64_e32 v[152:153], v[54:55]
	v_mov_b64_e32 v[154:155], v[56:57]
	v_mov_b64_e32 v[156:157], v[58:59]
	v_mov_b64_e32 v[158:159], v[60:61]
	v_mov_b64_e32 v[160:161], v[62:63]
	v_mov_b64_e32 v[162:163], v[64:65]
	v_mov_b64_e32 v[164:165], v[66:67]
	v_mov_b64_e32 v[166:167], v[68:69]
	v_mov_b64_e32 v[168:169], v[236:237]
	v_mov_b64_e32 v[170:171], v[238:239]
	s_cmp_lt_i32 s33, 0
	s_cbranch_scc1 .Lp2_skip_0
	v_add_f32_e32 v42, v204, v205
	v_mul_f32_e32 v43, v204, v204
	v_add_f32_e32 v44, v206, v207
	v_mul_f32_e32 v45, v206, v206
	v_add_f32_e32 v46, v208, v209
	v_mul_f32_e32 v47, v208, v208
	v_add_f32_e32 v48, v210, v211
	v_mul_f32_e32 v49, v210, v210
	v_add_f32_e32 v50, v212, v213
	v_mul_f32_e32 v51, v212, v212
	v_add_f32_e32 v52, v214, v215
	v_mul_f32_e32 v53, v214, v214
	v_add_f32_e32 v54, v216, v217
	v_mul_f32_e32 v55, v216, v216
	v_add_f32_e32 v56, v218, v219
	v_mul_f32_e32 v57, v218, v218
	v_add_f32_e32 v58, v220, v221
	v_mul_f32_e32 v59, v220, v220
	v_add_f32_e32 v60, v222, v223
	v_mul_f32_e32 v61, v222, v222
	v_add_f32_e32 v62, v224, v225
	v_mul_f32_e32 v63, v224, v224
	v_add_f32_e32 v64, v226, v227
	v_mul_f32_e32 v65, v226, v226
	v_add_f32_e32 v66, v228, v229
	v_mul_f32_e32 v67, v228, v228
	v_add_f32_e32 v68, v230, v231
	v_mul_f32_e32 v69, v230, v230
	v_add_f32_e32 v236, v232, v233
	v_mul_f32_e32 v237, v232, v232
	v_add_f32_e32 v238, v234, v235
	v_mul_f32_e32 v239, v234, v234
	v_fmac_f32_e32 v43, v205, v205
	v_fmac_f32_e32 v45, v207, v207
	v_fmac_f32_e32 v47, v209, v209
	v_fmac_f32_e32 v49, v211, v211
	v_fmac_f32_e32 v51, v213, v213
	v_fmac_f32_e32 v53, v215, v215
	v_fmac_f32_e32 v55, v217, v217
	v_fmac_f32_e32 v57, v219, v219
	v_fmac_f32_e32 v59, v221, v221
	v_fmac_f32_e32 v61, v223, v223
	v_fmac_f32_e32 v63, v225, v225
	v_fmac_f32_e32 v65, v227, v227
	v_fmac_f32_e32 v67, v229, v229
	v_fmac_f32_e32 v69, v231, v231
	v_fmac_f32_e32 v237, v233, v233
	v_fmac_f32_e32 v239, v235, v235
	v_permlane32_swap_b32_e32 v42, v58
	v_permlane32_swap_b32_e32 v43, v59
	v_permlane32_swap_b32_e32 v44, v60
	v_permlane32_swap_b32_e32 v45, v61
	v_permlane32_swap_b32_e32 v46, v62
	v_permlane32_swap_b32_e32 v47, v63
	v_permlane32_swap_b32_e32 v48, v64
	v_permlane32_swap_b32_e32 v49, v65
	v_permlane32_swap_b32_e32 v50, v66
	v_permlane32_swap_b32_e32 v51, v67
	v_permlane32_swap_b32_e32 v52, v68
	v_permlane32_swap_b32_e32 v53, v69
	v_permlane32_swap_b32_e32 v54, v236
	v_permlane32_swap_b32_e32 v55, v237
	v_permlane32_swap_b32_e32 v56, v238
	v_permlane32_swap_b32_e32 v57, v239
	v_add_f32_e32 v42, v42, v58
	v_add_f32_e32 v43, v43, v59
	v_add_f32_e32 v44, v44, v60
	v_add_f32_e32 v45, v45, v61
	v_add_f32_e32 v46, v46, v62
	v_add_f32_e32 v47, v47, v63
	v_add_f32_e32 v48, v48, v64
	v_add_f32_e32 v49, v49, v65
	v_add_f32_e32 v50, v50, v66
	v_add_f32_e32 v51, v51, v67
	v_add_f32_e32 v52, v52, v68
	v_add_f32_e32 v53, v53, v69
	v_add_f32_e32 v54, v54, v236
	v_add_f32_e32 v55, v55, v237
	v_add_f32_e32 v56, v56, v238
	v_add_f32_e32 v57, v57, v239
	v_permlane16_swap_b32_e32 v42, v50
	v_permlane16_swap_b32_e32 v43, v51
	v_permlane16_swap_b32_e32 v44, v52
	v_permlane16_swap_b32_e32 v45, v53
	v_permlane16_swap_b32_e32 v46, v54
	v_permlane16_swap_b32_e32 v47, v55
	v_permlane16_swap_b32_e32 v48, v56
	v_permlane16_swap_b32_e32 v49, v57
	v_add_f32_e32 v42, v42, v50
	v_add_f32_e32 v43, v43, v51
	v_add_f32_e32 v44, v44, v52
	v_add_f32_e32 v45, v45, v53
	v_add_f32_e32 v46, v46, v54
	v_add_f32_e32 v47, v47, v55
	v_add_f32_e32 v48, v48, v56
	v_add_f32_e32 v49, v49, v57
	v_add_f32_dpp v42, v42, v42 row_ror:8 row_mask:0xf bank_mask:0xf
	v_add_f32_dpp v43, v43, v43 row_ror:8 row_mask:0xf bank_mask:0xf
	v_add_f32_dpp v44, v44, v44 row_ror:8 row_mask:0xf bank_mask:0xf
	v_add_f32_dpp v45, v45, v45 row_ror:8 row_mask:0xf bank_mask:0xf
	v_add_f32_dpp v46, v46, v46 row_ror:8 row_mask:0xf bank_mask:0xf
	v_add_f32_dpp v47, v47, v47 row_ror:8 row_mask:0xf bank_mask:0xf
	v_add_f32_dpp v48, v48, v48 row_ror:8 row_mask:0xf bank_mask:0xf
	v_add_f32_dpp v49, v49, v49 row_ror:8 row_mask:0xf bank_mask:0xf
	v_add_f32_dpp v42, v42, v42 row_ror:4 row_mask:0xf bank_mask:0xf
	v_add_f32_dpp v43, v43, v43 row_ror:4 row_mask:0xf bank_mask:0xf
	v_add_f32_dpp v44, v44, v44 row_ror:4 row_mask:0xf bank_mask:0xf
	v_add_f32_dpp v45, v45, v45 row_ror:4 row_mask:0xf bank_mask:0xf
	v_add_f32_dpp v46, v46, v46 row_ror:4 row_mask:0xf bank_mask:0xf
	v_add_f32_dpp v47, v47, v47 row_ror:4 row_mask:0xf bank_mask:0xf
	v_add_f32_dpp v48, v48, v48 row_ror:4 row_mask:0xf bank_mask:0xf
	v_add_f32_dpp v49, v49, v49 row_ror:4 row_mask:0xf bank_mask:0xf
	v_add_f32_dpp v42, v42, v42 row_ror:2 row_mask:0xf bank_mask:0xf
	v_add_f32_dpp v43, v43, v43 row_ror:2 row_mask:0xf bank_mask:0xf
	v_add_f32_dpp v44, v44, v44 row_ror:2 row_mask:0xf bank_mask:0xf
	v_add_f32_dpp v45, v45, v45 row_ror:2 row_mask:0xf bank_mask:0xf
	v_add_f32_dpp v46, v46, v46 row_ror:2 row_mask:0xf bank_mask:0xf
	v_add_f32_dpp v47, v47, v47 row_ror:2 row_mask:0xf bank_mask:0xf
	v_add_f32_dpp v48, v48, v48 row_ror:2 row_mask:0xf bank_mask:0xf
	v_add_f32_dpp v49, v49, v49 row_ror:2 row_mask:0xf bank_mask:0xf
	v_add_f32_dpp v42, v42, v42 row_ror:1 row_mask:0xf bank_mask:0xf
	v_add_f32_dpp v43, v43, v43 row_ror:1 row_mask:0xf bank_mask:0xf
	v_add_f32_dpp v44, v44, v44 row_ror:1 row_mask:0xf bank_mask:0xf
	v_add_f32_dpp v45, v45, v45 row_ror:1 row_mask:0xf bank_mask:0xf
	v_add_f32_dpp v46, v46, v46 row_ror:1 row_mask:0xf bank_mask:0xf
	v_add_f32_dpp v47, v47, v47 row_ror:1 row_mask:0xf bank_mask:0xf
	v_add_f32_dpp v48, v48, v48 row_ror:1 row_mask:0xf bank_mask:0xf
	v_add_f32_dpp v49, v49, v49 row_ror:1 row_mask:0xf bank_mask:0xf
	s_mov_b32 exec_lo, 0x10001
	s_mov_b32 exec_hi, 0x10001
	ds_write_b64 v252, v[42:43] offset:0
	ds_write_b64 v252, v[44:45] offset:64
	ds_write_b64 v252, v[46:47] offset:128
	ds_write_b64 v252, v[48:49] offset:192
	s_mov_b64 exec, -1
	s_waitcnt lgkmcnt(0)
	s_barrier
	ds_read_b128 v[50:53], v253 offset:0
	ds_read_b128 v[54:57], v253 offset:16
	ds_read_b128 v[58:61], v253 offset:32
	ds_read_b128 v[62:65], v253 offset:48
	s_mov_b32 s66, 0x3a800000
	s_waitcnt lgkmcnt(0)
	v_add_f32_e32 v242, v50, v52
	v_add_f32_e32 v243, v51, v53
	v_add_f32_e32 v240, 0, v242
	v_add_f32_e32 v241, 0, v243
	v_add_f32_e32 v242, v54, v56
	v_add_f32_e32 v243, v55, v57
	v_add_f32_e32 v240, v240, v242
	v_add_f32_e32 v241, v241, v243
	v_add_f32_e32 v242, v58, v60
	v_add_f32_e32 v243, v59, v61
	v_add_f32_e32 v240, v240, v242
	v_add_f32_e32 v241, v241, v243
	v_add_f32_e32 v242, v62, v64
	v_add_f32_e32 v243, v63, v65
	v_add_f32_e32 v240, v240, v242
	v_add_f32_e32 v241, v241, v243
	v_mul_f32_e32 v244, 0x3a800000, v240
	v_mul_f32_e32 v245, v244, v244
	v_fma_f32 v246, v241, s66, -v245
	v_max_f32_e32 v246, 0, v246
	v_add_f32_e32 v246, 0x358637bd, v246
	v_rsq_f32_e32 v247, v246
	s_nop 0
	v_readlane_b32 s34, v244, 0
	v_readlane_b32 s35, v244, 1
	v_readlane_b32 s36, v244, 2
	v_readlane_b32 s37, v244, 3
	v_readlane_b32 s38, v244, 4
	v_readlane_b32 s39, v244, 5
	v_readlane_b32 s40, v244, 6
	v_readlane_b32 s41, v244, 7
	v_readlane_b32 s42, v244, 8
	v_readlane_b32 s43, v244, 9
	v_readlane_b32 s44, v244, 10
	v_readlane_b32 s45, v244, 11
	v_readlane_b32 s46, v244, 12
	v_readlane_b32 s47, v244, 13
	v_readlane_b32 s48, v244, 14
	v_readlane_b32 s49, v244, 15
	v_readlane_b32 s50, v247, 0
	v_readlane_b32 s51, v247, 1
	v_readlane_b32 s52, v247, 2
	v_readlane_b32 s53, v247, 3
	v_readlane_b32 s54, v247, 4
	v_readlane_b32 s55, v247, 5
	v_readlane_b32 s56, v247, 6
	v_readlane_b32 s57, v247, 7
	v_readlane_b32 s58, v247, 8
	v_readlane_b32 s59, v247, 9
	v_readlane_b32 s60, v247, 10
	v_readlane_b32 s61, v247, 11
	v_readlane_b32 s62, v247, 12
	v_readlane_b32 s63, v247, 13
	v_readlane_b32 s64, v247, 14
	v_readlane_b32 s65, v247, 15
	s_add_i32 s6, s28, 0
	s_lshl_b32 s6, s6, 12
	s_add_u32 s98, s16, s6
	s_addc_u32 s99, s17, 0
	s_add_u32 s98, s98, 0x23000000
	s_addc_u32 s99, s99, 0
	v_subrev_f32_e32 v50, s34, v204
	v_subrev_f32_e32 v51, s34, v205
	v_subrev_f32_e32 v54, s35, v206
	v_subrev_f32_e32 v55, s35, v207
	v_subrev_f32_e32 v58, s36, v208
	v_subrev_f32_e32 v59, s36, v209
	v_subrev_f32_e32 v62, s37, v210
	v_subrev_f32_e32 v63, s37, v211
	v_mul_f32_e32 v50, s50, v50
	v_mul_f32_e32 v51, s50, v51
	v_mul_f32_e32 v54, s51, v54
	v_mul_f32_e32 v55, s51, v55
	v_mul_f32_e32 v58, s52, v58
	v_mul_f32_e32 v59, s52, v59
	v_mul_f32_e32 v62, s53, v62
	v_mul_f32_e32 v63, s53, v63
	v_fma_f32 v50, v134, v50, v136
	v_fma_f32 v51, v135, v51, v137
	v_fma_f32 v54, v134, v54, v136
	v_fma_f32 v55, v135, v55, v137
	v_fma_f32 v58, v134, v58, v136
	v_fma_f32 v59, v135, v59, v137
	v_fma_f32 v62, v134, v62, v136
	v_fma_f32 v63, v135, v63, v137
	v_mul_f32_e32 v52, 0xbfb8aa3b, v50
	v_mul_f32_e32 v53, 0xbfb8aa3b, v51
	v_mul_f32_e32 v56, 0xbfb8aa3b, v54
	v_mul_f32_e32 v57, 0xbfb8aa3b, v55
	v_mul_f32_e32 v60, 0xbfb8aa3b, v58
	v_mul_f32_e32 v61, 0xbfb8aa3b, v59
	v_mul_f32_e32 v64, 0xbfb8aa3b, v62
	v_mul_f32_e32 v65, 0xbfb8aa3b, v63
	v_exp_f32_e32 v52, v52
	v_exp_f32_e32 v53, v53
	v_exp_f32_e32 v56, v56
	v_exp_f32_e32 v57, v57
	v_exp_f32_e32 v60, v60
	v_exp_f32_e32 v61, v61
	v_exp_f32_e32 v64, v64
	v_exp_f32_e32 v65, v65
	v_add_f32_e32 v52, 1.0, v52
	v_add_f32_e32 v53, 1.0, v53
	v_add_f32_e32 v56, 1.0, v56
	v_add_f32_e32 v57, 1.0, v57
	v_add_f32_e32 v60, 1.0, v60
	v_add_f32_e32 v61, 1.0, v61
	v_add_f32_e32 v64, 1.0, v64
	v_add_f32_e32 v65, 1.0, v65
	v_rcp_f32_e32 v52, v52
	v_rcp_f32_e32 v53, v53
	v_rcp_f32_e32 v56, v56
	v_rcp_f32_e32 v57, v57
	v_rcp_f32_e32 v60, v60
	v_rcp_f32_e32 v61, v61
	v_rcp_f32_e32 v64, v64
	v_rcp_f32_e32 v65, v65
	s_nop 0
	v_mul_f32_e32 v50, v50, v52
	v_mul_f32_e32 v51, v51, v53
	v_mul_f32_e32 v54, v54, v56
	v_mul_f32_e32 v55, v55, v57
	v_mul_f32_e32 v58, v58, v60
	v_mul_f32_e32 v59, v59, v61
	v_mul_f32_e32 v62, v62, v64
	v_mul_f32_e32 v63, v63, v65
	v_cvt_pk_bf16_f32 v52, v50, v51
	v_cvt_pk_bf16_f32 v56, v54, v55
	v_cvt_pk_bf16_f32 v60, v58, v59
	v_cvt_pk_bf16_f32 v64, v62, v63
	global_store_dword v251, v52, s[98:99] offset:2048
	s_add_u32 s98, s98, 0x1000
	s_addc_u32 s99, s99, 0
	global_store_dword v251, v56, s[98:99] offset:2048
	s_add_u32 s98, s98, 0x1000
	s_addc_u32 s99, s99, 0
	global_store_dword v251, v60, s[98:99] offset:2048
	s_add_u32 s98, s98, 0x1000
	s_addc_u32 s99, s99, 0
	global_store_dword v251, v64, s[98:99] offset:2048
	s_add_u32 s98, s98, 0x1000
	s_addc_u32 s99, s99, 0
	v_subrev_f32_e32 v50, s38, v212
	v_subrev_f32_e32 v51, s38, v213
	v_subrev_f32_e32 v54, s39, v214
	v_subrev_f32_e32 v55, s39, v215
	v_subrev_f32_e32 v58, s40, v216
	v_subrev_f32_e32 v59, s40, v217
	v_subrev_f32_e32 v62, s41, v218
	v_subrev_f32_e32 v63, s41, v219
	v_mul_f32_e32 v50, s54, v50
	v_mul_f32_e32 v51, s54, v51
	v_mul_f32_e32 v54, s55, v54
	v_mul_f32_e32 v55, s55, v55
	v_mul_f32_e32 v58, s56, v58
	v_mul_f32_e32 v59, s56, v59
	v_mul_f32_e32 v62, s57, v62
	v_mul_f32_e32 v63, s57, v63
	v_fma_f32 v50, v134, v50, v136
	v_fma_f32 v51, v135, v51, v137
	v_fma_f32 v54, v134, v54, v136
	v_fma_f32 v55, v135, v55, v137
	v_fma_f32 v58, v134, v58, v136
	v_fma_f32 v59, v135, v59, v137
	v_fma_f32 v62, v134, v62, v136
	v_fma_f32 v63, v135, v63, v137
	v_mul_f32_e32 v52, 0xbfb8aa3b, v50
	v_mul_f32_e32 v53, 0xbfb8aa3b, v51
	v_mul_f32_e32 v56, 0xbfb8aa3b, v54
	v_mul_f32_e32 v57, 0xbfb8aa3b, v55
	v_mul_f32_e32 v60, 0xbfb8aa3b, v58
	v_mul_f32_e32 v61, 0xbfb8aa3b, v59
	v_mul_f32_e32 v64, 0xbfb8aa3b, v62
	v_mul_f32_e32 v65, 0xbfb8aa3b, v63
	v_exp_f32_e32 v52, v52
	v_exp_f32_e32 v53, v53
	v_exp_f32_e32 v56, v56
	v_exp_f32_e32 v57, v57
	v_exp_f32_e32 v60, v60
	v_exp_f32_e32 v61, v61
	v_exp_f32_e32 v64, v64
	v_exp_f32_e32 v65, v65
	v_add_f32_e32 v52, 1.0, v52
	v_add_f32_e32 v53, 1.0, v53
	v_add_f32_e32 v56, 1.0, v56
	v_add_f32_e32 v57, 1.0, v57
	v_add_f32_e32 v60, 1.0, v60
	v_add_f32_e32 v61, 1.0, v61
	v_add_f32_e32 v64, 1.0, v64
	v_add_f32_e32 v65, 1.0, v65
	v_rcp_f32_e32 v52, v52
	v_rcp_f32_e32 v53, v53
	v_rcp_f32_e32 v56, v56
	v_rcp_f32_e32 v57, v57
	v_rcp_f32_e32 v60, v60
	v_rcp_f32_e32 v61, v61
	v_rcp_f32_e32 v64, v64
	v_rcp_f32_e32 v65, v65
	s_nop 0
	v_mul_f32_e32 v50, v50, v52
	v_mul_f32_e32 v51, v51, v53
	v_mul_f32_e32 v54, v54, v56
	v_mul_f32_e32 v55, v55, v57
	v_mul_f32_e32 v58, v58, v60
	v_mul_f32_e32 v59, v59, v61
	v_mul_f32_e32 v62, v62, v64
	v_mul_f32_e32 v63, v63, v65
	v_cvt_pk_bf16_f32 v52, v50, v51
	v_cvt_pk_bf16_f32 v56, v54, v55
	v_cvt_pk_bf16_f32 v60, v58, v59
	v_cvt_pk_bf16_f32 v64, v62, v63
	global_store_dword v251, v52, s[98:99] offset:2048
	s_add_u32 s98, s98, 0x1000
	s_addc_u32 s99, s99, 0
	global_store_dword v251, v56, s[98:99] offset:2048
	s_add_u32 s98, s98, 0x1000
	s_addc_u32 s99, s99, 0
	global_store_dword v251, v60, s[98:99] offset:2048
	s_add_u32 s98, s98, 0x1000
	s_addc_u32 s99, s99, 0
	global_store_dword v251, v64, s[98:99] offset:2048
	s_add_u32 s98, s98, 0x1000
	s_addc_u32 s99, s99, 0
	v_subrev_f32_e32 v50, s42, v220
	v_subrev_f32_e32 v51, s42, v221
	v_subrev_f32_e32 v54, s43, v222
	v_subrev_f32_e32 v55, s43, v223
	v_subrev_f32_e32 v58, s44, v224
	v_subrev_f32_e32 v59, s44, v225
	v_subrev_f32_e32 v62, s45, v226
	v_subrev_f32_e32 v63, s45, v227
	v_mul_f32_e32 v50, s58, v50
	v_mul_f32_e32 v51, s58, v51
	v_mul_f32_e32 v54, s59, v54
	v_mul_f32_e32 v55, s59, v55
	v_mul_f32_e32 v58, s60, v58
	v_mul_f32_e32 v59, s60, v59
	v_mul_f32_e32 v62, s61, v62
	v_mul_f32_e32 v63, s61, v63
	v_fma_f32 v50, v134, v50, v136
	v_fma_f32 v51, v135, v51, v137
	v_fma_f32 v54, v134, v54, v136
	v_fma_f32 v55, v135, v55, v137
	v_fma_f32 v58, v134, v58, v136
	v_fma_f32 v59, v135, v59, v137
	v_fma_f32 v62, v134, v62, v136
	v_fma_f32 v63, v135, v63, v137
	v_mul_f32_e32 v52, 0xbfb8aa3b, v50
	v_mul_f32_e32 v53, 0xbfb8aa3b, v51
	v_mul_f32_e32 v56, 0xbfb8aa3b, v54
	v_mul_f32_e32 v57, 0xbfb8aa3b, v55
	v_mul_f32_e32 v60, 0xbfb8aa3b, v58
	v_mul_f32_e32 v61, 0xbfb8aa3b, v59
	v_mul_f32_e32 v64, 0xbfb8aa3b, v62
	v_mul_f32_e32 v65, 0xbfb8aa3b, v63
	v_exp_f32_e32 v52, v52
	v_exp_f32_e32 v53, v53
	v_exp_f32_e32 v56, v56
	v_exp_f32_e32 v57, v57
	v_exp_f32_e32 v60, v60
	v_exp_f32_e32 v61, v61
	v_exp_f32_e32 v64, v64
	v_exp_f32_e32 v65, v65
	v_add_f32_e32 v52, 1.0, v52
	v_add_f32_e32 v53, 1.0, v53
	v_add_f32_e32 v56, 1.0, v56
	v_add_f32_e32 v57, 1.0, v57
	v_add_f32_e32 v60, 1.0, v60
	v_add_f32_e32 v61, 1.0, v61
	v_add_f32_e32 v64, 1.0, v64
	v_add_f32_e32 v65, 1.0, v65
	v_rcp_f32_e32 v52, v52
	v_rcp_f32_e32 v53, v53
	v_rcp_f32_e32 v56, v56
	v_rcp_f32_e32 v57, v57
	v_rcp_f32_e32 v60, v60
	v_rcp_f32_e32 v61, v61
	v_rcp_f32_e32 v64, v64
	v_rcp_f32_e32 v65, v65
	s_nop 0
	v_mul_f32_e32 v50, v50, v52
	v_mul_f32_e32 v51, v51, v53
	v_mul_f32_e32 v54, v54, v56
	v_mul_f32_e32 v55, v55, v57
	v_mul_f32_e32 v58, v58, v60
	v_mul_f32_e32 v59, v59, v61
	v_mul_f32_e32 v62, v62, v64
	v_mul_f32_e32 v63, v63, v65
	v_cvt_pk_bf16_f32 v52, v50, v51
	v_cvt_pk_bf16_f32 v56, v54, v55
	v_cvt_pk_bf16_f32 v60, v58, v59
	v_cvt_pk_bf16_f32 v64, v62, v63
	global_store_dword v251, v52, s[98:99] offset:2048
	s_add_u32 s98, s98, 0x1000
	s_addc_u32 s99, s99, 0
	global_store_dword v251, v56, s[98:99] offset:2048
	s_add_u32 s98, s98, 0x1000
	s_addc_u32 s99, s99, 0
	global_store_dword v251, v60, s[98:99] offset:2048
	s_add_u32 s98, s98, 0x1000
	s_addc_u32 s99, s99, 0
	global_store_dword v251, v64, s[98:99] offset:2048
	s_add_u32 s98, s98, 0x1000
	s_addc_u32 s99, s99, 0
	v_subrev_f32_e32 v50, s46, v228
	v_subrev_f32_e32 v51, s46, v229
	v_subrev_f32_e32 v54, s47, v230
	v_subrev_f32_e32 v55, s47, v231
	v_subrev_f32_e32 v58, s48, v232
	v_subrev_f32_e32 v59, s48, v233
	v_subrev_f32_e32 v62, s49, v234
	v_subrev_f32_e32 v63, s49, v235
	v_mul_f32_e32 v50, s62, v50
	v_mul_f32_e32 v51, s62, v51
	v_mul_f32_e32 v54, s63, v54
	v_mul_f32_e32 v55, s63, v55
	v_mul_f32_e32 v58, s64, v58
	v_mul_f32_e32 v59, s64, v59
	v_mul_f32_e32 v62, s65, v62
	v_mul_f32_e32 v63, s65, v63
	v_fma_f32 v50, v134, v50, v136
	v_fma_f32 v51, v135, v51, v137
	v_fma_f32 v54, v134, v54, v136
	v_fma_f32 v55, v135, v55, v137
	v_fma_f32 v58, v134, v58, v136
	v_fma_f32 v59, v135, v59, v137
	v_fma_f32 v62, v134, v62, v136
	v_fma_f32 v63, v135, v63, v137
	v_mul_f32_e32 v52, 0xbfb8aa3b, v50
	v_mul_f32_e32 v53, 0xbfb8aa3b, v51
	v_mul_f32_e32 v56, 0xbfb8aa3b, v54
	v_mul_f32_e32 v57, 0xbfb8aa3b, v55
	v_mul_f32_e32 v60, 0xbfb8aa3b, v58
	v_mul_f32_e32 v61, 0xbfb8aa3b, v59
	v_mul_f32_e32 v64, 0xbfb8aa3b, v62
	v_mul_f32_e32 v65, 0xbfb8aa3b, v63
	v_exp_f32_e32 v52, v52
	v_exp_f32_e32 v53, v53
	v_exp_f32_e32 v56, v56
	v_exp_f32_e32 v57, v57
	v_exp_f32_e32 v60, v60
	v_exp_f32_e32 v61, v61
	v_exp_f32_e32 v64, v64
	v_exp_f32_e32 v65, v65
	v_add_f32_e32 v52, 1.0, v52
	v_add_f32_e32 v53, 1.0, v53
	v_add_f32_e32 v56, 1.0, v56
	v_add_f32_e32 v57, 1.0, v57
	v_add_f32_e32 v60, 1.0, v60
	v_add_f32_e32 v61, 1.0, v61
	v_add_f32_e32 v64, 1.0, v64
	v_add_f32_e32 v65, 1.0, v65
	v_rcp_f32_e32 v52, v52
	v_rcp_f32_e32 v53, v53
	v_rcp_f32_e32 v56, v56
	v_rcp_f32_e32 v57, v57
	v_rcp_f32_e32 v60, v60
	v_rcp_f32_e32 v61, v61
	v_rcp_f32_e32 v64, v64
	v_rcp_f32_e32 v65, v65
	s_nop 0
	v_mul_f32_e32 v50, v50, v52
	v_mul_f32_e32 v51, v51, v53
	v_mul_f32_e32 v54, v54, v56
	v_mul_f32_e32 v55, v55, v57
	v_mul_f32_e32 v58, v58, v60
	v_mul_f32_e32 v59, v59, v61
	v_mul_f32_e32 v62, v62, v64
	v_mul_f32_e32 v63, v63, v65
	v_cvt_pk_bf16_f32 v52, v50, v51
	v_cvt_pk_bf16_f32 v56, v54, v55
	v_cvt_pk_bf16_f32 v60, v58, v59
	v_cvt_pk_bf16_f32 v64, v62, v63
	global_store_dword v251, v52, s[98:99] offset:2048
	s_add_u32 s98, s98, 0x1000
	s_addc_u32 s99, s99, 0
	global_store_dword v251, v56, s[98:99] offset:2048
	s_add_u32 s98, s98, 0x1000
	s_addc_u32 s99, s99, 0
	global_store_dword v251, v60, s[98:99] offset:2048
	s_add_u32 s98, s98, 0x1000
	s_addc_u32 s99, s99, 0
	global_store_dword v251, v64, s[98:99] offset:2048
	s_add_u32 s98, s98, 0x1000
	s_addc_u32 s99, s99, 0
.Lp2_skip_0:
	s_cmp_lt_i32 s33, 0
	s_cselect_b64 s[6:7], -1, 0
	s_and_b64 s[6:7], s[6:7], s[22:23]
	s_and_b64 vcc, exec, s[6:7]
	s_cbranch_vccnz .Lp2_zero_1
	s_cmp_gt_i32 s33, -1
	s_cbranch_scc1 .Lp2_w16_1
	s_waitcnt vmcnt(0)
	s_branch .Lp2_wd_1

.Lp2_glud_1:
	s_cmp_eq_u32 s33, 3
	s_cbranch_scc1 .Lp2_nopf
	s_mov_b32 s98, s24
	s_lshl_b32 s98, s98, 11
	s_ashr_i32 s99, s98, 31
	s_add_u32 s100, s98, s20
	s_addc_u32 s101, s99, s21
	s_add_u32 s98, s98, s18
	s_addc_u32 s99, s99, s19
	global_load_dword v10, v251, s[98:99]
	global_load_dword v26, v251, s[100:101]
	global_load_dword v11, v251, s[98:99] offset:2048
	global_load_dword v27, v251, s[100:101] offset:2048
	s_add_u32 s98, s98, 0x1000
	s_addc_u32 s99, s99, 0
	s_add_u32 s100, s100, 0x1000
	s_addc_u32 s101, s101, 0
	global_load_dword v12, v251, s[98:99]
	global_load_dword v28, v251, s[100:101]
	global_load_dword v13, v251, s[98:99] offset:2048
	global_load_dword v29, v251, s[100:101] offset:2048
	s_add_u32 s98, s98, 0x1000
	s_addc_u32 s99, s99, 0
	s_add_u32 s100, s100, 0x1000
	s_addc_u32 s101, s101, 0
	global_load_dword v14, v251, s[98:99]
	global_load_dword v30, v251, s[100:101]
	global_load_dword v15, v251, s[98:99] offset:2048
	global_load_dword v31, v251, s[100:101] offset:2048
	s_add_u32 s98, s98, 0x1000
	s_addc_u32 s99, s99, 0
	s_add_u32 s100, s100, 0x1000
	s_addc_u32 s101, s101, 0
	global_load_dword v16, v251, s[98:99]
	global_load_dword v32, v251, s[100:101]
	global_load_dword v17, v251, s[98:99] offset:2048
	global_load_dword v33, v251, s[100:101] offset:2048
	s_add_u32 s98, s98, 0x1000
	s_addc_u32 s99, s99, 0
	s_add_u32 s100, s100, 0x1000
	s_addc_u32 s101, s101, 0
	global_load_dword v18, v251, s[98:99]
	global_load_dword v34, v251, s[100:101]
	global_load_dword v19, v251, s[98:99] offset:2048
	global_load_dword v35, v251, s[100:101] offset:2048
	s_add_u32 s98, s98, 0x1000
	s_addc_u32 s99, s99, 0
	s_add_u32 s100, s100, 0x1000
	s_addc_u32 s101, s101, 0
	global_load_dword v20, v251, s[98:99]
	global_load_dword v36, v251, s[100:101]
	global_load_dword v21, v251, s[98:99] offset:2048
	global_load_dword v37, v251, s[100:101] offset:2048
	s_add_u32 s98, s98, 0x1000
	s_addc_u32 s99, s99, 0
	s_add_u32 s100, s100, 0x1000
	s_addc_u32 s101, s101, 0
	global_load_dword v22, v251, s[98:99]
	global_load_dword v38, v251, s[100:101]
	global_load_dword v23, v251, s[98:99] offset:2048
	global_load_dword v39, v251, s[100:101] offset:2048
	s_add_u32 s98, s98, 0x1000
	s_addc_u32 s99, s99, 0
	s_add_u32 s100, s100, 0x1000
	s_addc_u32 s101, s101, 0
	global_load_dword v24, v251, s[98:99]
	global_load_dword v40, v251, s[100:101]
	global_load_dword v25, v251, s[98:99] offset:2048
	global_load_dword v41, v251, s[100:101] offset:2048
.Lp2_nopf:
	s_cmp_lt_i32 s33, 0
	s_cbranch_scc1 .Lp2_nofma_1
	v_pk_fma_f32 v[204:205], v[176:177], v[70:71], v[132:133]
	v_pk_fma_f32 v[206:207], v[178:179], v[70:71], v[132:133]
	v_pk_fma_f32 v[208:209], v[180:181], v[70:71], v[132:133]
	v_pk_fma_f32 v[210:211], v[182:183], v[70:71], v[132:133]
	v_pk_fma_f32 v[204:205], v[178:179], v[72:73], v[204:205]
	v_pk_fma_f32 v[206:207], v[180:181], v[72:73], v[206:207]
	v_pk_fma_f32 v[208:209], v[182:183], v[72:73], v[208:209]
	v_pk_fma_f32 v[210:211], v[184:185], v[72:73], v[210:211]
	v_pk_fma_f32 v[204:205], v[180:181], v[74:75], v[204:205]
	v_pk_fma_f32 v[206:207], v[182:183], v[74:75], v[206:207]
	v_pk_fma_f32 v[208:209], v[184:185], v[74:75], v[208:209]
	v_pk_fma_f32 v[210:211], v[186:187], v[74:75], v[210:211]
	v_pk_fma_f32 v[204:205], v[182:183], v[76:77], v[204:205]
	v_pk_fma_f32 v[206:207], v[184:185], v[76:77], v[206:207]
	v_pk_fma_f32 v[208:209], v[186:187], v[76:77], v[208:209]
	v_pk_fma_f32 v[210:211], v[188:189], v[76:77], v[210:211]
	v_pk_fma_f32 v[204:205], v[184:185], v[78:79], v[204:205]
	v_pk_fma_f32 v[206:207], v[186:187], v[78:79], v[206:207]
	v_pk_fma_f32 v[208:209], v[188:189], v[78:79], v[208:209]
	v_pk_fma_f32 v[210:211], v[190:191], v[78:79], v[210:211]
	v_pk_fma_f32 v[204:205], v[186:187], v[80:81], v[204:205]
	v_pk_fma_f32 v[206:207], v[188:189], v[80:81], v[206:207]
	v_pk_fma_f32 v[208:209], v[190:191], v[80:81], v[208:209]
	v_pk_fma_f32 v[210:211], v[192:193], v[80:81], v[210:211]
	v_pk_fma_f32 v[204:205], v[188:189], v[82:83], v[204:205]
	v_pk_fma_f32 v[206:207], v[190:191], v[82:83], v[206:207]
	v_pk_fma_f32 v[208:209], v[192:193], v[82:83], v[208:209]
	v_pk_fma_f32 v[210:211], v[194:195], v[82:83], v[210:211]
	v_pk_fma_f32 v[204:205], v[190:191], v[84:85], v[204:205]
	v_pk_fma_f32 v[206:207], v[192:193], v[84:85], v[206:207]
	v_pk_fma_f32 v[208:209], v[194:195], v[84:85], v[208:209]
	v_pk_fma_f32 v[210:211], v[196:197], v[84:85], v[210:211]
	v_pk_fma_f32 v[204:205], v[192:193], v[86:87], v[204:205]
	v_pk_fma_f32 v[206:207], v[194:195], v[86:87], v[206:207]
	v_pk_fma_f32 v[208:209], v[196:197], v[86:87], v[208:209]
	v_pk_fma_f32 v[210:211], v[198:199], v[86:87], v[210:211]
	v_pk_fma_f32 v[204:205], v[194:195], v[92:93], v[204:205]
	v_pk_fma_f32 v[206:207], v[196:197], v[92:93], v[206:207]
	v_pk_fma_f32 v[208:209], v[198:199], v[92:93], v[208:209]
	v_pk_fma_f32 v[210:211], v[200:201], v[92:93], v[210:211]
	v_pk_fma_f32 v[204:205], v[196:197], v[94:95], v[204:205]
	v_pk_fma_f32 v[206:207], v[198:199], v[94:95], v[206:207]
	v_pk_fma_f32 v[208:209], v[200:201], v[94:95], v[208:209]
	v_pk_fma_f32 v[210:211], v[202:203], v[94:95], v[210:211]
	v_pk_fma_f32 v[204:205], v[198:199], v[96:97], v[204:205]
	v_pk_fma_f32 v[206:207], v[200:201], v[96:97], v[206:207]
	v_pk_fma_f32 v[208:209], v[202:203], v[96:97], v[208:209]
	v_pk_fma_f32 v[210:211], v[140:141], v[96:97], v[210:211]
	v_pk_fma_f32 v[204:205], v[200:201], v[98:99], v[204:205]
	v_pk_fma_f32 v[206:207], v[202:203], v[98:99], v[206:207]
	v_pk_fma_f32 v[208:209], v[140:141], v[98:99], v[208:209]
	v_pk_fma_f32 v[210:211], v[142:143], v[98:99], v[210:211]
	v_pk_fma_f32 v[204:205], v[202:203], v[100:101], v[204:205]
	v_pk_fma_f32 v[206:207], v[140:141], v[100:101], v[206:207]
	v_pk_fma_f32 v[208:209], v[142:143], v[100:101], v[208:209]
	v_pk_fma_f32 v[210:211], v[144:145], v[100:101], v[210:211]
	v_pk_fma_f32 v[204:205], v[140:141], v[102:103], v[204:205]
	v_pk_fma_f32 v[206:207], v[142:143], v[102:103], v[206:207]
	v_pk_fma_f32 v[208:209], v[144:145], v[102:103], v[208:209]
	v_pk_fma_f32 v[210:211], v[146:147], v[102:103], v[210:211]
	v_pk_fma_f32 v[204:205], v[142:143], v[104:105], v[204:205]
	v_pk_fma_f32 v[206:207], v[144:145], v[104:105], v[206:207]
	v_pk_fma_f32 v[208:209], v[146:147], v[104:105], v[208:209]
	v_pk_fma_f32 v[210:211], v[148:149], v[104:105], v[210:211]
	v_pk_fma_f32 v[204:205], v[144:145], v[106:107], v[204:205]
	v_pk_fma_f32 v[206:207], v[146:147], v[106:107], v[206:207]
	v_pk_fma_f32 v[208:209], v[148:149], v[106:107], v[208:209]
	v_pk_fma_f32 v[210:211], v[150:151], v[106:107], v[210:211]
	v_pk_fma_f32 v[204:205], v[146:147], v[108:109], v[204:205]
	v_pk_fma_f32 v[206:207], v[148:149], v[108:109], v[206:207]
	v_pk_fma_f32 v[208:209], v[150:151], v[108:109], v[208:209]
	v_pk_fma_f32 v[210:211], v[152:153], v[108:109], v[210:211]
	v_pk_fma_f32 v[204:205], v[148:149], v[110:111], v[204:205]
	v_pk_fma_f32 v[206:207], v[150:151], v[110:111], v[206:207]
	v_pk_fma_f32 v[208:209], v[152:153], v[110:111], v[208:209]
	v_pk_fma_f32 v[210:211], v[154:155], v[110:111], v[210:211]
	v_pk_fma_f32 v[204:205], v[150:151], v[112:113], v[204:205]
	v_pk_fma_f32 v[206:207], v[152:153], v[112:113], v[206:207]
	v_pk_fma_f32 v[208:209], v[154:155], v[112:113], v[208:209]
	v_pk_fma_f32 v[210:211], v[156:157], v[112:113], v[210:211]
	v_pk_fma_f32 v[204:205], v[152:153], v[114:115], v[204:205]
	v_pk_fma_f32 v[206:207], v[154:155], v[114:115], v[206:207]
	v_pk_fma_f32 v[208:209], v[156:157], v[114:115], v[208:209]
	v_pk_fma_f32 v[210:211], v[158:159], v[114:115], v[210:211]
	v_pk_fma_f32 v[204:205], v[154:155], v[116:117], v[204:205]
	v_pk_fma_f32 v[206:207], v[156:157], v[116:117], v[206:207]
	v_pk_fma_f32 v[208:209], v[158:159], v[116:117], v[208:209]
	v_pk_fma_f32 v[210:211], v[160:161], v[116:117], v[210:211]
	v_pk_fma_f32 v[204:205], v[156:157], v[118:119], v[204:205]
	v_pk_fma_f32 v[206:207], v[158:159], v[118:119], v[206:207]
	v_pk_fma_f32 v[208:209], v[160:161], v[118:119], v[208:209]
	v_pk_fma_f32 v[210:211], v[162:163], v[118:119], v[210:211]
	v_pk_fma_f32 v[204:205], v[158:159], v[120:121], v[204:205]
	v_pk_fma_f32 v[206:207], v[160:161], v[120:121], v[206:207]
	v_pk_fma_f32 v[208:209], v[162:163], v[120:121], v[208:209]
	v_pk_fma_f32 v[210:211], v[164:165], v[120:121], v[210:211]
	v_pk_fma_f32 v[204:205], v[160:161], v[122:123], v[204:205]
	v_pk_fma_f32 v[206:207], v[162:163], v[122:123], v[206:207]
	v_pk_fma_f32 v[208:209], v[164:165], v[122:123], v[208:209]
	v_pk_fma_f32 v[210:211], v[166:167], v[122:123], v[210:211]
	v_pk_fma_f32 v[204:205], v[162:163], v[124:125], v[204:205]
	v_pk_fma_f32 v[206:207], v[164:165], v[124:125], v[206:207]
	v_pk_fma_f32 v[208:209], v[166:167], v[124:125], v[208:209]
	v_pk_fma_f32 v[210:211], v[168:169], v[124:125], v[210:211]
	v_pk_fma_f32 v[204:205], v[164:165], v[126:127], v[204:205]
	v_pk_fma_f32 v[206:207], v[166:167], v[126:127], v[206:207]
	v_pk_fma_f32 v[208:209], v[168:169], v[126:127], v[208:209]
	v_pk_fma_f32 v[210:211], v[170:171], v[126:127], v[210:211]
	v_pk_fma_f32 v[204:205], v[166:167], v[128:129], v[204:205]
	v_pk_fma_f32 v[206:207], v[168:169], v[128:129], v[206:207]
	v_pk_fma_f32 v[208:209], v[170:171], v[128:129], v[208:209]
	v_pk_fma_f32 v[210:211], v[42:43], v[128:129], v[210:211]
	v_pk_fma_f32 v[204:205], v[168:169], v[130:131], v[204:205]
	v_pk_fma_f32 v[206:207], v[170:171], v[130:131], v[206:207]
	v_pk_fma_f32 v[208:209], v[42:43], v[130:131], v[208:209]
	v_pk_fma_f32 v[210:211], v[44:45], v[130:131], v[210:211]
	v_pk_fma_f32 v[204:205], v[170:171], v[88:89], v[204:205]
	v_pk_fma_f32 v[206:207], v[42:43], v[88:89], v[206:207]
	v_pk_fma_f32 v[208:209], v[44:45], v[88:89], v[208:209]
	v_pk_fma_f32 v[210:211], v[46:47], v[88:89], v[210:211]
	v_pk_fma_f32 v[204:205], v[42:43], v[90:91], v[204:205]
	v_pk_fma_f32 v[206:207], v[44:45], v[90:91], v[206:207]
	v_pk_fma_f32 v[208:209], v[46:47], v[90:91], v[208:209]
	v_pk_fma_f32 v[210:211], v[48:49], v[90:91], v[210:211]
	v_pk_fma_f32 v[212:213], v[184:185], v[70:71], v[132:133]
	v_pk_fma_f32 v[214:215], v[186:187], v[70:71], v[132:133]
	v_pk_fma_f32 v[216:217], v[188:189], v[70:71], v[132:133]
	v_pk_fma_f32 v[218:219], v[190:191], v[70:71], v[132:133]
	v_pk_fma_f32 v[212:213], v[186:187], v[72:73], v[212:213]
	v_pk_fma_f32 v[214:215], v[188:189], v[72:73], v[214:215]
	v_pk_fma_f32 v[216:217], v[190:191], v[72:73], v[216:217]
	v_pk_fma_f32 v[218:219], v[192:193], v[72:73], v[218:219]
	v_pk_fma_f32 v[212:213], v[188:189], v[74:75], v[212:213]
	v_pk_fma_f32 v[214:215], v[190:191], v[74:75], v[214:215]
	v_pk_fma_f32 v[216:217], v[192:193], v[74:75], v[216:217]
	v_pk_fma_f32 v[218:219], v[194:195], v[74:75], v[218:219]
	v_pk_fma_f32 v[212:213], v[190:191], v[76:77], v[212:213]
	v_pk_fma_f32 v[214:215], v[192:193], v[76:77], v[214:215]
	v_pk_fma_f32 v[216:217], v[194:195], v[76:77], v[216:217]
	v_pk_fma_f32 v[218:219], v[196:197], v[76:77], v[218:219]
	v_pk_fma_f32 v[212:213], v[192:193], v[78:79], v[212:213]
	v_pk_fma_f32 v[214:215], v[194:195], v[78:79], v[214:215]
	v_pk_fma_f32 v[216:217], v[196:197], v[78:79], v[216:217]
	v_pk_fma_f32 v[218:219], v[198:199], v[78:79], v[218:219]
	v_pk_fma_f32 v[212:213], v[194:195], v[80:81], v[212:213]
	v_pk_fma_f32 v[214:215], v[196:197], v[80:81], v[214:215]
	v_pk_fma_f32 v[216:217], v[198:199], v[80:81], v[216:217]
	v_pk_fma_f32 v[218:219], v[200:201], v[80:81], v[218:219]
	v_pk_fma_f32 v[212:213], v[196:197], v[82:83], v[212:213]
	v_pk_fma_f32 v[214:215], v[198:199], v[82:83], v[214:215]
	v_pk_fma_f32 v[216:217], v[200:201], v[82:83], v[216:217]
	v_pk_fma_f32 v[218:219], v[202:203], v[82:83], v[218:219]
	v_pk_fma_f32 v[212:213], v[198:199], v[84:85], v[212:213]
	v_pk_fma_f32 v[214:215], v[200:201], v[84:85], v[214:215]
	v_pk_fma_f32 v[216:217], v[202:203], v[84:85], v[216:217]
	v_pk_fma_f32 v[218:219], v[140:141], v[84:85], v[218:219]
	v_pk_fma_f32 v[212:213], v[200:201], v[86:87], v[212:213]
	v_pk_fma_f32 v[214:215], v[202:203], v[86:87], v[214:215]
	v_pk_fma_f32 v[216:217], v[140:141], v[86:87], v[216:217]
	v_pk_fma_f32 v[218:219], v[142:143], v[86:87], v[218:219]
	v_pk_fma_f32 v[212:213], v[202:203], v[92:93], v[212:213]
	v_pk_fma_f32 v[214:215], v[140:141], v[92:93], v[214:215]
	v_pk_fma_f32 v[216:217], v[142:143], v[92:93], v[216:217]
	v_pk_fma_f32 v[218:219], v[144:145], v[92:93], v[218:219]
	v_pk_fma_f32 v[212:213], v[140:141], v[94:95], v[212:213]
	v_pk_fma_f32 v[214:215], v[142:143], v[94:95], v[214:215]
	v_pk_fma_f32 v[216:217], v[144:145], v[94:95], v[216:217]
	v_pk_fma_f32 v[218:219], v[146:147], v[94:95], v[218:219]
	v_pk_fma_f32 v[212:213], v[142:143], v[96:97], v[212:213]
	v_pk_fma_f32 v[214:215], v[144:145], v[96:97], v[214:215]
	v_pk_fma_f32 v[216:217], v[146:147], v[96:97], v[216:217]
	v_pk_fma_f32 v[218:219], v[148:149], v[96:97], v[218:219]
	v_pk_fma_f32 v[212:213], v[144:145], v[98:99], v[212:213]
	v_pk_fma_f32 v[214:215], v[146:147], v[98:99], v[214:215]
	v_pk_fma_f32 v[216:217], v[148:149], v[98:99], v[216:217]
	v_pk_fma_f32 v[218:219], v[150:151], v[98:99], v[218:219]
	v_pk_fma_f32 v[212:213], v[146:147], v[100:101], v[212:213]
	v_pk_fma_f32 v[214:215], v[148:149], v[100:101], v[214:215]
	v_pk_fma_f32 v[216:217], v[150:151], v[100:101], v[216:217]
	v_pk_fma_f32 v[218:219], v[152:153], v[100:101], v[218:219]
	v_pk_fma_f32 v[212:213], v[148:149], v[102:103], v[212:213]
	v_pk_fma_f32 v[214:215], v[150:151], v[102:103], v[214:215]
	v_pk_fma_f32 v[216:217], v[152:153], v[102:103], v[216:217]
	v_pk_fma_f32 v[218:219], v[154:155], v[102:103], v[218:219]
	v_pk_fma_f32 v[212:213], v[150:151], v[104:105], v[212:213]
	v_pk_fma_f32 v[214:215], v[152:153], v[104:105], v[214:215]
	v_pk_fma_f32 v[216:217], v[154:155], v[104:105], v[216:217]
	v_pk_fma_f32 v[218:219], v[156:157], v[104:105], v[218:219]
	v_pk_fma_f32 v[212:213], v[152:153], v[106:107], v[212:213]
	v_pk_fma_f32 v[214:215], v[154:155], v[106:107], v[214:215]
	v_pk_fma_f32 v[216:217], v[156:157], v[106:107], v[216:217]
	v_pk_fma_f32 v[218:219], v[158:159], v[106:107], v[218:219]
	v_pk_fma_f32 v[212:213], v[154:155], v[108:109], v[212:213]
	v_pk_fma_f32 v[214:215], v[156:157], v[108:109], v[214:215]
	v_pk_fma_f32 v[216:217], v[158:159], v[108:109], v[216:217]
	v_pk_fma_f32 v[218:219], v[160:161], v[108:109], v[218:219]
	v_pk_fma_f32 v[212:213], v[156:157], v[110:111], v[212:213]
	v_pk_fma_f32 v[214:215], v[158:159], v[110:111], v[214:215]
	v_pk_fma_f32 v[216:217], v[160:161], v[110:111], v[216:217]
	v_pk_fma_f32 v[218:219], v[162:163], v[110:111], v[218:219]
	v_pk_fma_f32 v[212:213], v[158:159], v[112:113], v[212:213]
	v_pk_fma_f32 v[214:215], v[160:161], v[112:113], v[214:215]
	v_pk_fma_f32 v[216:217], v[162:163], v[112:113], v[216:217]
	v_pk_fma_f32 v[218:219], v[164:165], v[112:113], v[218:219]
	v_pk_fma_f32 v[212:213], v[160:161], v[114:115], v[212:213]
	v_pk_fma_f32 v[214:215], v[162:163], v[114:115], v[214:215]
	v_pk_fma_f32 v[216:217], v[164:165], v[114:115], v[216:217]
	v_pk_fma_f32 v[218:219], v[166:167], v[114:115], v[218:219]
	v_pk_fma_f32 v[212:213], v[162:163], v[116:117], v[212:213]
	v_pk_fma_f32 v[214:215], v[164:165], v[116:117], v[214:215]
	v_pk_fma_f32 v[216:217], v[166:167], v[116:117], v[216:217]
	v_pk_fma_f32 v[218:219], v[168:169], v[116:117], v[218:219]
	v_pk_fma_f32 v[212:213], v[164:165], v[118:119], v[212:213]
	v_pk_fma_f32 v[214:215], v[166:167], v[118:119], v[214:215]
	v_pk_fma_f32 v[216:217], v[168:169], v[118:119], v[216:217]
	v_pk_fma_f32 v[218:219], v[170:171], v[118:119], v[218:219]
	v_pk_fma_f32 v[212:213], v[166:167], v[120:121], v[212:213]
	v_pk_fma_f32 v[214:215], v[168:169], v[120:121], v[214:215]
	v_pk_fma_f32 v[216:217], v[170:171], v[120:121], v[216:217]
	v_pk_fma_f32 v[218:219], v[42:43], v[120:121], v[218:219]
	v_pk_fma_f32 v[212:213], v[168:169], v[122:123], v[212:213]
	v_pk_fma_f32 v[214:215], v[170:171], v[122:123], v[214:215]
	v_pk_fma_f32 v[216:217], v[42:43], v[122:123], v[216:217]
	v_pk_fma_f32 v[218:219], v[44:45], v[122:123], v[218:219]
	v_pk_fma_f32 v[212:213], v[170:171], v[124:125], v[212:213]
	v_pk_fma_f32 v[214:215], v[42:43], v[124:125], v[214:215]
	v_pk_fma_f32 v[216:217], v[44:45], v[124:125], v[216:217]
	v_pk_fma_f32 v[218:219], v[46:47], v[124:125], v[218:219]
	v_pk_fma_f32 v[212:213], v[42:43], v[126:127], v[212:213]
	v_pk_fma_f32 v[214:215], v[44:45], v[126:127], v[214:215]
	v_pk_fma_f32 v[216:217], v[46:47], v[126:127], v[216:217]
	v_pk_fma_f32 v[218:219], v[48:49], v[126:127], v[218:219]
	v_pk_fma_f32 v[212:213], v[44:45], v[128:129], v[212:213]
	v_pk_fma_f32 v[214:215], v[46:47], v[128:129], v[214:215]
	v_pk_fma_f32 v[216:217], v[48:49], v[128:129], v[216:217]
	v_pk_fma_f32 v[218:219], v[50:51], v[128:129], v[218:219]
	v_pk_fma_f32 v[212:213], v[46:47], v[130:131], v[212:213]
	v_pk_fma_f32 v[214:215], v[48:49], v[130:131], v[214:215]
	v_pk_fma_f32 v[216:217], v[50:51], v[130:131], v[216:217]
	v_pk_fma_f32 v[218:219], v[52:53], v[130:131], v[218:219]
	v_pk_fma_f32 v[212:213], v[48:49], v[88:89], v[212:213]
	v_pk_fma_f32 v[214:215], v[50:51], v[88:89], v[214:215]
	v_pk_fma_f32 v[216:217], v[52:53], v[88:89], v[216:217]
	v_pk_fma_f32 v[218:219], v[54:55], v[88:89], v[218:219]
	v_pk_fma_f32 v[212:213], v[50:51], v[90:91], v[212:213]
	v_pk_fma_f32 v[214:215], v[52:53], v[90:91], v[214:215]
	v_pk_fma_f32 v[216:217], v[54:55], v[90:91], v[216:217]
	v_pk_fma_f32 v[218:219], v[56:57], v[90:91], v[218:219]
	v_pk_fma_f32 v[220:221], v[192:193], v[70:71], v[132:133]
	v_pk_fma_f32 v[222:223], v[194:195], v[70:71], v[132:133]
	v_pk_fma_f32 v[224:225], v[196:197], v[70:71], v[132:133]
	v_pk_fma_f32 v[226:227], v[198:199], v[70:71], v[132:133]
	v_pk_fma_f32 v[220:221], v[194:195], v[72:73], v[220:221]
	v_pk_fma_f32 v[222:223], v[196:197], v[72:73], v[222:223]
	v_pk_fma_f32 v[224:225], v[198:199], v[72:73], v[224:225]
	v_pk_fma_f32 v[226:227], v[200:201], v[72:73], v[226:227]
	v_pk_fma_f32 v[220:221], v[196:197], v[74:75], v[220:221]
	v_pk_fma_f32 v[222:223], v[198:199], v[74:75], v[222:223]
	v_pk_fma_f32 v[224:225], v[200:201], v[74:75], v[224:225]
	v_pk_fma_f32 v[226:227], v[202:203], v[74:75], v[226:227]
	v_pk_fma_f32 v[220:221], v[198:199], v[76:77], v[220:221]
	v_pk_fma_f32 v[222:223], v[200:201], v[76:77], v[222:223]
	v_pk_fma_f32 v[224:225], v[202:203], v[76:77], v[224:225]
	v_pk_fma_f32 v[226:227], v[140:141], v[76:77], v[226:227]
	v_pk_fma_f32 v[220:221], v[200:201], v[78:79], v[220:221]
	v_pk_fma_f32 v[222:223], v[202:203], v[78:79], v[222:223]
	v_pk_fma_f32 v[224:225], v[140:141], v[78:79], v[224:225]
	v_pk_fma_f32 v[226:227], v[142:143], v[78:79], v[226:227]
	v_pk_fma_f32 v[220:221], v[202:203], v[80:81], v[220:221]
	v_pk_fma_f32 v[222:223], v[140:141], v[80:81], v[222:223]
	v_pk_fma_f32 v[224:225], v[142:143], v[80:81], v[224:225]
	v_pk_fma_f32 v[226:227], v[144:145], v[80:81], v[226:227]
	v_pk_fma_f32 v[220:221], v[140:141], v[82:83], v[220:221]
	v_pk_fma_f32 v[222:223], v[142:143], v[82:83], v[222:223]
	v_pk_fma_f32 v[224:225], v[144:145], v[82:83], v[224:225]
	v_pk_fma_f32 v[226:227], v[146:147], v[82:83], v[226:227]
	v_pk_fma_f32 v[220:221], v[142:143], v[84:85], v[220:221]
	v_pk_fma_f32 v[222:223], v[144:145], v[84:85], v[222:223]
	v_pk_fma_f32 v[224:225], v[146:147], v[84:85], v[224:225]
	v_pk_fma_f32 v[226:227], v[148:149], v[84:85], v[226:227]
	v_pk_fma_f32 v[220:221], v[144:145], v[86:87], v[220:221]
	v_pk_fma_f32 v[222:223], v[146:147], v[86:87], v[222:223]
	v_pk_fma_f32 v[224:225], v[148:149], v[86:87], v[224:225]
	v_pk_fma_f32 v[226:227], v[150:151], v[86:87], v[226:227]
	v_pk_fma_f32 v[220:221], v[146:147], v[92:93], v[220:221]
	v_pk_fma_f32 v[222:223], v[148:149], v[92:93], v[222:223]
	v_pk_fma_f32 v[224:225], v[150:151], v[92:93], v[224:225]
	v_pk_fma_f32 v[226:227], v[152:153], v[92:93], v[226:227]
	v_pk_fma_f32 v[220:221], v[148:149], v[94:95], v[220:221]
	v_pk_fma_f32 v[222:223], v[150:151], v[94:95], v[222:223]
	v_pk_fma_f32 v[224:225], v[152:153], v[94:95], v[224:225]
	v_pk_fma_f32 v[226:227], v[154:155], v[94:95], v[226:227]
	v_pk_fma_f32 v[220:221], v[150:151], v[96:97], v[220:221]
	v_pk_fma_f32 v[222:223], v[152:153], v[96:97], v[222:223]
	v_pk_fma_f32 v[224:225], v[154:155], v[96:97], v[224:225]
	v_pk_fma_f32 v[226:227], v[156:157], v[96:97], v[226:227]
	v_pk_fma_f32 v[220:221], v[152:153], v[98:99], v[220:221]
	v_pk_fma_f32 v[222:223], v[154:155], v[98:99], v[222:223]
	v_pk_fma_f32 v[224:225], v[156:157], v[98:99], v[224:225]
	v_pk_fma_f32 v[226:227], v[158:159], v[98:99], v[226:227]
	v_pk_fma_f32 v[220:221], v[154:155], v[100:101], v[220:221]
	v_pk_fma_f32 v[222:223], v[156:157], v[100:101], v[222:223]
	v_pk_fma_f32 v[224:225], v[158:159], v[100:101], v[224:225]
	v_pk_fma_f32 v[226:227], v[160:161], v[100:101], v[226:227]
	v_pk_fma_f32 v[220:221], v[156:157], v[102:103], v[220:221]
	v_pk_fma_f32 v[222:223], v[158:159], v[102:103], v[222:223]
	v_pk_fma_f32 v[224:225], v[160:161], v[102:103], v[224:225]
	v_pk_fma_f32 v[226:227], v[162:163], v[102:103], v[226:227]
	v_pk_fma_f32 v[220:221], v[158:159], v[104:105], v[220:221]
	v_pk_fma_f32 v[222:223], v[160:161], v[104:105], v[222:223]
	v_pk_fma_f32 v[224:225], v[162:163], v[104:105], v[224:225]
	v_pk_fma_f32 v[226:227], v[164:165], v[104:105], v[226:227]
	v_pk_fma_f32 v[220:221], v[160:161], v[106:107], v[220:221]
	v_pk_fma_f32 v[222:223], v[162:163], v[106:107], v[222:223]
	v_pk_fma_f32 v[224:225], v[164:165], v[106:107], v[224:225]
	v_pk_fma_f32 v[226:227], v[166:167], v[106:107], v[226:227]
	v_pk_fma_f32 v[220:221], v[162:163], v[108:109], v[220:221]
	v_pk_fma_f32 v[222:223], v[164:165], v[108:109], v[222:223]
	v_pk_fma_f32 v[224:225], v[166:167], v[108:109], v[224:225]
	v_pk_fma_f32 v[226:227], v[168:169], v[108:109], v[226:227]
	v_pk_fma_f32 v[220:221], v[164:165], v[110:111], v[220:221]
	v_pk_fma_f32 v[222:223], v[166:167], v[110:111], v[222:223]
	v_pk_fma_f32 v[224:225], v[168:169], v[110:111], v[224:225]
	v_pk_fma_f32 v[226:227], v[170:171], v[110:111], v[226:227]
	v_pk_fma_f32 v[220:221], v[166:167], v[112:113], v[220:221]
	v_pk_fma_f32 v[222:223], v[168:169], v[112:113], v[222:223]
	v_pk_fma_f32 v[224:225], v[170:171], v[112:113], v[224:225]
	v_pk_fma_f32 v[226:227], v[42:43], v[112:113], v[226:227]
	v_pk_fma_f32 v[220:221], v[168:169], v[114:115], v[220:221]
	v_pk_fma_f32 v[222:223], v[170:171], v[114:115], v[222:223]
	v_pk_fma_f32 v[224:225], v[42:43], v[114:115], v[224:225]
	v_pk_fma_f32 v[226:227], v[44:45], v[114:115], v[226:227]
	v_pk_fma_f32 v[220:221], v[170:171], v[116:117], v[220:221]
	v_pk_fma_f32 v[222:223], v[42:43], v[116:117], v[222:223]
	v_pk_fma_f32 v[224:225], v[44:45], v[116:117], v[224:225]
	v_pk_fma_f32 v[226:227], v[46:47], v[116:117], v[226:227]
	v_pk_fma_f32 v[220:221], v[42:43], v[118:119], v[220:221]
	v_pk_fma_f32 v[222:223], v[44:45], v[118:119], v[222:223]
	v_pk_fma_f32 v[224:225], v[46:47], v[118:119], v[224:225]
	v_pk_fma_f32 v[226:227], v[48:49], v[118:119], v[226:227]
	v_pk_fma_f32 v[220:221], v[44:45], v[120:121], v[220:221]
	v_pk_fma_f32 v[222:223], v[46:47], v[120:121], v[222:223]
	v_pk_fma_f32 v[224:225], v[48:49], v[120:121], v[224:225]
	v_pk_fma_f32 v[226:227], v[50:51], v[120:121], v[226:227]
	v_pk_fma_f32 v[220:221], v[46:47], v[122:123], v[220:221]
	v_pk_fma_f32 v[222:223], v[48:49], v[122:123], v[222:223]
	v_pk_fma_f32 v[224:225], v[50:51], v[122:123], v[224:225]
	v_pk_fma_f32 v[226:227], v[52:53], v[122:123], v[226:227]
	v_pk_fma_f32 v[220:221], v[48:49], v[124:125], v[220:221]
	v_pk_fma_f32 v[222:223], v[50:51], v[124:125], v[222:223]
	v_pk_fma_f32 v[224:225], v[52:53], v[124:125], v[224:225]
	v_pk_fma_f32 v[226:227], v[54:55], v[124:125], v[226:227]
	v_pk_fma_f32 v[220:221], v[50:51], v[126:127], v[220:221]
	v_pk_fma_f32 v[222:223], v[52:53], v[126:127], v[222:223]
	v_pk_fma_f32 v[224:225], v[54:55], v[126:127], v[224:225]
	v_pk_fma_f32 v[226:227], v[56:57], v[126:127], v[226:227]
	v_pk_fma_f32 v[220:221], v[52:53], v[128:129], v[220:221]
	v_pk_fma_f32 v[222:223], v[54:55], v[128:129], v[222:223]
	v_pk_fma_f32 v[224:225], v[56:57], v[128:129], v[224:225]
	v_pk_fma_f32 v[226:227], v[58:59], v[128:129], v[226:227]
	v_pk_fma_f32 v[220:221], v[54:55], v[130:131], v[220:221]
	v_pk_fma_f32 v[222:223], v[56:57], v[130:131], v[222:223]
	v_pk_fma_f32 v[224:225], v[58:59], v[130:131], v[224:225]
	v_pk_fma_f32 v[226:227], v[60:61], v[130:131], v[226:227]
	v_pk_fma_f32 v[220:221], v[56:57], v[88:89], v[220:221]
	v_pk_fma_f32 v[222:223], v[58:59], v[88:89], v[222:223]
	v_pk_fma_f32 v[224:225], v[60:61], v[88:89], v[224:225]
	v_pk_fma_f32 v[226:227], v[62:63], v[88:89], v[226:227]
	v_pk_fma_f32 v[220:221], v[58:59], v[90:91], v[220:221]
	v_pk_fma_f32 v[222:223], v[60:61], v[90:91], v[222:223]
	v_pk_fma_f32 v[224:225], v[62:63], v[90:91], v[224:225]
	v_pk_fma_f32 v[226:227], v[64:65], v[90:91], v[226:227]
	v_pk_fma_f32 v[228:229], v[200:201], v[70:71], v[132:133]
	v_pk_fma_f32 v[230:231], v[202:203], v[70:71], v[132:133]
	v_pk_fma_f32 v[232:233], v[140:141], v[70:71], v[132:133]
	v_pk_fma_f32 v[234:235], v[142:143], v[70:71], v[132:133]
	v_pk_fma_f32 v[228:229], v[202:203], v[72:73], v[228:229]
	v_pk_fma_f32 v[230:231], v[140:141], v[72:73], v[230:231]
	v_pk_fma_f32 v[232:233], v[142:143], v[72:73], v[232:233]
	v_pk_fma_f32 v[234:235], v[144:145], v[72:73], v[234:235]
	v_pk_fma_f32 v[228:229], v[140:141], v[74:75], v[228:229]
	v_pk_fma_f32 v[230:231], v[142:143], v[74:75], v[230:231]
	v_pk_fma_f32 v[232:233], v[144:145], v[74:75], v[232:233]
	v_pk_fma_f32 v[234:235], v[146:147], v[74:75], v[234:235]
	v_pk_fma_f32 v[228:229], v[142:143], v[76:77], v[228:229]
	v_pk_fma_f32 v[230:231], v[144:145], v[76:77], v[230:231]
	v_pk_fma_f32 v[232:233], v[146:147], v[76:77], v[232:233]
	v_pk_fma_f32 v[234:235], v[148:149], v[76:77], v[234:235]
	v_pk_fma_f32 v[228:229], v[144:145], v[78:79], v[228:229]
	v_pk_fma_f32 v[230:231], v[146:147], v[78:79], v[230:231]
	v_pk_fma_f32 v[232:233], v[148:149], v[78:79], v[232:233]
	v_pk_fma_f32 v[234:235], v[150:151], v[78:79], v[234:235]
	v_pk_fma_f32 v[228:229], v[146:147], v[80:81], v[228:229]
	v_pk_fma_f32 v[230:231], v[148:149], v[80:81], v[230:231]
	v_pk_fma_f32 v[232:233], v[150:151], v[80:81], v[232:233]
	v_pk_fma_f32 v[234:235], v[152:153], v[80:81], v[234:235]
	v_pk_fma_f32 v[228:229], v[148:149], v[82:83], v[228:229]
	v_pk_fma_f32 v[230:231], v[150:151], v[82:83], v[230:231]
	v_pk_fma_f32 v[232:233], v[152:153], v[82:83], v[232:233]
	v_pk_fma_f32 v[234:235], v[154:155], v[82:83], v[234:235]
	v_pk_fma_f32 v[228:229], v[150:151], v[84:85], v[228:229]
	v_pk_fma_f32 v[230:231], v[152:153], v[84:85], v[230:231]
	v_pk_fma_f32 v[232:233], v[154:155], v[84:85], v[232:233]
	v_pk_fma_f32 v[234:235], v[156:157], v[84:85], v[234:235]
	v_pk_fma_f32 v[228:229], v[152:153], v[86:87], v[228:229]
	v_pk_fma_f32 v[230:231], v[154:155], v[86:87], v[230:231]
	v_pk_fma_f32 v[232:233], v[156:157], v[86:87], v[232:233]
	v_pk_fma_f32 v[234:235], v[158:159], v[86:87], v[234:235]
	v_pk_fma_f32 v[228:229], v[154:155], v[92:93], v[228:229]
	v_pk_fma_f32 v[230:231], v[156:157], v[92:93], v[230:231]
	v_pk_fma_f32 v[232:233], v[158:159], v[92:93], v[232:233]
	v_pk_fma_f32 v[234:235], v[160:161], v[92:93], v[234:235]
	v_pk_fma_f32 v[228:229], v[156:157], v[94:95], v[228:229]
	v_pk_fma_f32 v[230:231], v[158:159], v[94:95], v[230:231]
	v_pk_fma_f32 v[232:233], v[160:161], v[94:95], v[232:233]
	v_pk_fma_f32 v[234:235], v[162:163], v[94:95], v[234:235]
	v_pk_fma_f32 v[228:229], v[158:159], v[96:97], v[228:229]
	v_pk_fma_f32 v[230:231], v[160:161], v[96:97], v[230:231]
	v_pk_fma_f32 v[232:233], v[162:163], v[96:97], v[232:233]
	v_pk_fma_f32 v[234:235], v[164:165], v[96:97], v[234:235]
	v_pk_fma_f32 v[228:229], v[160:161], v[98:99], v[228:229]
	v_pk_fma_f32 v[230:231], v[162:163], v[98:99], v[230:231]
	v_pk_fma_f32 v[232:233], v[164:165], v[98:99], v[232:233]
	v_pk_fma_f32 v[234:235], v[166:167], v[98:99], v[234:235]
	v_pk_fma_f32 v[228:229], v[162:163], v[100:101], v[228:229]
	v_pk_fma_f32 v[230:231], v[164:165], v[100:101], v[230:231]
	v_pk_fma_f32 v[232:233], v[166:167], v[100:101], v[232:233]
	v_pk_fma_f32 v[234:235], v[168:169], v[100:101], v[234:235]
	v_pk_fma_f32 v[228:229], v[164:165], v[102:103], v[228:229]
	v_pk_fma_f32 v[230:231], v[166:167], v[102:103], v[230:231]
	v_pk_fma_f32 v[232:233], v[168:169], v[102:103], v[232:233]
	v_pk_fma_f32 v[234:235], v[170:171], v[102:103], v[234:235]
	v_pk_fma_f32 v[228:229], v[166:167], v[104:105], v[228:229]
	v_pk_fma_f32 v[230:231], v[168:169], v[104:105], v[230:231]
	v_pk_fma_f32 v[232:233], v[170:171], v[104:105], v[232:233]
	v_pk_fma_f32 v[234:235], v[42:43], v[104:105], v[234:235]
	v_pk_fma_f32 v[228:229], v[168:169], v[106:107], v[228:229]
	v_pk_fma_f32 v[230:231], v[170:171], v[106:107], v[230:231]
	v_pk_fma_f32 v[232:233], v[42:43], v[106:107], v[232:233]
	v_pk_fma_f32 v[234:235], v[44:45], v[106:107], v[234:235]
	v_pk_fma_f32 v[228:229], v[170:171], v[108:109], v[228:229]
	v_pk_fma_f32 v[230:231], v[42:43], v[108:109], v[230:231]
	v_pk_fma_f32 v[232:233], v[44:45], v[108:109], v[232:233]
	v_pk_fma_f32 v[234:235], v[46:47], v[108:109], v[234:235]
	v_pk_fma_f32 v[228:229], v[42:43], v[110:111], v[228:229]
	v_pk_fma_f32 v[230:231], v[44:45], v[110:111], v[230:231]
	v_pk_fma_f32 v[232:233], v[46:47], v[110:111], v[232:233]
	v_pk_fma_f32 v[234:235], v[48:49], v[110:111], v[234:235]
	v_pk_fma_f32 v[228:229], v[44:45], v[112:113], v[228:229]
	v_pk_fma_f32 v[230:231], v[46:47], v[112:113], v[230:231]
	v_pk_fma_f32 v[232:233], v[48:49], v[112:113], v[232:233]
	v_pk_fma_f32 v[234:235], v[50:51], v[112:113], v[234:235]
	v_pk_fma_f32 v[228:229], v[46:47], v[114:115], v[228:229]
	v_pk_fma_f32 v[230:231], v[48:49], v[114:115], v[230:231]
	v_pk_fma_f32 v[232:233], v[50:51], v[114:115], v[232:233]
	v_pk_fma_f32 v[234:235], v[52:53], v[114:115], v[234:235]
	v_pk_fma_f32 v[228:229], v[48:49], v[116:117], v[228:229]
	v_pk_fma_f32 v[230:231], v[50:51], v[116:117], v[230:231]
	v_pk_fma_f32 v[232:233], v[52:53], v[116:117], v[232:233]
	v_pk_fma_f32 v[234:235], v[54:55], v[116:117], v[234:235]
	v_pk_fma_f32 v[228:229], v[50:51], v[118:119], v[228:229]
	v_pk_fma_f32 v[230:231], v[52:53], v[118:119], v[230:231]
	v_pk_fma_f32 v[232:233], v[54:55], v[118:119], v[232:233]
	v_pk_fma_f32 v[234:235], v[56:57], v[118:119], v[234:235]
	v_pk_fma_f32 v[228:229], v[52:53], v[120:121], v[228:229]
	v_pk_fma_f32 v[230:231], v[54:55], v[120:121], v[230:231]
	v_pk_fma_f32 v[232:233], v[56:57], v[120:121], v[232:233]
	v_pk_fma_f32 v[234:235], v[58:59], v[120:121], v[234:235]
	v_pk_fma_f32 v[228:229], v[54:55], v[122:123], v[228:229]
	v_pk_fma_f32 v[230:231], v[56:57], v[122:123], v[230:231]
	v_pk_fma_f32 v[232:233], v[58:59], v[122:123], v[232:233]
	v_pk_fma_f32 v[234:235], v[60:61], v[122:123], v[234:235]
	v_pk_fma_f32 v[228:229], v[56:57], v[124:125], v[228:229]
	v_pk_fma_f32 v[230:231], v[58:59], v[124:125], v[230:231]
	v_pk_fma_f32 v[232:233], v[60:61], v[124:125], v[232:233]
	v_pk_fma_f32 v[234:235], v[62:63], v[124:125], v[234:235]
	v_pk_fma_f32 v[228:229], v[58:59], v[126:127], v[228:229]
	v_pk_fma_f32 v[230:231], v[60:61], v[126:127], v[230:231]
	v_pk_fma_f32 v[232:233], v[62:63], v[126:127], v[232:233]
	v_pk_fma_f32 v[234:235], v[64:65], v[126:127], v[234:235]
	v_pk_fma_f32 v[228:229], v[60:61], v[128:129], v[228:229]
	v_pk_fma_f32 v[230:231], v[62:63], v[128:129], v[230:231]
	v_pk_fma_f32 v[232:233], v[64:65], v[128:129], v[232:233]
	v_pk_fma_f32 v[234:235], v[66:67], v[128:129], v[234:235]
	v_pk_fma_f32 v[228:229], v[62:63], v[130:131], v[228:229]
	v_pk_fma_f32 v[230:231], v[64:65], v[130:131], v[230:231]
	v_pk_fma_f32 v[232:233], v[66:67], v[130:131], v[232:233]
	v_pk_fma_f32 v[234:235], v[68:69], v[130:131], v[234:235]
	v_pk_fma_f32 v[228:229], v[64:65], v[88:89], v[228:229]
	v_pk_fma_f32 v[230:231], v[66:67], v[88:89], v[230:231]
	v_pk_fma_f32 v[232:233], v[68:69], v[88:89], v[232:233]
	v_pk_fma_f32 v[234:235], v[236:237], v[88:89], v[234:235]
	v_pk_fma_f32 v[228:229], v[66:67], v[90:91], v[228:229]
	v_pk_fma_f32 v[230:231], v[68:69], v[90:91], v[230:231]
	v_pk_fma_f32 v[232:233], v[236:237], v[90:91], v[232:233]
	v_pk_fma_f32 v[234:235], v[238:239], v[90:91], v[234:235]
.Lp2_nofma_1:
	v_mov_b64_e32 v[172:173], v[42:43]
	v_mov_b64_e32 v[174:175], v[44:45]
	v_mov_b64_e32 v[176:177], v[46:47]
	v_mov_b64_e32 v[178:179], v[48:49]
	v_mov_b64_e32 v[180:181], v[50:51]
	v_mov_b64_e32 v[182:183], v[52:53]
	v_mov_b64_e32 v[184:185], v[54:55]
	v_mov_b64_e32 v[186:187], v[56:57]
	v_mov_b64_e32 v[188:189], v[58:59]
	v_mov_b64_e32 v[190:191], v[60:61]
	v_mov_b64_e32 v[192:193], v[62:63]
	v_mov_b64_e32 v[194:195], v[64:65]
	v_mov_b64_e32 v[196:197], v[66:67]
	v_mov_b64_e32 v[198:199], v[68:69]
	v_mov_b64_e32 v[200:201], v[236:237]
	v_mov_b64_e32 v[202:203], v[238:239]
	s_cmp_lt_i32 s33, 0
	s_cbranch_scc1 .Lp2_skip_1
	v_add_f32_e32 v42, v204, v205
	v_mul_f32_e32 v43, v204, v204
	v_add_f32_e32 v44, v206, v207
	v_mul_f32_e32 v45, v206, v206
	v_add_f32_e32 v46, v208, v209
	v_mul_f32_e32 v47, v208, v208
	v_add_f32_e32 v48, v210, v211
	v_mul_f32_e32 v49, v210, v210
	v_add_f32_e32 v50, v212, v213
	v_mul_f32_e32 v51, v212, v212
	v_add_f32_e32 v52, v214, v215
	v_mul_f32_e32 v53, v214, v214
	v_add_f32_e32 v54, v216, v217
	v_mul_f32_e32 v55, v216, v216
	v_add_f32_e32 v56, v218, v219
	v_mul_f32_e32 v57, v218, v218
	v_add_f32_e32 v58, v220, v221
	v_mul_f32_e32 v59, v220, v220
	v_add_f32_e32 v60, v222, v223
	v_mul_f32_e32 v61, v222, v222
	v_add_f32_e32 v62, v224, v225
	v_mul_f32_e32 v63, v224, v224
	v_add_f32_e32 v64, v226, v227
	v_mul_f32_e32 v65, v226, v226
	v_add_f32_e32 v66, v228, v229
	v_mul_f32_e32 v67, v228, v228
	v_add_f32_e32 v68, v230, v231
	v_mul_f32_e32 v69, v230, v230
	v_add_f32_e32 v236, v232, v233
	v_mul_f32_e32 v237, v232, v232
	v_add_f32_e32 v238, v234, v235
	v_mul_f32_e32 v239, v234, v234
	v_fmac_f32_e32 v43, v205, v205
	v_fmac_f32_e32 v45, v207, v207
	v_fmac_f32_e32 v47, v209, v209
	v_fmac_f32_e32 v49, v211, v211
	v_fmac_f32_e32 v51, v213, v213
	v_fmac_f32_e32 v53, v215, v215
	v_fmac_f32_e32 v55, v217, v217
	v_fmac_f32_e32 v57, v219, v219
	v_fmac_f32_e32 v59, v221, v221
	v_fmac_f32_e32 v61, v223, v223
	v_fmac_f32_e32 v63, v225, v225
	v_fmac_f32_e32 v65, v227, v227
	v_fmac_f32_e32 v67, v229, v229
	v_fmac_f32_e32 v69, v231, v231
	v_fmac_f32_e32 v237, v233, v233
	v_fmac_f32_e32 v239, v235, v235
	v_permlane32_swap_b32_e32 v42, v58
	v_permlane32_swap_b32_e32 v43, v59
	v_permlane32_swap_b32_e32 v44, v60
	v_permlane32_swap_b32_e32 v45, v61
	v_permlane32_swap_b32_e32 v46, v62
	v_permlane32_swap_b32_e32 v47, v63
	v_permlane32_swap_b32_e32 v48, v64
	v_permlane32_swap_b32_e32 v49, v65
	v_permlane32_swap_b32_e32 v50, v66
	v_permlane32_swap_b32_e32 v51, v67
	v_permlane32_swap_b32_e32 v52, v68
	v_permlane32_swap_b32_e32 v53, v69
	v_permlane32_swap_b32_e32 v54, v236
	v_permlane32_swap_b32_e32 v55, v237
	v_permlane32_swap_b32_e32 v56, v238
	v_permlane32_swap_b32_e32 v57, v239
	v_add_f32_e32 v42, v42, v58
	v_add_f32_e32 v43, v43, v59
	v_add_f32_e32 v44, v44, v60
	v_add_f32_e32 v45, v45, v61
	v_add_f32_e32 v46, v46, v62
	v_add_f32_e32 v47, v47, v63
	v_add_f32_e32 v48, v48, v64
	v_add_f32_e32 v49, v49, v65
	v_add_f32_e32 v50, v50, v66
	v_add_f32_e32 v51, v51, v67
	v_add_f32_e32 v52, v52, v68
	v_add_f32_e32 v53, v53, v69
	v_add_f32_e32 v54, v54, v236
	v_add_f32_e32 v55, v55, v237
	v_add_f32_e32 v56, v56, v238
	v_add_f32_e32 v57, v57, v239
	v_permlane16_swap_b32_e32 v42, v50
	v_permlane16_swap_b32_e32 v43, v51
	v_permlane16_swap_b32_e32 v44, v52
	v_permlane16_swap_b32_e32 v45, v53
	v_permlane16_swap_b32_e32 v46, v54
	v_permlane16_swap_b32_e32 v47, v55
	v_permlane16_swap_b32_e32 v48, v56
	v_permlane16_swap_b32_e32 v49, v57
	v_add_f32_e32 v42, v42, v50
	v_add_f32_e32 v43, v43, v51
	v_add_f32_e32 v44, v44, v52
	v_add_f32_e32 v45, v45, v53
	v_add_f32_e32 v46, v46, v54
	v_add_f32_e32 v47, v47, v55
	v_add_f32_e32 v48, v48, v56
	v_add_f32_e32 v49, v49, v57
	v_add_f32_dpp v42, v42, v42 row_ror:8 row_mask:0xf bank_mask:0xf
	v_add_f32_dpp v43, v43, v43 row_ror:8 row_mask:0xf bank_mask:0xf
	v_add_f32_dpp v44, v44, v44 row_ror:8 row_mask:0xf bank_mask:0xf
	v_add_f32_dpp v45, v45, v45 row_ror:8 row_mask:0xf bank_mask:0xf
	v_add_f32_dpp v46, v46, v46 row_ror:8 row_mask:0xf bank_mask:0xf
	v_add_f32_dpp v47, v47, v47 row_ror:8 row_mask:0xf bank_mask:0xf
	v_add_f32_dpp v48, v48, v48 row_ror:8 row_mask:0xf bank_mask:0xf
	v_add_f32_dpp v49, v49, v49 row_ror:8 row_mask:0xf bank_mask:0xf
	v_add_f32_dpp v42, v42, v42 row_ror:4 row_mask:0xf bank_mask:0xf
	v_add_f32_dpp v43, v43, v43 row_ror:4 row_mask:0xf bank_mask:0xf
	v_add_f32_dpp v44, v44, v44 row_ror:4 row_mask:0xf bank_mask:0xf
	v_add_f32_dpp v45, v45, v45 row_ror:4 row_mask:0xf bank_mask:0xf
	v_add_f32_dpp v46, v46, v46 row_ror:4 row_mask:0xf bank_mask:0xf
	v_add_f32_dpp v47, v47, v47 row_ror:4 row_mask:0xf bank_mask:0xf
	v_add_f32_dpp v48, v48, v48 row_ror:4 row_mask:0xf bank_mask:0xf
	v_add_f32_dpp v49, v49, v49 row_ror:4 row_mask:0xf bank_mask:0xf
	v_add_f32_dpp v42, v42, v42 row_ror:2 row_mask:0xf bank_mask:0xf
	v_add_f32_dpp v43, v43, v43 row_ror:2 row_mask:0xf bank_mask:0xf
	v_add_f32_dpp v44, v44, v44 row_ror:2 row_mask:0xf bank_mask:0xf
	v_add_f32_dpp v45, v45, v45 row_ror:2 row_mask:0xf bank_mask:0xf
	v_add_f32_dpp v46, v46, v46 row_ror:2 row_mask:0xf bank_mask:0xf
	v_add_f32_dpp v47, v47, v47 row_ror:2 row_mask:0xf bank_mask:0xf
	v_add_f32_dpp v48, v48, v48 row_ror:2 row_mask:0xf bank_mask:0xf
	v_add_f32_dpp v49, v49, v49 row_ror:2 row_mask:0xf bank_mask:0xf
	v_add_f32_dpp v42, v42, v42 row_ror:1 row_mask:0xf bank_mask:0xf
	v_add_f32_dpp v43, v43, v43 row_ror:1 row_mask:0xf bank_mask:0xf
	v_add_f32_dpp v44, v44, v44 row_ror:1 row_mask:0xf bank_mask:0xf
	v_add_f32_dpp v45, v45, v45 row_ror:1 row_mask:0xf bank_mask:0xf
	v_add_f32_dpp v46, v46, v46 row_ror:1 row_mask:0xf bank_mask:0xf
	v_add_f32_dpp v47, v47, v47 row_ror:1 row_mask:0xf bank_mask:0xf
	v_add_f32_dpp v48, v48, v48 row_ror:1 row_mask:0xf bank_mask:0xf
	v_add_f32_dpp v49, v49, v49 row_ror:1 row_mask:0xf bank_mask:0xf
	s_mov_b32 exec_lo, 0x10001
	s_mov_b32 exec_hi, 0x10001
	ds_write_b64 v252, v[42:43] offset:1024
	ds_write_b64 v252, v[44:45] offset:1088
	ds_write_b64 v252, v[46:47] offset:1152
	ds_write_b64 v252, v[48:49] offset:1216
	s_mov_b64 exec, -1
	s_waitcnt lgkmcnt(0)
	s_barrier
	ds_read_b128 v[50:53], v253 offset:1024
	ds_read_b128 v[54:57], v253 offset:1040
	ds_read_b128 v[58:61], v253 offset:1056
	ds_read_b128 v[62:65], v253 offset:1072
	s_mov_b32 s66, 0x3a800000
	s_waitcnt lgkmcnt(0)
	v_add_f32_e32 v242, v50, v52
	v_add_f32_e32 v243, v51, v53
	v_add_f32_e32 v240, 0, v242
	v_add_f32_e32 v241, 0, v243
	v_add_f32_e32 v242, v54, v56
	v_add_f32_e32 v243, v55, v57
	v_add_f32_e32 v240, v240, v242
	v_add_f32_e32 v241, v241, v243
	v_add_f32_e32 v242, v58, v60
	v_add_f32_e32 v243, v59, v61
	v_add_f32_e32 v240, v240, v242
	v_add_f32_e32 v241, v241, v243
	v_add_f32_e32 v242, v62, v64
	v_add_f32_e32 v243, v63, v65
	v_add_f32_e32 v240, v240, v242
	v_add_f32_e32 v241, v241, v243
	v_mul_f32_e32 v244, 0x3a800000, v240
	v_mul_f32_e32 v245, v244, v244
	v_fma_f32 v246, v241, s66, -v245
	v_max_f32_e32 v246, 0, v246
	v_add_f32_e32 v246, 0x358637bd, v246
	v_rsq_f32_e32 v247, v246
	s_nop 0
	v_readlane_b32 s34, v244, 0
	v_readlane_b32 s35, v244, 1
	v_readlane_b32 s36, v244, 2
	v_readlane_b32 s37, v244, 3
	v_readlane_b32 s38, v244, 4
	v_readlane_b32 s39, v244, 5
	v_readlane_b32 s40, v244, 6
	v_readlane_b32 s41, v244, 7
	v_readlane_b32 s42, v244, 8
	v_readlane_b32 s43, v244, 9
	v_readlane_b32 s44, v244, 10
	v_readlane_b32 s45, v244, 11
	v_readlane_b32 s46, v244, 12
	v_readlane_b32 s47, v244, 13
	v_readlane_b32 s48, v244, 14
	v_readlane_b32 s49, v244, 15
	v_readlane_b32 s50, v247, 0
	v_readlane_b32 s51, v247, 1
	v_readlane_b32 s52, v247, 2
	v_readlane_b32 s53, v247, 3
	v_readlane_b32 s54, v247, 4
	v_readlane_b32 s55, v247, 5
	v_readlane_b32 s56, v247, 6
	v_readlane_b32 s57, v247, 7
	v_readlane_b32 s58, v247, 8
	v_readlane_b32 s59, v247, 9
	v_readlane_b32 s60, v247, 10
	v_readlane_b32 s61, v247, 11
	v_readlane_b32 s62, v247, 12
	v_readlane_b32 s63, v247, 13
	v_readlane_b32 s64, v247, 14
	v_readlane_b32 s65, v247, 15
	s_add_i32 s6, s28, 16
	s_lshl_b32 s6, s6, 12
	s_add_u32 s98, s16, s6
	s_addc_u32 s99, s17, 0
	s_add_u32 s98, s98, 0x23000000
	s_addc_u32 s99, s99, 0
	v_subrev_f32_e32 v50, s34, v204
	v_subrev_f32_e32 v51, s34, v205
	v_subrev_f32_e32 v54, s35, v206
	v_subrev_f32_e32 v55, s35, v207
	v_subrev_f32_e32 v58, s36, v208
	v_subrev_f32_e32 v59, s36, v209
	v_subrev_f32_e32 v62, s37, v210
	v_subrev_f32_e32 v63, s37, v211
	v_mul_f32_e32 v50, s50, v50
	v_mul_f32_e32 v51, s50, v51
	v_mul_f32_e32 v54, s51, v54
	v_mul_f32_e32 v55, s51, v55
	v_mul_f32_e32 v58, s52, v58
	v_mul_f32_e32 v59, s52, v59
	v_mul_f32_e32 v62, s53, v62
	v_mul_f32_e32 v63, s53, v63
	v_fma_f32 v50, v134, v50, v136
	v_fma_f32 v51, v135, v51, v137
	v_fma_f32 v54, v134, v54, v136
	v_fma_f32 v55, v135, v55, v137
	v_fma_f32 v58, v134, v58, v136
	v_fma_f32 v59, v135, v59, v137
	v_fma_f32 v62, v134, v62, v136
	v_fma_f32 v63, v135, v63, v137
	v_mul_f32_e32 v52, 0xbfb8aa3b, v50
	v_mul_f32_e32 v53, 0xbfb8aa3b, v51
	v_mul_f32_e32 v56, 0xbfb8aa3b, v54
	v_mul_f32_e32 v57, 0xbfb8aa3b, v55
	v_mul_f32_e32 v60, 0xbfb8aa3b, v58
	v_mul_f32_e32 v61, 0xbfb8aa3b, v59
	v_mul_f32_e32 v64, 0xbfb8aa3b, v62
	v_mul_f32_e32 v65, 0xbfb8aa3b, v63
	v_exp_f32_e32 v52, v52
	v_exp_f32_e32 v53, v53
	v_exp_f32_e32 v56, v56
	v_exp_f32_e32 v57, v57
	v_exp_f32_e32 v60, v60
	v_exp_f32_e32 v61, v61
	v_exp_f32_e32 v64, v64
	v_exp_f32_e32 v65, v65
	v_add_f32_e32 v52, 1.0, v52
	v_add_f32_e32 v53, 1.0, v53
	v_add_f32_e32 v56, 1.0, v56
	v_add_f32_e32 v57, 1.0, v57
	v_add_f32_e32 v60, 1.0, v60
	v_add_f32_e32 v61, 1.0, v61
	v_add_f32_e32 v64, 1.0, v64
	v_add_f32_e32 v65, 1.0, v65
	v_rcp_f32_e32 v52, v52
	v_rcp_f32_e32 v53, v53
	v_rcp_f32_e32 v56, v56
	v_rcp_f32_e32 v57, v57
	v_rcp_f32_e32 v60, v60
	v_rcp_f32_e32 v61, v61
	v_rcp_f32_e32 v64, v64
	v_rcp_f32_e32 v65, v65
	s_nop 0
	v_mul_f32_e32 v50, v50, v52
	v_mul_f32_e32 v51, v51, v53
	v_mul_f32_e32 v54, v54, v56
	v_mul_f32_e32 v55, v55, v57
	v_mul_f32_e32 v58, v58, v60
	v_mul_f32_e32 v59, v59, v61
	v_mul_f32_e32 v62, v62, v64
	v_mul_f32_e32 v63, v63, v65
	v_cvt_pk_bf16_f32 v52, v50, v51
	v_cvt_pk_bf16_f32 v56, v54, v55
	v_cvt_pk_bf16_f32 v60, v58, v59
	v_cvt_pk_bf16_f32 v64, v62, v63
	global_store_dword v251, v52, s[98:99] offset:2048
	s_add_u32 s98, s98, 0x1000
	s_addc_u32 s99, s99, 0
	global_store_dword v251, v56, s[98:99] offset:2048
	s_add_u32 s98, s98, 0x1000
	s_addc_u32 s99, s99, 0
	global_store_dword v251, v60, s[98:99] offset:2048
	s_add_u32 s98, s98, 0x1000
	s_addc_u32 s99, s99, 0
	global_store_dword v251, v64, s[98:99] offset:2048
	s_add_u32 s98, s98, 0x1000
	s_addc_u32 s99, s99, 0
	v_subrev_f32_e32 v50, s38, v212
	v_subrev_f32_e32 v51, s38, v213
	v_subrev_f32_e32 v54, s39, v214
	v_subrev_f32_e32 v55, s39, v215
	v_subrev_f32_e32 v58, s40, v216
	v_subrev_f32_e32 v59, s40, v217
	v_subrev_f32_e32 v62, s41, v218
	v_subrev_f32_e32 v63, s41, v219
	v_mul_f32_e32 v50, s54, v50
	v_mul_f32_e32 v51, s54, v51
	v_mul_f32_e32 v54, s55, v54
	v_mul_f32_e32 v55, s55, v55
	v_mul_f32_e32 v58, s56, v58
	v_mul_f32_e32 v59, s56, v59
	v_mul_f32_e32 v62, s57, v62
	v_mul_f32_e32 v63, s57, v63
	v_fma_f32 v50, v134, v50, v136
	v_fma_f32 v51, v135, v51, v137
	v_fma_f32 v54, v134, v54, v136
	v_fma_f32 v55, v135, v55, v137
	v_fma_f32 v58, v134, v58, v136
	v_fma_f32 v59, v135, v59, v137
	v_fma_f32 v62, v134, v62, v136
	v_fma_f32 v63, v135, v63, v137
	v_mul_f32_e32 v52, 0xbfb8aa3b, v50
	v_mul_f32_e32 v53, 0xbfb8aa3b, v51
	v_mul_f32_e32 v56, 0xbfb8aa3b, v54
	v_mul_f32_e32 v57, 0xbfb8aa3b, v55
	v_mul_f32_e32 v60, 0xbfb8aa3b, v58
	v_mul_f32_e32 v61, 0xbfb8aa3b, v59
	v_mul_f32_e32 v64, 0xbfb8aa3b, v62
	v_mul_f32_e32 v65, 0xbfb8aa3b, v63
	v_exp_f32_e32 v52, v52
	v_exp_f32_e32 v53, v53
	v_exp_f32_e32 v56, v56
	v_exp_f32_e32 v57, v57
	v_exp_f32_e32 v60, v60
	v_exp_f32_e32 v61, v61
	v_exp_f32_e32 v64, v64
	v_exp_f32_e32 v65, v65
	v_add_f32_e32 v52, 1.0, v52
	v_add_f32_e32 v53, 1.0, v53
	v_add_f32_e32 v56, 1.0, v56
	v_add_f32_e32 v57, 1.0, v57
	v_add_f32_e32 v60, 1.0, v60
	v_add_f32_e32 v61, 1.0, v61
	v_add_f32_e32 v64, 1.0, v64
	v_add_f32_e32 v65, 1.0, v65
	v_rcp_f32_e32 v52, v52
	v_rcp_f32_e32 v53, v53
	v_rcp_f32_e32 v56, v56
	v_rcp_f32_e32 v57, v57
	v_rcp_f32_e32 v60, v60
	v_rcp_f32_e32 v61, v61
	v_rcp_f32_e32 v64, v64
	v_rcp_f32_e32 v65, v65
	s_nop 0
	v_mul_f32_e32 v50, v50, v52
	v_mul_f32_e32 v51, v51, v53
	v_mul_f32_e32 v54, v54, v56
	v_mul_f32_e32 v55, v55, v57
	v_mul_f32_e32 v58, v58, v60
	v_mul_f32_e32 v59, v59, v61
	v_mul_f32_e32 v62, v62, v64
	v_mul_f32_e32 v63, v63, v65
	v_cvt_pk_bf16_f32 v52, v50, v51
	v_cvt_pk_bf16_f32 v56, v54, v55
	v_cvt_pk_bf16_f32 v60, v58, v59
	v_cvt_pk_bf16_f32 v64, v62, v63
	global_store_dword v251, v52, s[98:99] offset:2048
	s_add_u32 s98, s98, 0x1000
	s_addc_u32 s99, s99, 0
	global_store_dword v251, v56, s[98:99] offset:2048
	s_add_u32 s98, s98, 0x1000
	s_addc_u32 s99, s99, 0
	global_store_dword v251, v60, s[98:99] offset:2048
	s_add_u32 s98, s98, 0x1000
	s_addc_u32 s99, s99, 0
	global_store_dword v251, v64, s[98:99] offset:2048
	s_add_u32 s98, s98, 0x1000
	s_addc_u32 s99, s99, 0
	v_subrev_f32_e32 v50, s42, v220
	v_subrev_f32_e32 v51, s42, v221
	v_subrev_f32_e32 v54, s43, v222
	v_subrev_f32_e32 v55, s43, v223
	v_subrev_f32_e32 v58, s44, v224
	v_subrev_f32_e32 v59, s44, v225
	v_subrev_f32_e32 v62, s45, v226
	v_subrev_f32_e32 v63, s45, v227
	v_mul_f32_e32 v50, s58, v50
	v_mul_f32_e32 v51, s58, v51
	v_mul_f32_e32 v54, s59, v54
	v_mul_f32_e32 v55, s59, v55
	v_mul_f32_e32 v58, s60, v58
	v_mul_f32_e32 v59, s60, v59
	v_mul_f32_e32 v62, s61, v62
	v_mul_f32_e32 v63, s61, v63
	v_fma_f32 v50, v134, v50, v136
	v_fma_f32 v51, v135, v51, v137
	v_fma_f32 v54, v134, v54, v136
	v_fma_f32 v55, v135, v55, v137
	v_fma_f32 v58, v134, v58, v136
	v_fma_f32 v59, v135, v59, v137
	v_fma_f32 v62, v134, v62, v136
	v_fma_f32 v63, v135, v63, v137
	v_mul_f32_e32 v52, 0xbfb8aa3b, v50
	v_mul_f32_e32 v53, 0xbfb8aa3b, v51
	v_mul_f32_e32 v56, 0xbfb8aa3b, v54
	v_mul_f32_e32 v57, 0xbfb8aa3b, v55
	v_mul_f32_e32 v60, 0xbfb8aa3b, v58
	v_mul_f32_e32 v61, 0xbfb8aa3b, v59
	v_mul_f32_e32 v64, 0xbfb8aa3b, v62
	v_mul_f32_e32 v65, 0xbfb8aa3b, v63
	v_exp_f32_e32 v52, v52
	v_exp_f32_e32 v53, v53
	v_exp_f32_e32 v56, v56
	v_exp_f32_e32 v57, v57
	v_exp_f32_e32 v60, v60
	v_exp_f32_e32 v61, v61
	v_exp_f32_e32 v64, v64
	v_exp_f32_e32 v65, v65
	v_add_f32_e32 v52, 1.0, v52
	v_add_f32_e32 v53, 1.0, v53
	v_add_f32_e32 v56, 1.0, v56
	v_add_f32_e32 v57, 1.0, v57
	v_add_f32_e32 v60, 1.0, v60
	v_add_f32_e32 v61, 1.0, v61
	v_add_f32_e32 v64, 1.0, v64
	v_add_f32_e32 v65, 1.0, v65
	v_rcp_f32_e32 v52, v52
	v_rcp_f32_e32 v53, v53
	v_rcp_f32_e32 v56, v56
	v_rcp_f32_e32 v57, v57
	v_rcp_f32_e32 v60, v60
	v_rcp_f32_e32 v61, v61
	v_rcp_f32_e32 v64, v64
	v_rcp_f32_e32 v65, v65
	s_nop 0
	v_mul_f32_e32 v50, v50, v52
	v_mul_f32_e32 v51, v51, v53
	v_mul_f32_e32 v54, v54, v56
	v_mul_f32_e32 v55, v55, v57
	v_mul_f32_e32 v58, v58, v60
	v_mul_f32_e32 v59, v59, v61
	v_mul_f32_e32 v62, v62, v64
	v_mul_f32_e32 v63, v63, v65
	v_cvt_pk_bf16_f32 v52, v50, v51
	v_cvt_pk_bf16_f32 v56, v54, v55
	v_cvt_pk_bf16_f32 v60, v58, v59
	v_cvt_pk_bf16_f32 v64, v62, v63
	global_store_dword v251, v52, s[98:99] offset:2048
	s_add_u32 s98, s98, 0x1000
	s_addc_u32 s99, s99, 0
	global_store_dword v251, v56, s[98:99] offset:2048
	s_add_u32 s98, s98, 0x1000
	s_addc_u32 s99, s99, 0
	global_store_dword v251, v60, s[98:99] offset:2048
	s_add_u32 s98, s98, 0x1000
	s_addc_u32 s99, s99, 0
	global_store_dword v251, v64, s[98:99] offset:2048
	s_add_u32 s98, s98, 0x1000
	s_addc_u32 s99, s99, 0
	v_subrev_f32_e32 v50, s46, v228
	v_subrev_f32_e32 v51, s46, v229
	v_subrev_f32_e32 v54, s47, v230
	v_subrev_f32_e32 v55, s47, v231
	v_subrev_f32_e32 v58, s48, v232
	v_subrev_f32_e32 v59, s48, v233
	v_subrev_f32_e32 v62, s49, v234
	v_subrev_f32_e32 v63, s49, v235
	v_mul_f32_e32 v50, s62, v50
	v_mul_f32_e32 v51, s62, v51
	v_mul_f32_e32 v54, s63, v54
	v_mul_f32_e32 v55, s63, v55
	v_mul_f32_e32 v58, s64, v58
	v_mul_f32_e32 v59, s64, v59
	v_mul_f32_e32 v62, s65, v62
	v_mul_f32_e32 v63, s65, v63
	v_fma_f32 v50, v134, v50, v136
	v_fma_f32 v51, v135, v51, v137
	v_fma_f32 v54, v134, v54, v136
	v_fma_f32 v55, v135, v55, v137
	v_fma_f32 v58, v134, v58, v136
	v_fma_f32 v59, v135, v59, v137
	v_fma_f32 v62, v134, v62, v136
	v_fma_f32 v63, v135, v63, v137
	v_mul_f32_e32 v52, 0xbfb8aa3b, v50
	v_mul_f32_e32 v53, 0xbfb8aa3b, v51
	v_mul_f32_e32 v56, 0xbfb8aa3b, v54
	v_mul_f32_e32 v57, 0xbfb8aa3b, v55
	v_mul_f32_e32 v60, 0xbfb8aa3b, v58
	v_mul_f32_e32 v61, 0xbfb8aa3b, v59
	v_mul_f32_e32 v64, 0xbfb8aa3b, v62
	v_mul_f32_e32 v65, 0xbfb8aa3b, v63
	v_exp_f32_e32 v52, v52
	v_exp_f32_e32 v53, v53
	v_exp_f32_e32 v56, v56
	v_exp_f32_e32 v57, v57
	v_exp_f32_e32 v60, v60
	v_exp_f32_e32 v61, v61
	v_exp_f32_e32 v64, v64
	v_exp_f32_e32 v65, v65
	v_add_f32_e32 v52, 1.0, v52
	v_add_f32_e32 v53, 1.0, v53
	v_add_f32_e32 v56, 1.0, v56
	v_add_f32_e32 v57, 1.0, v57
	v_add_f32_e32 v60, 1.0, v60
	v_add_f32_e32 v61, 1.0, v61
	v_add_f32_e32 v64, 1.0, v64
	v_add_f32_e32 v65, 1.0, v65
	v_rcp_f32_e32 v52, v52
	v_rcp_f32_e32 v53, v53
	v_rcp_f32_e32 v56, v56
	v_rcp_f32_e32 v57, v57
	v_rcp_f32_e32 v60, v60
	v_rcp_f32_e32 v61, v61
	v_rcp_f32_e32 v64, v64
	v_rcp_f32_e32 v65, v65
	s_nop 0
	v_mul_f32_e32 v50, v50, v52
	v_mul_f32_e32 v51, v51, v53
	v_mul_f32_e32 v54, v54, v56
	v_mul_f32_e32 v55, v55, v57
	v_mul_f32_e32 v58, v58, v60
	v_mul_f32_e32 v59, v59, v61
	v_mul_f32_e32 v62, v62, v64
	v_mul_f32_e32 v63, v63, v65
	v_cvt_pk_bf16_f32 v52, v50, v51
	v_cvt_pk_bf16_f32 v56, v54, v55
	v_cvt_pk_bf16_f32 v60, v58, v59
	v_cvt_pk_bf16_f32 v64, v62, v63
	global_store_dword v251, v52, s[98:99] offset:2048
	s_add_u32 s98, s98, 0x1000
	s_addc_u32 s99, s99, 0
	global_store_dword v251, v56, s[98:99] offset:2048
	s_add_u32 s98, s98, 0x1000
	s_addc_u32 s99, s99, 0
	global_store_dword v251, v60, s[98:99] offset:2048
	s_add_u32 s98, s98, 0x1000
	s_addc_u32 s99, s99, 0
	global_store_dword v251, v64, s[98:99] offset:2048
	s_add_u32 s98, s98, 0x1000
	s_addc_u32 s99, s99, 0
.Lp2_skip_1:
	s_branch .LBB0_320
.LBB0_456:
	v_readlane_b32 s74, v254, 4
	v_readlane_b32 s75, v254, 5
	s_cmp_gt_i32 s75, 3
	v_readlane_b32 s4, v254, 6
	s_cselect_b64 s[0:1], -1, 0
	v_readlane_b32 s5, v254, 7
	s_and_b64 s[4:5], s[4:5], s[0:1]
	v_readlane_b32 s76, v254, 1
	s_and_b64 vcc, exec, s[4:5]
	v_readlane_b32 s73, v254, 3
	v_readlane_b32 s77, v254, 2
	v_readlane_b32 s78, v254, 0
	s_cbranch_vccz .LBB0_510
	s_add_i32 s4, 0, 0x250a8
	v_mov_b32_e32 v0, s4
	ds_read_b64 v[0:1], v0
	v_mbcnt_lo_u32_b32 v2, -1, 0
	v_mbcnt_hi_u32_b32 v2, -1, v2
	s_getreg_b32 s8, hwreg(HW_REG_XCC_ID, 0, 4)
	s_waitcnt vmcnt(0)
	s_waitcnt lgkmcnt(0)
	v_readfirstlane_b32 s6, v0
	s_and_b32 s4, s78, 0xffffffc0
	v_sub_u32_e32 v0, 0, v2
	v_readfirstlane_b32 s7, v1
	v_cmp_eq_u32_e32 vcc, s4, v0
	s_waitcnt vmcnt(0)
	s_barrier
	s_and_saveexec_b64 s[4:5], vcc
	s_cbranch_execz .LBB0_509
	s_add_i32 s9, 0, 0x250c0
	v_mov_b32_e32 v0, s9
	s_waitcnt vmcnt(0) expcnt(0) lgkmcnt(0)
	ds_read_b32 v2, v0
	s_add_i32 s9, 0, 0x250c4
	v_mov_b32_e32 v0, s9
	ds_read_b32 v0, v0
	s_and_b32 s24, s8, 15
	s_waitcnt lgkmcnt(1)
	v_cmp_ne_u32_e32 vcc, 0, v2
	s_cbranch_vccnz .LBB0_473
	s_load_dwordx2 s[12:13], s[76:77], 0x4
	s_add_u32 s8, s6, 0x4200
	s_addc_u32 s9, s7, 0
	s_add_u32 s10, s6, 0x4400
	s_addc_u32 s11, s7, 0
	s_waitcnt lgkmcnt(0)
	s_mul_i32 s25, s12, s3
	s_add_u32 s12, s6, 0x4500
	s_mul_i32 s25, s25, s13
	s_addc_u32 s13, s7, 0
	s_add_u32 s14, s6, 0x4600
	s_addc_u32 s15, s7, 0
	s_add_u32 s16, s6, 0x4700
	s_addc_u32 s17, s7, 0
	s_add_u32 s18, s6, 0x4800
	s_addc_u32 s19, s7, 0
	s_add_u32 s20, s6, 0x4900
	s_addc_u32 s21, s7, 0
	s_add_u32 s22, s6, 0x4a00
	s_addc_u32 s23, s7, 0
	s_add_u32 s28, s6, 0x4b00
	s_addc_u32 s29, s7, 0
	s_add_u32 s30, s6, 0x4c00
	s_addc_u32 s31, s7, 0
	s_add_u32 s34, s6, 0x4d00
	s_addc_u32 s35, s7, 0
	s_add_u32 s36, s6, 0x4e00
	s_addc_u32 s37, s7, 0
	s_add_u32 s38, s6, 0x4f00
	s_addc_u32 s39, s7, 0
	s_add_u32 s40, s6, 0x5000
	s_addc_u32 s41, s7, 0
	s_add_u32 s42, s6, 0x5100
	s_addc_u32 s43, s7, 0
	s_add_u32 s44, s6, 0x5200
	s_addc_u32 s45, s7, 0
	s_add_u32 s46, s6, 0x5300
	s_addc_u32 s47, s7, 0
	s_mov_b32 s26, 1
	v_mov_b32_e32 v16, 0
	s_branch .LBB0_461

.LBB0_812:
	s_and_b64 vcc, exec, s[4:5]
	s_cbranch_vccnz .LBB0_878
	s_lshl_b64 s[4:5], s[34:35], 16
	s_add_u32 s14, s33, s4
	s_addc_u32 s15, s42, s5
	s_lshl_b32 s8, s16, 1
	v_lshl_add_u64 v[190:191], v[186:187], 0, s[8:9]
	v_subrev_u32_e32 v189, s61, v194
	s_waitcnt vmcnt(0)
	s_add_i32 s4, s66, 16
	s_cmp_ge_u32 s4, s65
	s_cbranch_scc1 .LBB0_817

.LBB0_818:
	s_add_i32 s66, s66, 8
	s_cmp_ge_u32 s66, s65
	s_cselect_b64 s[18:19], -1, 0
	v_mov_b64_e32 v[62:63], v[30:31]
	v_mov_b64_e32 v[78:79], v[46:47]
	s_and_b64 vcc, exec, s[18:19]
	v_mov_b64_e32 v[60:61], v[28:29]
	v_mov_b64_e32 v[58:59], v[26:27]
	v_mov_b64_e32 v[56:57], v[24:25]
	v_mov_b64_e32 v[54:55], v[22:23]
	v_mov_b64_e32 v[52:53], v[20:21]
	v_mov_b64_e32 v[50:51], v[18:19]
	v_mov_b64_e32 v[48:49], v[16:17]
	v_mov_b64_e32 v[76:77], v[44:45]
	v_mov_b64_e32 v[74:75], v[42:43]
	v_mov_b64_e32 v[72:73], v[40:41]
	v_mov_b64_e32 v[70:71], v[38:39]
	v_mov_b64_e32 v[68:69], v[36:37]
	v_mov_b64_e32 v[66:67], v[34:35]
	v_mov_b64_e32 v[64:65], v[32:33]
	s_cbranch_vccnz .LBB0_820
	v_and_b32_e32 v0, 0x3fff, v198
	v_or_b32_e32 v2, s60, v0
	v_ashrrev_i32_e32 v3, 31, v2
	v_lshlrev_b64 v[2:3], 11, v[2:3]
	v_lshl_add_u64 v[2:3], v[190:191], 0, v[2:3]
	global_load_dwordx4 v[48:51], v[2:3], off
	global_load_dwordx4 v[52:55], v[2:3], off offset:32
	global_load_dwordx4 v[56:59], v[2:3], off offset:64
	global_load_dwordx4 v[60:63], v[2:3], off offset:96
	global_load_dwordx4 v[64:67], v[2:3], off offset:128
	global_load_dwordx4 v[68:71], v[2:3], off offset:160
	global_load_dwordx4 v[72:75], v[2:3], off offset:192
	global_load_dwordx4 v[76:79], v[2:3], off offset:224

.LBB0_876:
	s_waitcnt vmcnt(9)
	v_mov_b64_e32 v[16:17], v[48:49]
	v_mov_b64_e32 v[32:33], v[64:65]
	v_mov_b32_e32 v200, v198
	v_mov_b32_e32 v198, v199
	s_mov_b64 s[12:13], s[10:11]
	s_mov_b64 s[10:11], s[16:17]
	v_mov_b64_e32 v[18:19], v[50:51]
	v_mov_b64_e32 v[20:21], v[52:53]
	v_mov_b64_e32 v[22:23], v[54:55]
	v_mov_b64_e32 v[24:25], v[56:57]
	v_mov_b64_e32 v[26:27], v[58:59]
	v_mov_b64_e32 v[28:29], v[60:61]
	v_mov_b64_e32 v[30:31], v[62:63]
	v_mov_b64_e32 v[34:35], v[66:67]
	v_mov_b64_e32 v[36:37], v[68:69]
	v_mov_b64_e32 v[38:39], v[70:71]
	v_mov_b64_e32 v[40:41], v[72:73]
	v_mov_b64_e32 v[42:43], v[74:75]
	v_mov_b64_e32 v[44:45], v[76:77]
	v_mov_b64_e32 v[46:47], v[78:79]
	s_add_i32 s4, s66, 16
	s_cmp_ge_u32 s4, s65
	s_cbranch_scc1 .LBB0_817
	s_branch .LBB0_814
.LBB0_877:
	v_mov_b64_e32 v[16:17], v[48:49]
	v_mov_b64_e32 v[32:33], v[64:65]
	v_mov_b64_e32 v[18:19], v[50:51]
	v_mov_b64_e32 v[20:21], v[52:53]
	v_mov_b64_e32 v[22:23], v[54:55]
	v_mov_b64_e32 v[24:25], v[56:57]
	v_mov_b64_e32 v[26:27], v[58:59]
	v_mov_b64_e32 v[28:29], v[60:61]
	v_mov_b64_e32 v[30:31], v[62:63]
	v_mov_b64_e32 v[34:35], v[66:67]
	v_mov_b64_e32 v[36:37], v[68:69]
	v_mov_b64_e32 v[38:39], v[70:71]
	v_mov_b64_e32 v[40:41], v[72:73]
	v_mov_b64_e32 v[42:43], v[74:75]
	v_mov_b64_e32 v[44:45], v[76:77]
	v_mov_b64_e32 v[46:47], v[78:79]

.LBB0_1198:
	v_lshl_add_u32 v144, s44, 8, v150
	v_lshl_or_b32 v148, s42, 8, v152
	v_ashrrev_i32_e32 v145, 31, v144
	v_ashrrev_i32_e32 v149, 31, v148
	v_lshlrev_b64 v[146:147], 11, v[144:145]
	v_lshl_add_u64 v[146:147], v[146:147], 0, v[148:149]
	v_lshl_add_u64 v[164:165], v[146:147], 2, s[8:9]
	s_mov_b64 s[98:99], 0x20000
	s_mov_b64 s[100:101], 0xa0000
	v_mov_b64_e32 v[244:245], v[164:165]
	global_load_dwordx4 v[170:173], v[244:245], off
	global_load_dwordx4 v[174:177], v[244:245], off offset:16
	global_load_dwordx4 v[178:181], v[244:245], off offset:512
	global_load_dwordx4 v[182:185], v[244:245], off offset:528
	v_lshl_add_u64 v[244:245], v[244:245], 0, s[98:99]
	global_load_dwordx4 v[186:189], v[244:245], off
	global_load_dwordx4 v[190:193], v[244:245], off offset:16
	global_load_dwordx4 v[194:197], v[244:245], off offset:512
	global_load_dwordx4 v[198:201], v[244:245], off offset:528
	v_lshl_add_u64 v[244:245], v[244:245], 0, s[98:99]
	global_load_dwordx4 v[202:205], v[244:245], off
	global_load_dwordx4 v[206:209], v[244:245], off offset:16
	global_load_dwordx4 v[210:213], v[244:245], off offset:512
	global_load_dwordx4 v[224:227], v[244:245], off offset:528
	v_lshl_add_u64 v[244:245], v[244:245], 0, s[98:99]
	global_load_dwordx4 v[228:231], v[244:245], off
	global_load_dwordx4 v[232:235], v[244:245], off offset:16
	global_load_dwordx4 v[236:239], v[244:245], off offset:512
	global_load_dwordx4 v[240:243], v[244:245], off offset:528
	v_lshl_add_u64 v[166:167], v[146:147], 1, s[14:15]
	s_waitcnt vmcnt(14)
	v_pk_add_f32 v[126:127], v[126:127], v[172:173]
	v_pk_add_f32 v[124:125], v[124:125], v[170:171]
	v_pk_add_f32 v[122:123], v[122:123], v[176:177]
	v_pk_add_f32 v[120:121], v[120:121], v[174:175]
	v_cvt_pk_bf16_f32 v156, v124, v125
	v_cvt_pk_bf16_f32 v157, v126, v127
	v_mul_f32_e32 v125, v125, v125
	v_cvt_pk_bf16_f32 v158, v120, v121
	v_cvt_pk_bf16_f32 v159, v122, v123
	global_store_dwordx4 v[166:167], v[156:159], off
	s_nop 0
	v_or_b32_e32 v164, 16, v144
	v_ashrrev_i32_e32 v165, 31, v164
	v_lshlrev_b64 v[164:165], 11, v[164:165]
	v_lshl_add_u64 v[164:165], v[164:165], 0, v[148:149]
	v_lshl_add_u64 v[168:169], v[164:165], 2, s[8:9]
	v_lshl_add_u64 v[164:165], v[164:165], 1, s[14:15]
	v_mul_f32_e32 v127, v127, v127
	v_mul_f32_e32 v121, v121, v121
	v_mul_f32_e32 v123, v123, v123
	v_fmac_f32_e32 v125, v124, v124
	v_fmac_f32_e32 v127, v126, v126
	v_fmac_f32_e32 v121, v120, v120
	v_fmac_f32_e32 v123, v122, v122
	v_add_f32_e32 v120, v125, v127
	v_add_f32_e32 v121, v121, v123
	v_add_f32_e32 v120, v120, v121
	s_waitcnt vmcnt(13)
	v_pk_add_f32 v[118:119], v[118:119], v[180:181]
	v_pk_add_f32 v[116:117], v[116:117], v[178:179]
	v_pk_add_f32 v[114:115], v[114:115], v[184:185]
	v_pk_add_f32 v[112:113], v[112:113], v[182:183]
	v_cvt_pk_bf16_f32 v156, v116, v117
	v_cvt_pk_bf16_f32 v157, v118, v119
	v_mul_f32_e32 v117, v117, v117
	v_cvt_pk_bf16_f32 v158, v112, v113
	v_cvt_pk_bf16_f32 v159, v114, v115
	global_store_dwordx4 v[166:167], v[156:159], off offset:256
	s_nop 0
	v_or_b32_e32 v166, 32, v144
	v_ashrrev_i32_e32 v167, 31, v166
	v_lshlrev_b64 v[166:167], 11, v[166:167]
	v_lshl_add_u64 v[166:167], v[166:167], 0, v[148:149]
	v_mul_f32_e32 v119, v119, v119
	v_mul_f32_e32 v113, v113, v113
	v_mul_f32_e32 v115, v115, v115
	v_fmac_f32_e32 v117, v116, v116
	v_fmac_f32_e32 v119, v118, v118
	v_fmac_f32_e32 v113, v112, v112
	v_fmac_f32_e32 v115, v114, v114
	v_add_f32_e32 v112, v117, v119
	v_add_f32_e32 v113, v113, v115
	v_add_f32_e32 v112, v112, v113
	v_add_f32_e32 v112, v120, v112
	v_mov_b32_e32 v113, v112
	s_nop 1
	v_permlane16_swap_b32_e32 v112, v113
	v_add_f32_e32 v114, v112, v113
	v_mov_b32_e32 v115, v114
	s_nop 1
	v_permlane32_swap_b32_e32 v114, v115
	s_waitcnt vmcnt(12)
	v_pk_add_f32 v[110:111], v[110:111], v[188:189]
	v_pk_add_f32 v[108:109], v[108:109], v[186:187]
	v_pk_add_f32 v[106:107], v[106:107], v[192:193]
	v_pk_add_f32 v[104:105], v[104:105], v[190:191]
	v_cvt_pk_bf16_f32 v156, v108, v109
	v_cvt_pk_bf16_f32 v157, v110, v111
	s_nop 0
	v_cvt_pk_bf16_f32 v158, v104, v105
	v_cvt_pk_bf16_f32 v159, v106, v107
	global_store_dwordx4 v[164:165], v[156:159], off
	s_nop 0
	v_lshl_add_u64 v[168:169], v[166:167], 2, s[8:9]
	s_waitcnt vmcnt(11)
	v_pk_add_f32 v[102:103], v[102:103], v[196:197]
	v_pk_add_f32 v[100:101], v[100:101], v[194:195]
	v_pk_add_f32 v[98:99], v[98:99], v[200:201]
	v_pk_add_f32 v[96:97], v[96:97], v[198:199]
	v_cvt_pk_bf16_f32 v156, v100, v101
	v_cvt_pk_bf16_f32 v157, v102, v103
	s_nop 0
	v_cvt_pk_bf16_f32 v158, v96, v97
	v_cvt_pk_bf16_f32 v159, v98, v99
	global_store_dwordx4 v[164:165], v[156:159], off offset:256
	v_lshl_add_u64 v[244:245], v[244:245], 0, s[100:101]
	global_load_dwordx4 v[170:173], v[244:245], off
	global_load_dwordx4 v[174:177], v[244:245], off offset:16
	global_load_dwordx4 v[178:181], v[244:245], off offset:512
	global_load_dwordx4 v[182:185], v[244:245], off offset:528
	v_lshl_add_u64 v[244:245], v[244:245], 0, s[98:99]
	global_load_dwordx4 v[186:189], v[244:245], off
	global_load_dwordx4 v[190:193], v[244:245], off offset:16
	global_load_dwordx4 v[194:197], v[244:245], off offset:512
	global_load_dwordx4 v[198:201], v[244:245], off offset:528
	s_nop 0
	v_lshl_add_u64 v[164:165], v[166:167], 1, s[14:15]
	v_or_b32_e32 v166, 48, v144
	v_ashrrev_i32_e32 v167, 31, v166
	v_lshlrev_b64 v[166:167], 11, v[166:167]
	v_lshl_add_u64 v[148:149], v[166:167], 0, v[148:149]
	v_lshl_add_u64 v[166:167], v[148:149], 2, s[8:9]
	v_lshl_add_u64 v[148:149], v[148:149], 1, s[14:15]
	s_waitcnt vmcnt(18)
	v_pk_add_f32 v[94:95], v[94:95], v[204:205]
	v_pk_add_f32 v[92:93], v[92:93], v[202:203]
	v_pk_add_f32 v[90:91], v[90:91], v[208:209]
	v_pk_add_f32 v[88:89], v[88:89], v[206:207]
	v_cvt_pk_bf16_f32 v156, v92, v93
	v_cvt_pk_bf16_f32 v157, v94, v95
	s_nop 0
	v_cvt_pk_bf16_f32 v158, v88, v89
	v_cvt_pk_bf16_f32 v159, v90, v91
	global_store_dwordx4 v[164:165], v[156:159], off
	s_nop 0
	s_waitcnt vmcnt(17)
	v_pk_add_f32 v[86:87], v[86:87], v[212:213]
	v_pk_add_f32 v[84:85], v[84:85], v[210:211]
	v_pk_add_f32 v[82:83], v[82:83], v[226:227]
	v_pk_add_f32 v[80:81], v[80:81], v[224:225]
	v_cvt_pk_bf16_f32 v156, v84, v85
	v_cvt_pk_bf16_f32 v157, v86, v87
	s_nop 0
	v_cvt_pk_bf16_f32 v158, v80, v81
	v_cvt_pk_bf16_f32 v159, v82, v83
	global_store_dwordx4 v[164:165], v[156:159], off offset:256
	s_nop 0
	v_lshl_add_u64 v[164:165], v[146:147], 0, s[18:19]
	s_waitcnt vmcnt(16)
	v_pk_add_f32 v[78:79], v[78:79], v[230:231]
	v_pk_add_f32 v[76:77], v[76:77], v[228:229]
	v_pk_add_f32 v[74:75], v[74:75], v[234:235]
	v_pk_add_f32 v[72:73], v[72:73], v[232:233]
	v_cvt_pk_bf16_f32 v156, v76, v77
	v_cvt_pk_bf16_f32 v157, v78, v79
	s_nop 0
	v_cvt_pk_bf16_f32 v158, v72, v73
	v_cvt_pk_bf16_f32 v159, v74, v75
	global_store_dwordx4 v[148:149], v[156:159], off
	s_nop 0
	v_lshl_add_u64 v[166:167], v[164:165], 2, s[8:9]
	s_waitcnt vmcnt(15)
	v_pk_add_f32 v[70:71], v[70:71], v[238:239]
	v_pk_add_f32 v[68:69], v[68:69], v[236:237]
	v_pk_add_f32 v[66:67], v[66:67], v[242:243]
	v_pk_add_f32 v[64:65], v[64:65], v[240:241]
	v_cvt_pk_bf16_f32 v156, v68, v69
	v_cvt_pk_bf16_f32 v157, v70, v71
	s_nop 0
	v_cvt_pk_bf16_f32 v158, v64, v65
	v_cvt_pk_bf16_f32 v159, v66, v67
	global_store_dwordx4 v[148:149], v[156:159], off offset:256
	v_lshl_add_u64 v[244:245], v[244:245], 0, s[98:99]
	global_load_dwordx4 v[202:205], v[244:245], off
	global_load_dwordx4 v[206:209], v[244:245], off offset:16
	global_load_dwordx4 v[210:213], v[244:245], off offset:512
	global_load_dwordx4 v[224:227], v[244:245], off offset:528
	v_lshl_add_u64 v[244:245], v[244:245], 0, s[98:99]
	global_load_dwordx4 v[228:231], v[244:245], off
	global_load_dwordx4 v[232:235], v[244:245], off offset:16
	global_load_dwordx4 v[236:239], v[244:245], off offset:512
	global_load_dwordx4 v[240:243], v[244:245], off offset:528
	s_nop 0
	v_lshl_add_u64 v[148:149], v[164:165], 1, s[14:15]
	v_lshl_add_u64 v[164:165], v[146:147], 0, s[22:23]
	s_waitcnt vmcnt(18)
	v_pk_add_f32 v[62:63], v[62:63], v[172:173]
	v_pk_add_f32 v[60:61], v[60:61], v[170:171]
	v_pk_add_f32 v[58:59], v[58:59], v[176:177]
	v_pk_add_f32 v[56:57], v[56:57], v[174:175]
	v_cvt_pk_bf16_f32 v156, v60, v61
	v_cvt_pk_bf16_f32 v157, v62, v63
	s_nop 0
	v_cvt_pk_bf16_f32 v158, v56, v57
	v_cvt_pk_bf16_f32 v159, v58, v59
	global_store_dwordx4 v[148:149], v[156:159], off
	s_nop 0
	v_lshl_add_u64 v[166:167], v[164:165], 2, s[8:9]
	s_waitcnt vmcnt(17)
	v_pk_add_f32 v[54:55], v[54:55], v[180:181]
	v_pk_add_f32 v[52:53], v[52:53], v[178:179]
	v_pk_add_f32 v[50:51], v[50:51], v[184:185]
	v_pk_add_f32 v[48:49], v[48:49], v[182:183]
	v_cvt_pk_bf16_f32 v156, v52, v53
	v_cvt_pk_bf16_f32 v157, v54, v55
	s_nop 0
	v_cvt_pk_bf16_f32 v158, v48, v49
	v_cvt_pk_bf16_f32 v159, v50, v51
	global_store_dwordx4 v[148:149], v[156:159], off offset:256
	s_nop 0
	v_lshl_add_u64 v[148:149], v[164:165], 1, s[14:15]
	v_lshl_add_u64 v[164:165], v[146:147], 0, s[28:29]
	s_waitcnt vmcnt(16)
	v_pk_add_f32 v[46:47], v[46:47], v[188:189]
	v_pk_add_f32 v[44:45], v[44:45], v[186:187]
	v_pk_add_f32 v[42:43], v[42:43], v[192:193]
	v_pk_add_f32 v[40:41], v[40:41], v[190:191]
	v_cvt_pk_bf16_f32 v156, v44, v45
	v_cvt_pk_bf16_f32 v157, v46, v47
	s_nop 0
	v_cvt_pk_bf16_f32 v158, v40, v41
	v_cvt_pk_bf16_f32 v159, v42, v43
	global_store_dwordx4 v[148:149], v[156:159], off
	s_nop 0
	v_lshl_add_u64 v[166:167], v[164:165], 2, s[8:9]
	v_lshl_add_u64 v[164:165], v[164:165], 1, s[14:15]
	s_waitcnt vmcnt(15)
	v_pk_add_f32 v[38:39], v[38:39], v[196:197]
	v_pk_add_f32 v[36:37], v[36:37], v[194:195]
	v_pk_add_f32 v[34:35], v[34:35], v[200:201]
	v_pk_add_f32 v[32:33], v[32:33], v[198:199]
	v_cvt_pk_bf16_f32 v156, v36, v37
	v_cvt_pk_bf16_f32 v157, v38, v39
	s_nop 0
	v_cvt_pk_bf16_f32 v158, v32, v33
	v_cvt_pk_bf16_f32 v159, v34, v35
	global_store_dwordx4 v[148:149], v[156:159], off offset:256
	s_nop 0
	s_waitcnt vmcnt(10)
	v_pk_add_f32 v[30:31], v[30:31], v[204:205]
	v_pk_add_f32 v[28:29], v[28:29], v[202:203]
	v_pk_add_f32 v[26:27], v[26:27], v[208:209]
	v_pk_add_f32 v[24:25], v[24:25], v[206:207]
	v_cvt_pk_bf16_f32 v156, v28, v29
	v_cvt_pk_bf16_f32 v157, v30, v31
	s_nop 0
	v_cvt_pk_bf16_f32 v158, v24, v25
	v_cvt_pk_bf16_f32 v159, v26, v27
	global_store_dwordx4 v[164:165], v[156:159], off
	s_nop 0
	v_lshl_add_u64 v[166:167], v[146:147], 0, s[30:31]
	v_lshl_add_u64 v[168:169], v[166:167], 2, s[8:9]
	s_waitcnt vmcnt(9)
	v_pk_add_f32 v[22:23], v[22:23], v[212:213]
	v_pk_add_f32 v[20:21], v[20:21], v[210:211]
	v_pk_add_f32 v[18:19], v[18:19], v[226:227]
	v_pk_add_f32 v[16:17], v[16:17], v[224:225]
	v_cvt_pk_bf16_f32 v146, v20, v21
	v_cvt_pk_bf16_f32 v147, v22, v23
	v_lshl_add_u64 v[160:161], v[166:167], 1, s[14:15]
	v_cvt_pk_bf16_f32 v148, v16, v17
	v_cvt_pk_bf16_f32 v149, v18, v19
	global_store_dwordx4 v[164:165], v[146:149], off offset:256
	s_nop 0
	s_waitcnt vmcnt(8)
	v_pk_add_f32 v[14:15], v[14:15], v[230:231]
	v_pk_add_f32 v[12:13], v[12:13], v[228:229]
	v_pk_add_f32 v[10:11], v[10:11], v[234:235]
	v_pk_add_f32 v[8:9], v[8:9], v[232:233]
	v_cvt_pk_bf16_f32 v146, v12, v13
	v_cvt_pk_bf16_f32 v147, v14, v15
	s_nop 0
	v_cvt_pk_bf16_f32 v148, v8, v9
	v_cvt_pk_bf16_f32 v149, v10, v11
	global_store_dwordx4 v[160:161], v[146:149], off
	s_nop 0
	s_waitcnt vmcnt(7)
	v_pk_add_f32 v[6:7], v[6:7], v[238:239]
	v_pk_add_f32 v[112:113], v[4:5], v[236:237]
	v_pk_add_f32 v[2:3], v[2:3], v[242:243]
	v_pk_add_f32 v[4:5], v[0:1], v[240:241]
	v_lshl_add_u64 v[0:1], v[144:145], 2, s[12:13]
	v_cvt_pk_bf16_f32 v116, v112, v113
	v_cvt_pk_bf16_f32 v117, v6, v7
	v_cvt_pk_bf16_f32 v118, v4, v5
	v_cvt_pk_bf16_f32 v119, v2, v3
	global_store_dwordx4 v[160:161], v[116:119], off offset:256
	s_and_saveexec_b64 s[42:43], s[0:1]
	s_cbranch_execz .LBB0_1200
	v_add_f32_e32 v114, v114, v115
	global_atomic_add_f32 v[0:1], v114, off
